# wave-sum tails: zero-init + v_mov_dpp row_bcast + v_add fused into one in-place v_add_f32_dpp (same row mask), dead zero copies in the prep loop turned into s_nop; instruction spacing unchanged
# baseline (speedup 1.0000x reference)
.LBB0_253:
	v_mul_f32_e32 v35, v31, v31
	v_mul_f32_e32 v40, v33, v33
	v_fmac_f32_e32 v35, v30, v30
	v_fmac_f32_e32 v40, v32, v32
	v_add_f32_e32 v35, v35, v40
	v_mul_f32_e32 v40, v27, v27
	v_mul_f32_e32 v49, v29, v29
	v_fmac_f32_e32 v40, v26, v26
	v_fmac_f32_e32 v49, v28, v28
	v_add_f32_e32 v40, v40, v49
	v_add_f32_e32 v35, v40, v35
	v_mul_f32_e32 v40, v23, v23
	v_mul_f32_e32 v49, v25, v25
	v_fmac_f32_e32 v40, v22, v22
	v_fmac_f32_e32 v49, v24, v24
	v_add_f32_e32 v40, v40, v49
	v_add_f32_e32 v35, v40, v35
	v_mul_f32_e32 v40, v19, v19
	v_mul_f32_e32 v49, v21, v21
	v_fmac_f32_e32 v40, v18, v18
	v_fmac_f32_e32 v49, v20, v20
	v_add_f32_e32 v40, v40, v49
	v_add_f32_e32 v35, v40, v35
	v_mov_b32_e32 v40, 0
	s_ashr_i32 s13, s12, 31
	v_add_f32_dpp v35, v35, v35 row_ror:8 row_mask:0xf bank_mask:0xf bound_ctrl:1
	s_lshl_b64 s[20:21], s[12:13], 11
	v_lshl_add_u64 v[50:51], v[44:45], 0, s[20:21]
	v_add_f32_dpp v35, v35, v35 row_ror:4 row_mask:0xf bank_mask:0xf bound_ctrl:1
	v_cvt_pk_bf16_f32 v52, v30, v31
	v_cvt_pk_bf16_f32 v53, v32, v33
	v_add_f32_dpp v35, v35, v35 quad_perm:[2,3,0,1] row_mask:0xf bank_mask:0xf bound_ctrl:1
	global_store_dwordx2 v[50:51], v[52:53], off
	v_cvt_pk_bf16_f32 v52, v26, v27
	v_add_f32_dpp v35, v35, v35 quad_perm:[1,0,3,2] row_mask:0xf bank_mask:0xf bound_ctrl:1
	v_cvt_pk_bf16_f32 v53, v28, v29
	global_store_dwordx2 v[50:51], v[52:53], off offset:512
	s_nop 0
	v_add_f32_dpp v35, v35, v35 row_bcast:15 row_mask:0xa bank_mask:0xf
	v_mov_b32_e32 v40, 0
	v_cvt_pk_bf16_f32 v52, v22, v23
	v_cvt_pk_bf16_f32 v53, v24, v25
	s_nop 0
	v_add_f32_dpp v35, v35, v35 row_bcast:31 row_mask:0xc bank_mask:0xf
	global_store_dwordx2 v[50:51], v[52:53], off offset:1024
	v_readlane_b32 s8, v35, 63
	v_cvt_pk_bf16_f32 v52, v18, v19
	v_cvt_pk_bf16_f32 v53, v20, v21
	v_mov_b32_e32 v35, 0
	s_mov_b32 s9, 0
	global_store_dwordx2 v[50:51], v[52:53], off offset:1536
	ds_read_b128 v[126:129], v1 offset:0
	ds_read_b128 v[130:133], v1 offset:1024
	ds_read_b128 v[134:137], v1 offset:2048
	ds_read_b128 v[138:141], v1 offset:3072
	ds_read_b128 v[142:145], v1 offset:4096
	ds_read_b128 v[146:149], v1 offset:5120
	ds_read_b128 v[150:153], v1 offset:6144
	ds_read_b128 v[154:157], v1 offset:7168
	ds_read_b128 v[160:163], v1 offset:8192
	ds_read_b128 v[164:167], v1 offset:9216
	ds_read_b128 v[168:171], v1 offset:10240
	ds_read_b128 v[172:175], v1 offset:11264
	s_waitcnt lgkmcnt(8)
	v_mul_f32_e32 v110, v30, v126
	v_mul_f32_e32 v158, v31, v127
	v_fmac_f32_e32 v110, v32, v128
	v_fmac_f32_e32 v158, v33, v129
	v_fmac_f32_e32 v110, v26, v130
	v_fmac_f32_e32 v158, v27, v131
	v_fmac_f32_e32 v110, v28, v132
	v_fmac_f32_e32 v158, v29, v133
	v_fmac_f32_e32 v110, v22, v134
	v_fmac_f32_e32 v158, v23, v135
	v_fmac_f32_e32 v110, v24, v136
	v_fmac_f32_e32 v158, v25, v137
	v_fmac_f32_e32 v110, v18, v138
	v_fmac_f32_e32 v158, v19, v139
	v_fmac_f32_e32 v110, v20, v140
	v_fmac_f32_e32 v158, v21, v141
	ds_read_b128 v[176:179], v1 offset:12288
	ds_read_b128 v[180:183], v1 offset:13312
	ds_read_b128 v[184:187], v1 offset:14336
	ds_read_b128 v[188:191], v1 offset:15360
	v_add_f32_e32 v110, v110, v158
	s_waitcnt lgkmcnt(8)
	v_mul_f32_e32 v111, v30, v142
	v_mul_f32_e32 v158, v31, v143
	v_fmac_f32_e32 v111, v32, v144
	v_fmac_f32_e32 v158, v33, v145
	v_fmac_f32_e32 v111, v26, v146
	v_fmac_f32_e32 v158, v27, v147
	v_fmac_f32_e32 v111, v28, v148
	v_fmac_f32_e32 v158, v29, v149
	v_fmac_f32_e32 v111, v22, v150
	v_fmac_f32_e32 v158, v23, v151
	v_fmac_f32_e32 v111, v24, v152
	v_fmac_f32_e32 v158, v25, v153
	v_fmac_f32_e32 v111, v18, v154
	v_fmac_f32_e32 v158, v19, v155
	v_fmac_f32_e32 v111, v20, v156
	v_fmac_f32_e32 v158, v21, v157
	ds_read_b128 v[126:129], v1 offset:16384
	ds_read_b128 v[130:133], v1 offset:17408
	ds_read_b128 v[134:137], v1 offset:18432
	ds_read_b128 v[138:141], v1 offset:19456
	v_add_f32_e32 v111, v111, v158
	s_waitcnt lgkmcnt(8)
	v_mul_f32_e32 v112, v30, v160
	v_mul_f32_e32 v158, v31, v161
	v_fmac_f32_e32 v112, v32, v162
	v_fmac_f32_e32 v158, v33, v163
	v_fmac_f32_e32 v112, v26, v164
	v_fmac_f32_e32 v158, v27, v165
	v_fmac_f32_e32 v112, v28, v166
	v_fmac_f32_e32 v158, v29, v167
	v_fmac_f32_e32 v112, v22, v168
	v_fmac_f32_e32 v158, v23, v169
	v_fmac_f32_e32 v112, v24, v170
	v_fmac_f32_e32 v158, v25, v171
	v_fmac_f32_e32 v112, v18, v172
	v_fmac_f32_e32 v158, v19, v173
	v_fmac_f32_e32 v112, v20, v174
	v_fmac_f32_e32 v158, v21, v175
	ds_read_b128 v[142:145], v1 offset:20480
	ds_read_b128 v[146:149], v1 offset:21504
	ds_read_b128 v[150:153], v1 offset:22528
	ds_read_b128 v[154:157], v1 offset:23552
	v_add_f32_e32 v112, v112, v158
	s_waitcnt lgkmcnt(8)
	v_mul_f32_e32 v113, v30, v176
	v_mul_f32_e32 v158, v31, v177
	v_fmac_f32_e32 v113, v32, v178
	v_fmac_f32_e32 v158, v33, v179
	v_fmac_f32_e32 v113, v26, v180
	v_fmac_f32_e32 v158, v27, v181
	v_fmac_f32_e32 v113, v28, v182
	v_fmac_f32_e32 v158, v29, v183
	v_fmac_f32_e32 v113, v22, v184
	v_fmac_f32_e32 v158, v23, v185
	v_fmac_f32_e32 v113, v24, v186
	v_fmac_f32_e32 v158, v25, v187
	v_fmac_f32_e32 v113, v18, v188
	v_fmac_f32_e32 v158, v19, v189
	v_fmac_f32_e32 v113, v20, v190
	v_fmac_f32_e32 v158, v21, v191
	ds_read_b128 v[160:163], v1 offset:24576
	ds_read_b128 v[164:167], v1 offset:25600
	ds_read_b128 v[168:171], v1 offset:26624
	ds_read_b128 v[172:175], v1 offset:27648
	v_add_f32_e32 v113, v113, v158
	s_waitcnt lgkmcnt(8)
	v_mul_f32_e32 v114, v30, v126
	v_mul_f32_e32 v158, v31, v127
	v_fmac_f32_e32 v114, v32, v128
	v_fmac_f32_e32 v158, v33, v129
	v_fmac_f32_e32 v114, v26, v130
	v_fmac_f32_e32 v158, v27, v131
	v_fmac_f32_e32 v114, v28, v132
	v_fmac_f32_e32 v158, v29, v133
	v_fmac_f32_e32 v114, v22, v134
	v_fmac_f32_e32 v158, v23, v135
	v_fmac_f32_e32 v114, v24, v136
	v_fmac_f32_e32 v158, v25, v137
	v_fmac_f32_e32 v114, v18, v138
	v_fmac_f32_e32 v158, v19, v139
	v_fmac_f32_e32 v114, v20, v140
	v_fmac_f32_e32 v158, v21, v141
	ds_read_b128 v[176:179], v1 offset:28672
	ds_read_b128 v[180:183], v1 offset:29696
	ds_read_b128 v[184:187], v1 offset:30720
	ds_read_b128 v[188:191], v1 offset:31744
	v_add_f32_e32 v114, v114, v158
	s_waitcnt lgkmcnt(8)
	v_mul_f32_e32 v115, v30, v142
	v_mul_f32_e32 v158, v31, v143
	v_fmac_f32_e32 v115, v32, v144
	v_fmac_f32_e32 v158, v33, v145
	v_fmac_f32_e32 v115, v26, v146
	v_fmac_f32_e32 v158, v27, v147
	v_fmac_f32_e32 v115, v28, v148
	v_fmac_f32_e32 v158, v29, v149
	v_fmac_f32_e32 v115, v22, v150
	v_fmac_f32_e32 v158, v23, v151
	v_fmac_f32_e32 v115, v24, v152
	v_fmac_f32_e32 v158, v25, v153
	v_fmac_f32_e32 v115, v18, v154
	v_fmac_f32_e32 v158, v19, v155
	v_fmac_f32_e32 v115, v20, v156
	v_fmac_f32_e32 v158, v21, v157
	ds_read_b128 v[126:129], v1 offset:32768
	ds_read_b128 v[130:133], v1 offset:33792
	ds_read_b128 v[134:137], v1 offset:34816
	ds_read_b128 v[138:141], v1 offset:35840
	v_add_f32_e32 v115, v115, v158
	s_waitcnt lgkmcnt(8)
	v_mul_f32_e32 v116, v30, v160
	v_mul_f32_e32 v158, v31, v161
	v_fmac_f32_e32 v116, v32, v162
	v_fmac_f32_e32 v158, v33, v163
	v_fmac_f32_e32 v116, v26, v164
	v_fmac_f32_e32 v158, v27, v165
	v_fmac_f32_e32 v116, v28, v166
	v_fmac_f32_e32 v158, v29, v167
	v_fmac_f32_e32 v116, v22, v168
	v_fmac_f32_e32 v158, v23, v169
	v_fmac_f32_e32 v116, v24, v170
	v_fmac_f32_e32 v158, v25, v171
	v_fmac_f32_e32 v116, v18, v172
	v_fmac_f32_e32 v158, v19, v173
	v_fmac_f32_e32 v116, v20, v174
	v_fmac_f32_e32 v158, v21, v175
	ds_read_b128 v[142:145], v1 offset:36864
	ds_read_b128 v[146:149], v1 offset:37888
	ds_read_b128 v[150:153], v1 offset:38912
	ds_read_b128 v[154:157], v1 offset:39936
	v_add_f32_e32 v116, v116, v158
	s_waitcnt lgkmcnt(8)
	v_mul_f32_e32 v117, v30, v176
	v_mul_f32_e32 v158, v31, v177
	v_fmac_f32_e32 v117, v32, v178
	v_fmac_f32_e32 v158, v33, v179
	v_fmac_f32_e32 v117, v26, v180
	v_fmac_f32_e32 v158, v27, v181
	v_fmac_f32_e32 v117, v28, v182
	v_fmac_f32_e32 v158, v29, v183
	v_fmac_f32_e32 v117, v22, v184
	v_fmac_f32_e32 v158, v23, v185
	v_fmac_f32_e32 v117, v24, v186
	v_fmac_f32_e32 v158, v25, v187
	v_fmac_f32_e32 v117, v18, v188
	v_fmac_f32_e32 v158, v19, v189
	v_fmac_f32_e32 v117, v20, v190
	v_fmac_f32_e32 v158, v21, v191
	ds_read_b128 v[160:163], v1 offset:40960
	ds_read_b128 v[164:167], v1 offset:41984
	ds_read_b128 v[168:171], v1 offset:43008
	ds_read_b128 v[172:175], v1 offset:44032
	v_add_f32_e32 v117, v117, v158
	s_waitcnt lgkmcnt(8)
	v_mul_f32_e32 v118, v30, v126
	v_mul_f32_e32 v158, v31, v127
	v_fmac_f32_e32 v118, v32, v128
	v_fmac_f32_e32 v158, v33, v129
	v_fmac_f32_e32 v118, v26, v130
	v_fmac_f32_e32 v158, v27, v131
	v_fmac_f32_e32 v118, v28, v132
	v_fmac_f32_e32 v158, v29, v133
	v_fmac_f32_e32 v118, v22, v134
	v_fmac_f32_e32 v158, v23, v135
	v_fmac_f32_e32 v118, v24, v136
	v_fmac_f32_e32 v158, v25, v137
	v_fmac_f32_e32 v118, v18, v138
	v_fmac_f32_e32 v158, v19, v139
	v_fmac_f32_e32 v118, v20, v140
	v_fmac_f32_e32 v158, v21, v141
	ds_read_b128 v[176:179], v1 offset:45056
	ds_read_b128 v[180:183], v1 offset:46080
	ds_read_b128 v[184:187], v1 offset:47104
	ds_read_b128 v[188:191], v1 offset:48128
	v_add_f32_e32 v118, v118, v158
	s_waitcnt lgkmcnt(8)
	v_mul_f32_e32 v119, v30, v142
	v_mul_f32_e32 v158, v31, v143
	v_fmac_f32_e32 v119, v32, v144
	v_fmac_f32_e32 v158, v33, v145
	v_fmac_f32_e32 v119, v26, v146
	v_fmac_f32_e32 v158, v27, v147
	v_fmac_f32_e32 v119, v28, v148
	v_fmac_f32_e32 v158, v29, v149
	v_fmac_f32_e32 v119, v22, v150
	v_fmac_f32_e32 v158, v23, v151
	v_fmac_f32_e32 v119, v24, v152
	v_fmac_f32_e32 v158, v25, v153
	v_fmac_f32_e32 v119, v18, v154
	v_fmac_f32_e32 v158, v19, v155
	v_fmac_f32_e32 v119, v20, v156
	v_fmac_f32_e32 v158, v21, v157
	ds_read_b128 v[126:129], v1 offset:49152
	ds_read_b128 v[130:133], v1 offset:50176
	ds_read_b128 v[134:137], v1 offset:51200
	ds_read_b128 v[138:141], v1 offset:52224
	v_add_f32_e32 v119, v119, v158
	s_waitcnt lgkmcnt(8)
	v_mul_f32_e32 v120, v30, v160
	v_mul_f32_e32 v158, v31, v161
	v_fmac_f32_e32 v120, v32, v162
	v_fmac_f32_e32 v158, v33, v163
	v_fmac_f32_e32 v120, v26, v164
	v_fmac_f32_e32 v158, v27, v165
	v_fmac_f32_e32 v120, v28, v166
	v_fmac_f32_e32 v158, v29, v167
	v_fmac_f32_e32 v120, v22, v168
	v_fmac_f32_e32 v158, v23, v169
	v_fmac_f32_e32 v120, v24, v170
	v_fmac_f32_e32 v158, v25, v171
	v_fmac_f32_e32 v120, v18, v172
	v_fmac_f32_e32 v158, v19, v173
	v_fmac_f32_e32 v120, v20, v174
	v_fmac_f32_e32 v158, v21, v175
	ds_read_b128 v[142:145], v1 offset:53248
	ds_read_b128 v[146:149], v1 offset:54272
	ds_read_b128 v[150:153], v1 offset:55296
	ds_read_b128 v[154:157], v1 offset:56320
	v_add_f32_e32 v120, v120, v158
	s_waitcnt lgkmcnt(8)
	v_mul_f32_e32 v121, v30, v176
	v_mul_f32_e32 v158, v31, v177
	v_fmac_f32_e32 v121, v32, v178
	v_fmac_f32_e32 v158, v33, v179
	v_fmac_f32_e32 v121, v26, v180
	v_fmac_f32_e32 v158, v27, v181
	v_fmac_f32_e32 v121, v28, v182
	v_fmac_f32_e32 v158, v29, v183
	v_fmac_f32_e32 v121, v22, v184
	v_fmac_f32_e32 v158, v23, v185
	v_fmac_f32_e32 v121, v24, v186
	v_fmac_f32_e32 v158, v25, v187
	v_fmac_f32_e32 v121, v18, v188
	v_fmac_f32_e32 v158, v19, v189
	v_fmac_f32_e32 v121, v20, v190
	v_fmac_f32_e32 v158, v21, v191
	ds_read_b128 v[160:163], v1 offset:57344
	ds_read_b128 v[164:167], v1 offset:58368
	ds_read_b128 v[168:171], v1 offset:59392
	ds_read_b128 v[172:175], v1 offset:60416
	v_add_f32_e32 v121, v121, v158
	s_waitcnt lgkmcnt(8)
	v_mul_f32_e32 v122, v30, v126
	v_mul_f32_e32 v158, v31, v127
	v_fmac_f32_e32 v122, v32, v128
	v_fmac_f32_e32 v158, v33, v129
	v_fmac_f32_e32 v122, v26, v130
	v_fmac_f32_e32 v158, v27, v131
	v_fmac_f32_e32 v122, v28, v132
	v_fmac_f32_e32 v158, v29, v133
	v_fmac_f32_e32 v122, v22, v134
	v_fmac_f32_e32 v158, v23, v135
	v_fmac_f32_e32 v122, v24, v136
	v_fmac_f32_e32 v158, v25, v137
	v_fmac_f32_e32 v122, v18, v138
	v_fmac_f32_e32 v158, v19, v139
	v_fmac_f32_e32 v122, v20, v140
	v_fmac_f32_e32 v158, v21, v141
	ds_read_b128 v[176:179], v1 offset:61440
	ds_read_b128 v[180:183], v1 offset:62464
	ds_read_b128 v[184:187], v1 offset:63488
	ds_read_b128 v[188:191], v1 offset:64512
	v_add_f32_e32 v122, v122, v158
	s_waitcnt lgkmcnt(8)
	v_mul_f32_e32 v123, v30, v142
	v_mul_f32_e32 v158, v31, v143
	v_fmac_f32_e32 v123, v32, v144
	v_fmac_f32_e32 v158, v33, v145
	v_fmac_f32_e32 v123, v26, v146
	v_fmac_f32_e32 v158, v27, v147
	v_fmac_f32_e32 v123, v28, v148
	v_fmac_f32_e32 v158, v29, v149
	v_fmac_f32_e32 v123, v22, v150
	v_fmac_f32_e32 v158, v23, v151
	v_fmac_f32_e32 v123, v24, v152
	v_fmac_f32_e32 v158, v25, v153
	v_fmac_f32_e32 v123, v18, v154
	v_fmac_f32_e32 v158, v19, v155
	v_fmac_f32_e32 v123, v20, v156
	v_fmac_f32_e32 v158, v21, v157
	v_add_f32_e32 v123, v123, v158
	s_waitcnt lgkmcnt(4)
	v_mul_f32_e32 v124, v30, v160
	v_mul_f32_e32 v158, v31, v161
	v_fmac_f32_e32 v124, v32, v162
	v_fmac_f32_e32 v158, v33, v163
	v_fmac_f32_e32 v124, v26, v164
	v_fmac_f32_e32 v158, v27, v165
	v_fmac_f32_e32 v124, v28, v166
	v_fmac_f32_e32 v158, v29, v167
	v_fmac_f32_e32 v124, v22, v168
	v_fmac_f32_e32 v158, v23, v169
	v_fmac_f32_e32 v124, v24, v170
	v_fmac_f32_e32 v158, v25, v171
	v_fmac_f32_e32 v124, v18, v172
	v_fmac_f32_e32 v158, v19, v173
	v_fmac_f32_e32 v124, v20, v174
	v_fmac_f32_e32 v158, v21, v175
	v_add_f32_e32 v124, v124, v158
	s_waitcnt lgkmcnt(0)
	v_mul_f32_e32 v125, v30, v176
	v_mul_f32_e32 v158, v31, v177
	v_fmac_f32_e32 v125, v32, v178
	v_fmac_f32_e32 v158, v33, v179
	v_fmac_f32_e32 v125, v26, v180
	v_fmac_f32_e32 v158, v27, v181
	v_fmac_f32_e32 v125, v28, v182
	v_fmac_f32_e32 v158, v29, v183
	v_fmac_f32_e32 v125, v22, v184
	v_fmac_f32_e32 v158, v23, v185
	v_fmac_f32_e32 v125, v24, v186
	v_fmac_f32_e32 v158, v25, v187
	v_fmac_f32_e32 v125, v18, v188
	v_fmac_f32_e32 v158, v19, v189
	v_fmac_f32_e32 v125, v20, v190
	v_fmac_f32_e32 v158, v21, v191
	v_add_f32_e32 v125, v125, v158
	v_add_f32_dpp v192, v110, v110 row_ror:8 row_mask:0xf bank_mask:0xf
	v_add_f32_dpp v193, v111, v111 row_ror:8 row_mask:0xf bank_mask:0xf
	v_add_f32_dpp v194, v112, v112 row_ror:8 row_mask:0xf bank_mask:0xf
	v_add_f32_dpp v195, v113, v113 row_ror:8 row_mask:0xf bank_mask:0xf
	v_add_f32_dpp v196, v114, v114 row_ror:8 row_mask:0xf bank_mask:0xf
	v_add_f32_dpp v197, v115, v115 row_ror:8 row_mask:0xf bank_mask:0xf
	v_add_f32_dpp v198, v116, v116 row_ror:8 row_mask:0xf bank_mask:0xf
	v_add_f32_dpp v199, v117, v117 row_ror:8 row_mask:0xf bank_mask:0xf
	v_add_f32_dpp v192, v118, v118 row_ror:8 row_mask:0xf bank_mask:0xc
	v_add_f32_dpp v193, v119, v119 row_ror:8 row_mask:0xf bank_mask:0xc
	v_add_f32_dpp v194, v120, v120 row_ror:8 row_mask:0xf bank_mask:0xc
	v_add_f32_dpp v195, v121, v121 row_ror:8 row_mask:0xf bank_mask:0xc
	v_add_f32_dpp v196, v122, v122 row_ror:8 row_mask:0xf bank_mask:0xc
	v_add_f32_dpp v197, v123, v123 row_ror:8 row_mask:0xf bank_mask:0xc
	v_add_f32_dpp v198, v124, v124 row_ror:8 row_mask:0xf bank_mask:0xc
	v_add_f32_dpp v199, v125, v125 row_ror:8 row_mask:0xf bank_mask:0xc
	v_add_f32_dpp v200, v192, v192 row_half_mirror row_mask:0xf bank_mask:0x5
	v_add_f32_dpp v201, v193, v193 row_half_mirror row_mask:0xf bank_mask:0x5
	v_add_f32_dpp v202, v194, v194 row_half_mirror row_mask:0xf bank_mask:0x5
	v_add_f32_dpp v203, v195, v195 row_half_mirror row_mask:0xf bank_mask:0x5
	v_add_f32_dpp v200, v196, v196 row_half_mirror row_mask:0xf bank_mask:0xa
	v_add_f32_dpp v201, v197, v197 row_half_mirror row_mask:0xf bank_mask:0xa
	v_add_f32_dpp v202, v198, v198 row_half_mirror row_mask:0xf bank_mask:0xa
	v_add_f32_dpp v203, v199, v199 row_half_mirror row_mask:0xf bank_mask:0xa
	v_add_f32_dpp v192, v200, v200 quad_perm:[2,3,0,1] row_mask:0xf bank_mask:0xf
	v_add_f32_dpp v193, v202, v202 quad_perm:[2,3,0,1] row_mask:0xf bank_mask:0xf
	v_add_f32_dpp v194, v201, v201 quad_perm:[2,3,0,1] row_mask:0xf bank_mask:0xf
	v_add_f32_dpp v195, v203, v203 quad_perm:[2,3,0,1] row_mask:0xf bank_mask:0xf
	v_cndmask_b32_e64 v196, v192, v193, s[100:101]
	v_cndmask_b32_e64 v197, v194, v195, s[100:101]
	s_nop 0
	v_add_f32_dpp v198, v196, v196 quad_perm:[1,0,3,2] row_mask:0xf bank_mask:0xf
	v_add_f32_dpp v199, v197, v197 quad_perm:[1,0,3,2] row_mask:0xf bank_mask:0xf
	s_nop 0
	v_cndmask_b32_e64 v198, v198, v199, s[98:99]
	ds_bpermute_b32 v199, v206, v198
	s_waitcnt lgkmcnt(0)
	v_add_f32_e32 v198, v198, v199
	ds_bpermute_b32 v199, v207, v198
	s_waitcnt lgkmcnt(0)
	v_add_f32_e32 v35, v198, v199
	v_fma_f32 v18, s8, v48, v46
	s_mov_b32 s8, 0xf800000
	v_mul_f32_e32 v19, 0x4f800000, v18
	v_cmp_gt_f32_e32 vcc, s8, v18
	s_nop 1
	v_cndmask_b32_e32 v18, v18, v19, vcc
	v_sqrt_f32_e32 v19, v18
	s_nop 0
	v_add_u32_e32 v20, -1, v19
	v_add_u32_e32 v21, 1, v19
	v_fma_f32 v22, -v20, v19, v18
	v_fma_f32 v23, -v21, v19, v18
	v_cmp_ge_f32_e64 s[8:9], 0, v22
	s_nop 1
	v_cndmask_b32_e64 v19, v19, v20, s[8:9]
	v_cmp_lt_f32_e64 s[8:9], 0, v23
	s_nop 1
	v_cndmask_b32_e64 v19, v19, v21, s[8:9]
	v_mul_f32_e32 v20, 0x37800000, v19
	v_cndmask_b32_e32 v19, v19, v20, vcc
	v_cmp_class_f32_e32 vcc, v18, v47
	s_nop 1
	v_cndmask_b32_e32 v18, v19, v18, vcc
	v_div_scale_f32 v19, s[8:9], v18, v18, 1.0
	v_rcp_f32_e32 v20, v19
	s_nop 0
	v_fma_f32 v21, -v19, v20, 1.0
	v_fmac_f32_e32 v20, v21, v20
	v_div_scale_f32 v21, vcc, 1.0, v18, 1.0
	v_mul_f32_e32 v22, v21, v20
	v_fma_f32 v23, -v19, v22, v21
	v_fmac_f32_e32 v22, v23, v20
	v_fma_f32 v19, -v19, v22, v21
	v_div_fmas_f32 v19, v19, v20, v22
	v_div_fixup_f32 v18, v19, v18, 1.0
	s_and_saveexec_b64 s[8:9], s[6:7]
	s_cbranch_execz .LBB0_257
	s_lshl_b64 s[20:21], s[12:13], 6
	v_mul_f32_e32 v19, v18, v35
	v_lshl_add_u64 v[20:21], v[42:43], 0, s[20:21]
	global_store_dword v[20:21], v19, off

.LBB0_262:
	global_load_dwordx4 v[8:11], v[2:3], off offset:-2048 nt
	global_load_dwordx4 v[12:15], v[2:3], off offset:-1024 nt
	global_load_dwordx4 v[16:19], v[2:3], off nt
	global_load_dwordx4 v[20:23], v[2:3], off offset:1024 nt
	v_mov_b32_e32 v32, 0
	v_mov_b32_e32 v33, 0
	s_waitcnt vmcnt(3)
	v_mul_f32_e32 v34, v9, v9
	v_mul_f32_e32 v35, v11, v11
	s_waitcnt vmcnt(2)
	v_mul_f32_e32 v36, v13, v13
	v_mul_f32_e32 v37, v15, v15
	s_waitcnt vmcnt(1)
	v_mul_f32_e32 v38, v17, v17
	v_mul_f32_e32 v40, v19, v19
	v_fmac_f32_e32 v34, v8, v8
	v_fmac_f32_e32 v35, v10, v10
	v_fmac_f32_e32 v36, v12, v12
	v_fmac_f32_e32 v37, v14, v14
	s_waitcnt vmcnt(0)
	v_mul_f32_e32 v41, v21, v21
	v_mul_f32_e32 v42, v23, v23
	v_cvt_pk_bf16_f32 v24, v8, v9
	v_fmac_f32_e32 v38, v16, v16
	v_fmac_f32_e32 v40, v18, v18
	v_add_f32_e32 v8, v34, v35
	v_add_f32_e32 v9, v36, v37
	v_cvt_pk_bf16_f32 v25, v10, v11
	v_fmac_f32_e32 v41, v20, v20
	v_fmac_f32_e32 v42, v22, v22
	v_add_f32_e32 v10, v38, v40
	v_add_f32_e32 v8, v8, v9
	v_add_f32_e32 v11, v41, v42
	v_add_f32_e32 v8, v8, v10
	v_add_f32_e32 v8, v8, v11
	v_cvt_pk_bf16_f32 v30, v20, v21
	v_cvt_pk_bf16_f32 v31, v22, v23
	v_add_f32_dpp v8, v8, v8 row_ror:8 row_mask:0xf bank_mask:0xf bound_ctrl:1
	v_cvt_pk_bf16_f32 v26, v12, v13
	v_cvt_pk_bf16_f32 v27, v14, v15
	v_add_f32_dpp v8, v8, v8 row_ror:4 row_mask:0xf bank_mask:0xf bound_ctrl:1
	v_cvt_pk_bf16_f32 v28, v16, v17
	v_cvt_pk_bf16_f32 v29, v18, v19
	v_add_f32_dpp v8, v8, v8 quad_perm:[2,3,0,1] row_mask:0xf bank_mask:0xf bound_ctrl:1
	global_store_dwordx2 v[4:5], v[24:25], off offset:-1024
	global_store_dwordx2 v[4:5], v[26:27], off offset:-512
	global_store_dwordx2 v[4:5], v[28:29], off
	v_add_f32_dpp v8, v8, v8 quad_perm:[1,0,3,2] row_mask:0xf bank_mask:0xf bound_ctrl:1
	global_store_dwordx2 v[4:5], v[30:31], off offset:512
	s_nop 0
	s_nop 0
	v_add_f32_dpp v8, v8, v8 row_bcast:15 row_mask:0xa bank_mask:0xf
	s_nop 1
	s_nop 0
	v_add_f32_dpp v8, v8, v8 row_bcast:31 row_mask:0xc bank_mask:0xf
	s_nop 0
	v_readlane_b32 s6, v8, 63
	s_and_saveexec_b64 s[18:19], s[4:5]
	s_cbranch_execz .LBB0_261
	v_fma_f32 v8, s6, v7, v1
	v_mul_f32_e32 v9, 0x4f800000, v8
	v_cmp_gt_f32_e32 vcc, s11, v8
	s_nop 1
	v_cndmask_b32_e32 v8, v8, v9, vcc
	v_sqrt_f32_e32 v9, v8
	s_nop 0
	v_add_u32_e32 v10, -1, v9
	v_fma_f32 v12, -v10, v9, v8
	v_add_u32_e32 v11, 1, v9
	v_cmp_ge_f32_e64 s[6:7], 0, v12
	s_nop 1
	v_cndmask_b32_e64 v10, v9, v10, s[6:7]
	v_fma_f32 v9, -v11, v9, v8
	v_cmp_lt_f32_e64 s[6:7], 0, v9
	s_nop 1
	v_cndmask_b32_e64 v9, v10, v11, s[6:7]
	v_mul_f32_e32 v10, 0x37800000, v9
	v_cndmask_b32_e32 v9, v9, v10, vcc
	v_cmp_class_f32_e32 vcc, v8, v6
	s_nop 1
	v_cndmask_b32_e32 v8, v9, v8, vcc
	v_div_scale_f32 v9, s[6:7], v8, v8, 1.0
	v_rcp_f32_e32 v10, v9
	s_nop 0
	v_fma_f32 v11, -v9, v10, 1.0
	v_fmac_f32_e32 v10, v11, v10
	v_div_scale_f32 v11, vcc, 1.0, v8, 1.0
	v_mul_f32_e32 v12, v11, v10
	v_fma_f32 v13, -v9, v12, v11
	v_fmac_f32_e32 v12, v13, v10
	v_fma_f32 v9, -v9, v12, v11
	v_div_fmas_f32 v9, v9, v10, v12
	v_div_fixup_f32 v8, v9, v8, 1.0
	global_store_dword v39, v8, s[8:9]
	s_branch .LBB0_261

.LBB0_541:
	v_lshlrev_b32_e32 v94, 16, v35
	v_and_b32_e32 v95, 0xffff0000, v35
	s_and_b32 s6, s2, 31
	v_lshlrev_b32_e32 v158, 16, v32
	v_and_b32_e32 v159, 0xffff0000, v32
	v_lshlrev_b32_e32 v70, 16, v56
	v_lshlrev_b32_e32 v75, 16, v41
	v_and_b32_e32 v79, 0xffff0000, v41
	v_lshlrev_b32_e32 v56, 16, v40
	v_and_b32_e32 v60, 0xffff0000, v40
	v_lshlrev_b32_e32 v40, 16, v146
	v_and_b32_e32 v41, 0xffff0000, v146
	v_lshlrev_b32_e32 v28, 16, v147
	v_and_b32_e32 v32, 0xffff0000, v147
	s_lshl_b32 s4, s6, 6
	s_lshr_b32 s20, s45, 6
	s_and_b32 s5, s24, 0xfffff800
	s_nop 0
	v_pk_mul_f32 v[146:147], v[22:23], v[94:95]
	v_lshlrev_b32_e32 v86, 16, v38
	v_and_b32_e32 v87, 0xffff0000, v38
	s_or_b32 s15, s4, s5
	s_lshl_b32 s16, s20, 3
	s_lshl_b32 s14, s47, 1
	s_nop 0
	v_pk_fma_f32 v[146:147], v[24:25], v[158:159], v[146:147]
	v_lshlrev_b32_e32 v82, 16, v47
	v_and_b32_e32 v83, 0xffff0000, v47
	s_add_u32 s4, s3, s14
	v_pk_fma_f32 v[146:147], v[18:19], v[86:87], v[146:147]
	v_lshlrev_b32_e32 v58, 1, v156
	s_addc_u32 s5, s85, 0
	v_pk_fma_f32 v[146:147], v[20:21], v[82:83], v[146:147]
	v_lshlrev_b32_e32 v71, 16, v37
	v_lshlrev_b32_e32 v84, 16, v36
	v_and_b32_e32 v85, 0xffff0000, v36
	v_lshlrev_b32_e32 v72, 16, v55
	v_lshlrev_b32_e32 v74, 16, v54
	v_and_b32_e32 v163, 0xffff0000, v37
	v_lshlrev_b32_e32 v64, 16, v52
	v_and_b32_e32 v65, 0xffff0000, v52
	v_lshlrev_b32_e32 v62, 16, v44
	v_and_b32_e32 v63, 0xffff0000, v44
	v_lshlrev_b32_e32 v54, 16, v53
	v_and_b32_e32 v55, 0xffff0000, v53
	v_lshlrev_b32_e32 v52, 16, v45
	v_and_b32_e32 v53, 0xffff0000, v45
	v_lshlrev_b32_e32 v44, 16, v145
	v_and_b32_e32 v45, 0xffff0000, v145
	v_add_u32_e32 v145, 0, v58
	v_lshl_add_u64 v[36:37], s[4:5], 0, v[58:59]
	v_mul_f32_e32 v58, 0xbfb8aa3b, v146
	v_lshlrev_b32_e32 v89, 16, v33
	v_lshlrev_b32_e32 v88, 16, v30
	v_lshlrev_b32_e32 v73, 16, v39
	v_and_b32_e32 v91, 0xffff0000, v33
	v_and_b32_e32 v90, 0xffff0000, v30
	v_and_b32_e32 v77, 0xffff0000, v39
	v_lshlrev_b32_e32 v26, 16, v48
	v_lshlrev_b32_e32 v38, 16, v49
	v_and_b32_e32 v39, 0xffff0000, v49
	v_and_b32_e32 v30, 0xffff0000, v48
	v_lshlrev_b32_e32 v48, 16, v151
	v_and_b32_e32 v49, 0xffff0000, v151
	v_lshlrev_b32_e32 v29, 16, v150
	v_and_b32_e32 v33, 0xffff0000, v150
	v_pk_mul_f32 v[150:151], v[6:7], v[70:71] op_sel_hi:[0,1]
	v_exp_f32_e32 v58, v58
	v_mul_f32_e32 v70, 0xbfb8aa3b, v147
	v_exp_f32_e32 v70, v70
	v_lshlrev_b32_e32 v92, 16, v34
	v_add_f32_e32 v58, 1.0, v58
	v_rcp_f32_e32 v158, v58
	v_add_f32_e32 v58, 1.0, v70
	v_rcp_f32_e32 v159, v58
	v_and_b32_e32 v93, 0xffff0000, v34
	v_readlane_b32 s5, v153, s16
	v_lshlrev_b32_e32 v160, 16, v31
	v_pk_mul_f32 v[146:147], v[146:147], v[158:159]
	v_and_b32_e32 v161, 0xffff0000, v31
	v_lshlrev_b32_e32 v80, 16, v42
	v_and_b32_e32 v81, 0xffff0000, v42
	v_lshlrev_b32_e32 v68, 16, v51
	v_and_b32_e32 v69, 0xffff0000, v51
	v_lshlrev_b32_e32 v66, 16, v43
	v_and_b32_e32 v67, 0xffff0000, v43
	v_mov_b32_e32 v162, v91
	v_lshlrev_b32_e32 v57, 16, v50
	v_and_b32_e32 v61, 0xffff0000, v50
	v_lshlrev_b32_e32 v34, 16, v46
	v_and_b32_e32 v35, 0xffff0000, v46
	v_lshlrev_b32_e32 v46, 16, v149
	v_and_b32_e32 v47, 0xffff0000, v149
	v_lshlrev_b32_e32 v50, 16, v152
	v_and_b32_e32 v51, 0xffff0000, v152
	v_lshlrev_b32_e32 v42, 16, v148
	v_and_b32_e32 v43, 0xffff0000, v148
	s_nop 0
	v_pk_mul_f32 v[148:149], v[14:15], v[92:93]
	v_mul_f32_e32 v152, s5, v101
	v_mov_b32_e32 v58, s5
	v_pk_mul_f32 v[158:159], v[146:147], v[146:147]
	v_pk_mul_f32 v[156:157], v[6:7], v[162:163] op_sel:[1,0]
	v_exp_f32_e32 v162, v152
	v_sub_f32_e32 v152, s44, v58
	v_add_f32_e32 v58, v158, v159
	v_pk_fma_f32 v[148:149], v[10:11], v[160:161], v[148:149]
	s_nop 0
	v_add_f32_dpp v58, v58, v58 row_ror:8 row_mask:0xf bank_mask:0xf bound_ctrl:1
	s_nop 0
	v_pk_fma_f32 v[148:149], v[12:13], v[84:85], v[148:149]
	v_pk_mul_f32 v[160:161], v[22:23], v[86:87]
	v_add_f32_dpp v58, v58, v58 row_ror:4 row_mask:0xf bank_mask:0xf bound_ctrl:1
	s_nop 0
	v_pk_fma_f32 v[148:149], v[16:17], v[80:81], v[148:149]
	v_pk_fma_f32 v[94:95], v[24:25], v[94:95], v[160:161]
	v_add_f32_dpp v58, v58, v58 quad_perm:[2,3,0,1] row_mask:0xf bank_mask:0xf bound_ctrl:1
	v_mul_f32_e32 v158, 0xbfb8aa3b, v148
	v_exp_f32_e32 v158, v158
	v_add_f32_dpp v58, v58, v58 quad_perm:[1,0,3,2] row_mask:0xf bank_mask:0xf bound_ctrl:1
	v_mul_f32_e32 v159, 0xbfb8aa3b, v149
	v_exp_f32_e32 v159, v159
	s_nop 0
	v_add_f32_dpp v58, v58, v58 row_bcast:15 row_mask:0xa bank_mask:0xf
	s_nop 0
	v_mul_f32_e32 v152, 0x3fb8aa3b, v152
	v_pk_fma_f32 v[94:95], v[18:19], v[82:83], v[94:95]
	s_nop 0
	v_add_f32_dpp v58, v58, v58 row_bcast:31 row_mask:0xc bank_mask:0xf
	v_add_f32_e32 v70, 1.0, v158
	v_rcp_f32_e32 v158, v70
	v_add_f32_e32 v70, 1.0, v159
	v_rcp_f32_e32 v159, v70
	v_readlane_b32 s5, v58, 63
	v_pk_fma_f32 v[94:95], v[20:21], v[68:69], v[94:95]
	s_add_i32 s18, s16, s15
	v_pk_mul_f32 v[148:149], v[148:149], v[158:159]
	v_add_f32_e32 v58, s5, v102
	v_pk_mul_f32 v[158:159], v[148:149], v[148:149]
	v_rsq_f32_e32 v58, v58
	v_add_f32_e32 v70, v158, v159
	s_nop 0
	s_ashr_i32 s19, s18, 31
	v_add_f32_dpp v70, v70, v70 row_ror:8 row_mask:0xf bank_mask:0xf bound_ctrl:1
	v_pk_mul_f32 v[146:147], v[146:147], v[58:59] op_sel_hi:[1,0]
	s_lshl_b64 s[18:19], s[18:19], 11
	v_add_f32_dpp v70, v70, v70 row_ror:4 row_mask:0xf bank_mask:0xf bound_ctrl:1
	v_cvt_pk_bf16_f32 v58, v146, v147
	v_pk_mul_f32 v[146:147], v[146:147], v[162:163] op_sel_hi:[1,0]
	v_add_f32_dpp v70, v70, v70 quad_perm:[2,3,0,1] row_mask:0xf bank_mask:0xf bound_ctrl:1
	v_pk_mul_f32 v[146:147], v[146:147], s[8:9] op_sel_hi:[1,0]
	s_or_b32 s17, s16, 1
	v_add_f32_dpp v70, v70, v70 quad_perm:[1,0,3,2] row_mask:0xf bank_mask:0xf bound_ctrl:1
	v_readlane_b32 s21, v153, s17
	v_mov_b32_e32 v76, v163
	s_nop 0
	v_add_f32_dpp v70, v70, v70 row_bcast:15 row_mask:0xa bank_mask:0xf
	s_nop 0
	v_pk_fma_f32 v[90:91], v[2:3], v[90:91], v[156:157] op_sel:[1,0,0]
	v_mov_b32_e32 v78, v77
	s_nop 0
	v_add_f32_dpp v70, v70, v70 row_bcast:31 row_mask:0xc bank_mask:0xf
	v_exp_f32_e32 v158, v152
	v_readlane_b32 s5, v70, 63
	v_pk_fma_f32 v[90:91], v[4:5], v[76:77], v[90:91] op_sel:[1,0,0]
	v_pk_fma_f32 v[88:89], v[2:3], v[88:89], v[150:151] op_sel_hi:[0,1,1]
	v_add_f32_e32 v70, s5, v102
	v_rsq_f32_e32 v70, v70
	s_mul_i32 s5, s20, 0x880
	v_pk_fma_f32 v[90:91], v[8:9], v[78:79], v[90:91] op_sel:[1,0,0]
	v_pk_fma_f32 v[88:89], v[4:5], v[72:73], v[88:89] op_sel_hi:[0,1,1]
	v_pk_mul_f32 v[148:149], v[148:149], v[70:71] op_sel_hi:[1,0]
	v_add_u32_e32 v70, s5, v145
	v_cvt_pk_bf16_f32 v152, v148, v149
	ds_write2st64_b32 v70, v58, v152 offset1:68
	v_mul_f32_e32 v70, 0xbfb8aa3b, v94
	v_exp_f32_e32 v70, v70
	v_mul_f32_e32 v152, 0xbfb8aa3b, v95
	v_exp_f32_e32 v152, v152
	v_cvt_pk_bf16_f32 v58, v146, v147
	v_lshl_add_u64 v[146:147], v[36:37], 0, s[18:19]
	global_store_dword v[146:147], v58, off
	v_add_f32_e32 v58, 1.0, v70
	v_rcp_f32_e32 v146, v58
	v_add_f32_e32 v58, 1.0, v152
	v_rcp_f32_e32 v147, v58
	s_nop 0
	v_pk_fma_f32 v[88:89], v[8:9], v[74:75], v[88:89] op_sel_hi:[0,1,1]
	v_mul_f32_e32 v72, 0xbfb8aa3b, v89
	v_pk_mul_f32 v[94:95], v[94:95], v[146:147]
	v_exp_f32_e32 v72, v72
	v_pk_mul_f32 v[146:147], v[94:95], v[94:95]
	v_readlane_b32 s4, v154, s16
	v_add_f32_e32 v58, v146, v147
	v_pk_mul_f32 v[146:147], v[14:15], v[84:85]
	v_readlane_b32 s5, v154, s17
	v_pk_fma_f32 v[92:93], v[10:11], v[92:93], v[146:147]
	v_add_f32_dpp v58, v58, v58 row_ror:8 row_mask:0xf bank_mask:0xf bound_ctrl:1
	v_pk_fma_f32 v[92:93], v[12:13], v[80:81], v[92:93]
	s_or_b32 s22, s16, 2
	v_add_f32_dpp v58, v58, v58 row_ror:4 row_mask:0xf bank_mask:0xf bound_ctrl:1
	v_pk_fma_f32 v[92:93], v[16:17], v[66:67], v[92:93]
	s_add_i32 s48, s22, s15
	v_add_f32_dpp v58, v58, v58 quad_perm:[2,3,0,1] row_mask:0xf bank_mask:0xf bound_ctrl:1
	v_mul_f32_e32 v146, 0xbfb8aa3b, v92
	v_exp_f32_e32 v146, v146
	v_add_f32_dpp v58, v58, v58 quad_perm:[1,0,3,2] row_mask:0xf bank_mask:0xf bound_ctrl:1
	v_mul_f32_e32 v147, 0xbfb8aa3b, v93
	v_exp_f32_e32 v147, v147
	s_nop 0
	v_add_f32_dpp v58, v58, v58 row_bcast:15 row_mask:0xa bank_mask:0xf
	s_nop 0
	s_ashr_i32 s49, s48, 31
	s_lshl_b64 s[48:49], s[48:49], 11
	s_nop 0
	v_add_f32_dpp v58, v58, v58 row_bcast:31 row_mask:0xc bank_mask:0xf
	v_add_f32_e32 v70, 1.0, v146
	v_rcp_f32_e32 v146, v70
	v_add_f32_e32 v70, 1.0, v147
	v_rcp_f32_e32 v147, v70
	v_readlane_b32 s18, v58, 63
	s_or_b32 s23, s16, 3
	v_readlane_b32 s47, v153, s23
	v_pk_mul_f32 v[92:93], v[92:93], v[146:147]
	v_add_f32_e32 v58, s18, v102
	v_pk_mul_f32 v[146:147], v[92:93], v[92:93]
	v_rsq_f32_e32 v58, v58
	v_add_f32_e32 v70, v146, v147
	s_nop 0
	v_and_b32_e32 v31, 0xffff0000, v144
	v_add_f32_dpp v70, v70, v70 row_ror:8 row_mask:0xf bank_mask:0xf bound_ctrl:1
	v_pk_mul_f32 v[94:95], v[94:95], v[58:59] op_sel_hi:[1,0]
	v_lshlrev_b32_e32 v27, 16, v144
	v_add_f32_dpp v70, v70, v70 row_ror:4 row_mask:0xf bank_mask:0xf bound_ctrl:1
	v_cvt_pk_bf16_f32 v58, v94, v95
	v_and_b32_e32 v144, 15, v106
	v_add_f32_dpp v70, v70, v70 quad_perm:[2,3,0,1] row_mask:0xf bank_mask:0xf bound_ctrl:1
	s_nop 1
	v_add_f32_dpp v70, v70, v70 quad_perm:[1,0,3,2] row_mask:0xf bank_mask:0xf bound_ctrl:1
	s_nop 1
	s_nop 0
	v_add_f32_dpp v70, v70, v70 row_bcast:15 row_mask:0xa bank_mask:0xf
	s_nop 0
	s_nop 1
	s_nop 0
	v_add_f32_dpp v70, v70, v70 row_bcast:31 row_mask:0xc bank_mask:0xf
	v_mul_f32_e32 v146, s21, v101
	v_readlane_b32 s18, v70, 63
	v_exp_f32_e32 v146, v146
	s_nop 0
	v_add_f32_e32 v70, s18, v102
	v_rsq_f32_e32 v70, v70
	s_mul_i32 s18, s17, 0x110
	v_pk_mul_f32 v[94:95], v[94:95], v[146:147] op_sel_hi:[1,0]
	v_mov_b32_e32 v163, v146
	v_pk_mul_f32 v[160:161], v[92:93], v[70:71] op_sel_hi:[1,0]
	v_add_u32_e32 v92, s18, v145
	s_add_i32 s18, s17, s15
	s_ashr_i32 s19, s18, 31
	ds_write_b32 v92, v58
	v_cvt_pk_bf16_f32 v58, v160, v161
	v_pk_mul_f32 v[94:95], v[94:95], s[8:9] op_sel_hi:[1,0]
	s_lshl_b64 s[18:19], s[18:19], 11
	v_mov_b32_e32 v70, s21
	ds_write_b32 v92, v58 offset:17408
	v_cvt_pk_bf16_f32 v58, v94, v95
	v_lshl_add_u64 v[94:95], v[36:37], 0, s[18:19]
	v_sub_f32_e32 v70, s44, v70
	v_mul_f32_e32 v70, 0x3fb8aa3b, v70
	global_store_dword v[94:95], v58, off
	v_mul_f32_e32 v58, 0xbfb8aa3b, v90
	v_exp_f32_e32 v159, v70
	v_exp_f32_e32 v58, v58
	v_mul_f32_e32 v70, 0xbfb8aa3b, v91
	v_exp_f32_e32 v70, v70
	v_mov_b32_e32 v94, v149
	v_add_f32_e32 v58, 1.0, v58
	v_rcp_f32_e32 v156, v58
	v_add_f32_e32 v58, 1.0, v70
	v_mul_f32_e32 v70, 0xbfb8aa3b, v88
	v_exp_f32_e32 v70, v70
	v_rcp_f32_e32 v157, v58
	v_mov_b32_e32 v95, v161
	v_mov_b32_e32 v149, v160
	v_add_f32_e32 v58, 1.0, v70
	v_rcp_f32_e32 v150, v58
	v_add_f32_e32 v58, 1.0, v72
	v_rcp_f32_e32 v151, v58
	v_pk_mul_f32 v[90:91], v[90:91], v[156:157]
	s_lshl_b32 s21, s20, 4
	v_pk_mul_f32 v[164:165], v[94:95], v[158:159]
	v_pk_mul_f32 v[88:89], v[88:89], v[150:151]
	v_pk_mul_f32 v[90:91], v[90:91], s[4:5]
	v_pk_mul_f32 v[88:89], v[88:89], s[4:5]
	v_pk_mul_f32 v[94:95], v[94:95], s[4:5]
	v_pk_mul_f32 v[146:147], v[148:149], s[4:5]
	s_and_b32 s5, s21, 0x3fffffc0
	s_add_i32 s18, s38, s5
	s_lshr_b32 s5, s45, 1
	v_pk_mul_f32 v[146:147], v[146:147], v[162:163]
	s_add_i32 s4, s21, 0
	s_and_b32 s19, s5, 32
	s_lshr_b32 s17, s45, 4
	v_mul_u32_u24_e32 v58, 0x48, v155
	s_add_i32 s5, s18, s19
	s_and_b32 s17, s17, 8
	v_cvt_pk_bf16_f32 v70, v146, v147
	v_lshl_add_u32 v58, v58, 1, s4
	v_pk_mul_f32 v[158:159], v[148:149], v[158:159]
	s_add_i32 s5, s5, s17
	ds_write_b32 v58, v70 offset:53248
	v_cvt_pk_bf16_f32 v70, v88, v89
	v_lshlrev_b32_e32 v88, 7, v155
	v_pk_mul_f32 v[94:95], v[94:95], v[162:163]
	ds_write_b32 v58, v70 offset:34816
	v_cvt_pk_bf16_f32 v70, v158, v159
	v_add_u32_e32 v72, s5, v88
	ds_write_b32 v72, v70
	v_cvt_pk_bf16_f32 v70, v94, v95
	ds_write_b32 v58, v70 offset:53392
	v_cvt_pk_bf16_f32 v70, v90, v91
	v_pk_mul_f32 v[90:91], v[22:23], v[82:83]
	v_or_b32_e32 v89, 0x80, v88
	v_pk_fma_f32 v[86:87], v[24:25], v[86:87], v[90:91]
	ds_write_b32 v58, v70 offset:34960
	v_pk_fma_f32 v[86:87], v[18:19], v[68:69], v[86:87]
	v_cvt_pk_bf16_f32 v70, v164, v165
	v_add_u32_e32 v72, s5, v89
	v_pk_fma_f32 v[86:87], v[20:21], v[64:65], v[86:87]
	ds_write_b32 v72, v70
	v_mul_f32_e32 v70, 0xbfb8aa3b, v86
	v_exp_f32_e32 v70, v70
	v_mul_f32_e32 v72, 0xbfb8aa3b, v87
	v_exp_f32_e32 v72, v72
	v_readlane_b32 s5, v153, s22
	v_add_f32_e32 v70, 1.0, v70
	v_rcp_f32_e32 v90, v70
	v_add_f32_e32 v70, 1.0, v72
	v_rcp_f32_e32 v91, v70
	v_mul_f32_e32 v93, s5, v101
	v_mov_b32_e32 v70, s5
	v_exp_f32_e32 v94, v93
	v_pk_mul_f32 v[86:87], v[86:87], v[90:91]
	v_sub_f32_e32 v93, s44, v70
	v_pk_mul_f32 v[90:91], v[86:87], v[86:87]
	s_nop 0
	v_add_f32_e32 v70, v90, v91
	v_pk_mul_f32 v[90:91], v[14:15], v[80:81]
	v_pk_mul_f32 v[146:147], v[22:23], v[68:69]
	v_pk_fma_f32 v[84:85], v[10:11], v[84:85], v[90:91]
	v_add_f32_dpp v70, v70, v70 row_ror:8 row_mask:0xf bank_mask:0xf bound_ctrl:1
	v_pk_fma_f32 v[84:85], v[12:13], v[66:67], v[84:85]
	v_pk_fma_f32 v[82:83], v[24:25], v[82:83], v[146:147]
	v_add_f32_dpp v70, v70, v70 row_ror:4 row_mask:0xf bank_mask:0xf bound_ctrl:1
	v_pk_fma_f32 v[84:85], v[16:17], v[62:63], v[84:85]
	v_pk_fma_f32 v[82:83], v[18:19], v[64:65], v[82:83]
	v_add_f32_dpp v70, v70, v70 quad_perm:[2,3,0,1] row_mask:0xf bank_mask:0xf bound_ctrl:1
	v_mul_f32_e32 v90, 0xbfb8aa3b, v84
	v_exp_f32_e32 v90, v90
	v_add_f32_dpp v70, v70, v70 quad_perm:[1,0,3,2] row_mask:0xf bank_mask:0xf bound_ctrl:1
	v_mul_f32_e32 v91, 0xbfb8aa3b, v85
	v_exp_f32_e32 v91, v91
	s_nop 0
	v_add_f32_dpp v70, v70, v70 row_bcast:15 row_mask:0xa bank_mask:0xf
	s_nop 0
	v_pk_fma_f32 v[82:83], v[20:21], v[54:55], v[82:83]
	v_pk_mul_f32 v[148:149], v[6:7], v[78:79] op_sel:[1,0]
	s_nop 0
	v_add_f32_dpp v70, v70, v70 row_bcast:31 row_mask:0xc bank_mask:0xf
	v_add_f32_e32 v72, 1.0, v90
	v_rcp_f32_e32 v90, v72
	v_add_f32_e32 v72, 1.0, v91
	v_rcp_f32_e32 v91, v72
	v_readlane_b32 s5, v70, 63
	v_pk_fma_f32 v[148:149], v[2:3], v[76:77], v[148:149] op_sel:[1,0,0]
	v_pk_mov_b32 v[76:77], v[78:79], v[60:61] op_sel:[1,0]
	v_pk_mul_f32 v[84:85], v[84:85], v[90:91]
	v_add_f32_e32 v70, s5, v102
	v_pk_mul_f32 v[90:91], v[84:85], v[84:85]
	v_rsq_f32_e32 v70, v70
	v_add_f32_e32 v72, v90, v91
	s_nop 0
	v_pk_fma_f32 v[78:79], v[4:5], v[76:77], v[148:149] op_sel:[1,0,0]
	v_add_f32_dpp v72, v72, v72 row_ror:8 row_mask:0xf bank_mask:0xf bound_ctrl:1
	v_pk_mul_f32 v[86:87], v[86:87], v[70:71] op_sel_hi:[1,0]
	v_pk_fma_f32 v[78:79], v[8:9], v[60:61], v[78:79] op_sel:[1,0,0]
	v_add_f32_dpp v72, v72, v72 row_ror:4 row_mask:0xf bank_mask:0xf bound_ctrl:1
	v_cvt_pk_bf16_f32 v91, v86, v87
	v_pk_mul_f32 v[86:87], v[86:87], v[94:95] op_sel_hi:[1,0]
	v_add_f32_dpp v72, v72, v72 quad_perm:[2,3,0,1] row_mask:0xf bank_mask:0xf bound_ctrl:1
	v_mul_f32_e32 v95, 0xbfb8aa3b, v83
	v_exp_f32_e32 v95, v95
	v_add_f32_dpp v72, v72, v72 quad_perm:[1,0,3,2] row_mask:0xf bank_mask:0xf bound_ctrl:1
	v_pk_mul_f32 v[86:87], v[86:87], s[8:9] op_sel_hi:[1,0]
	v_readlane_b32 s4, v154, s22
	s_nop 0
	v_add_f32_dpp v72, v72, v72 row_bcast:15 row_mask:0xa bank_mask:0xf
	s_nop 0
	v_cvt_pk_bf16_f32 v70, v86, v87
	v_lshl_add_u64 v[86:87], v[36:37], 0, s[48:49]
	s_nop 0
	v_add_f32_dpp v72, v72, v72 row_bcast:31 row_mask:0xc bank_mask:0xf
	global_store_dword v[86:87], v70, off
	v_readlane_b32 s5, v72, 63
	v_mul_f32_e32 v90, 0x3fb8aa3b, v93
	v_exp_f32_e32 v90, v90
	v_add_f32_e32 v72, s5, v102
	v_rsq_f32_e32 v72, v72
	v_readlane_b32 s5, v154, s23
	v_pk_mul_f32 v[84:85], v[84:85], v[72:73] op_sel_hi:[1,0]
	v_mul_f32_e32 v72, 0xbfb8aa3b, v82
	v_exp_f32_e32 v72, v72
	v_cvt_pk_bf16_f32 v93, v84, v85
	v_add_f32_e32 v70, 1.0, v72
	v_rcp_f32_e32 v86, v70
	v_add_f32_e32 v70, 1.0, v95
	v_rcp_f32_e32 v87, v70
	s_nop 0
	v_pk_mul_f32 v[82:83], v[82:83], v[86:87]
	s_nop 0
	v_pk_mul_f32 v[86:87], v[82:83], v[82:83]
	s_nop 0
	v_add_f32_e32 v70, v86, v87
	v_pk_mul_f32 v[86:87], v[14:15], v[66:67]
	s_nop 0
	v_pk_fma_f32 v[80:81], v[10:11], v[80:81], v[86:87]
	v_add_f32_dpp v70, v70, v70 row_ror:8 row_mask:0xf bank_mask:0xf bound_ctrl:1
	v_pk_fma_f32 v[80:81], v[12:13], v[62:63], v[80:81]
	s_nop 0
	v_add_f32_dpp v70, v70, v70 row_ror:4 row_mask:0xf bank_mask:0xf bound_ctrl:1
	v_pk_fma_f32 v[80:81], v[16:17], v[52:53], v[80:81]
	s_nop 0
	v_add_f32_dpp v70, v70, v70 quad_perm:[2,3,0,1] row_mask:0xf bank_mask:0xf bound_ctrl:1
	v_mul_f32_e32 v86, 0xbfb8aa3b, v80
	v_exp_f32_e32 v86, v86
	v_add_f32_dpp v70, v70, v70 quad_perm:[1,0,3,2] row_mask:0xf bank_mask:0xf bound_ctrl:1
	v_mul_f32_e32 v87, 0xbfb8aa3b, v81
	v_exp_f32_e32 v87, v87
	s_nop 0
	v_add_f32_dpp v70, v70, v70 row_bcast:15 row_mask:0xa bank_mask:0xf
	s_nop 0
	s_nop 1
	s_nop 0
	v_add_f32_dpp v70, v70, v70 row_bcast:31 row_mask:0xc bank_mask:0xf
	v_add_f32_e32 v72, 1.0, v86
	v_rcp_f32_e32 v86, v72
	v_add_f32_e32 v72, 1.0, v87
	v_rcp_f32_e32 v87, v72
	v_readlane_b32 s48, v70, 63
	v_pk_mul_f32 v[80:81], v[80:81], v[86:87]
	s_nop 0
	v_pk_mul_f32 v[86:87], v[80:81], v[80:81]
	v_add_f32_e32 v70, s48, v102
	v_add_f32_e32 v72, v86, v87
	s_nop 0
	v_rsq_f32_e32 v70, v70
	v_add_f32_dpp v72, v72, v72 row_ror:8 row_mask:0xf bank_mask:0xf bound_ctrl:1
	v_pk_mul_f32 v[82:83], v[82:83], v[70:71] op_sel_hi:[1,0]
	s_nop 0
	v_add_f32_dpp v72, v72, v72 row_ror:4 row_mask:0xf bank_mask:0xf bound_ctrl:1
	v_cvt_pk_bf16_f32 v70, v82, v83
	ds_write2_b32 v92, v91, v70 offset0:68 offset1:136
	v_add_f32_dpp v72, v72, v72 quad_perm:[2,3,0,1] row_mask:0xf bank_mask:0xf bound_ctrl:1
	s_nop 1
	v_add_f32_dpp v72, v72, v72 quad_perm:[1,0,3,2] row_mask:0xf bank_mask:0xf bound_ctrl:1
	s_nop 1
	s_nop 0
	v_add_f32_dpp v72, v72, v72 row_bcast:15 row_mask:0xa bank_mask:0xf
	s_nop 0
	s_nop 1
	s_nop 0
	v_add_f32_dpp v72, v72, v72 row_bcast:31 row_mask:0xc bank_mask:0xf
	v_mul_f32_e32 v86, s47, v101
	v_readlane_b32 s48, v72, 63
	v_exp_f32_e32 v86, v86
	s_nop 0
	v_add_f32_e32 v72, s48, v102
	v_rsq_f32_e32 v72, v72
	s_add_i32 s48, s23, s15
	v_pk_mul_f32 v[82:83], v[82:83], v[86:87] op_sel_hi:[1,0]
	s_ashr_i32 s49, s48, 31
	v_pk_mul_f32 v[80:81], v[80:81], v[72:73] op_sel_hi:[1,0]
	v_add_u32_e32 v72, 0x4400, v92
	v_cvt_pk_bf16_f32 v70, v80, v81
	ds_write2_b32 v72, v93, v70 offset0:68 offset1:136
	v_pk_mul_f32 v[82:83], v[82:83], s[8:9] op_sel_hi:[1,0]
	s_lshl_b64 s[48:49], s[48:49], 11
	v_mov_b32_e32 v72, s47
	v_cvt_pk_bf16_f32 v70, v82, v83
	v_lshl_add_u64 v[82:83], v[36:37], 0, s[48:49]
	v_sub_f32_e32 v72, s44, v72
	v_mul_f32_e32 v72, 0x3fb8aa3b, v72
	global_store_dword v[82:83], v70, off
	v_mul_f32_e32 v70, 0xbfb8aa3b, v78
	v_exp_f32_e32 v91, v72
	v_exp_f32_e32 v70, v70
	v_mul_f32_e32 v72, 0xbfb8aa3b, v79
	v_exp_f32_e32 v72, v72
	v_mov_b32_e32 v82, v85
	v_add_f32_e32 v70, 1.0, v70
	v_mov_b32_e32 v83, v81
	v_mov_b32_e32 v85, v80
	v_rcp_f32_e32 v80, v70
	v_add_f32_e32 v81, 1.0, v72
	v_mov_b32_e32 v72, v71
	v_mov_b32_e32 v70, v73
	v_mov_b32_e32 v71, v75
	v_pk_mul_f32 v[70:71], v[6:7], v[70:71] op_sel_hi:[0,1]
	v_pk_fma_f32 v[72:73], v[2:3], v[72:73], v[70:71] op_sel_hi:[0,1,1]
	v_pk_mov_b32 v[70:71], v[74:75], v[56:57] op_sel:[1,0]
	v_rcp_f32_e32 v81, v81
	v_pk_fma_f32 v[72:73], v[4:5], v[70:71], v[72:73] op_sel_hi:[0,1,1]
	v_pk_fma_f32 v[72:73], v[8:9], v[56:57], v[72:73] op_sel_hi:[0,1,1]
	v_mul_f32_e32 v74, 0xbfb8aa3b, v72
	v_mul_f32_e32 v75, 0xbfb8aa3b, v73
	v_exp_f32_e32 v74, v74
	v_exp_f32_e32 v75, v75
	v_pk_mul_f32 v[78:79], v[78:79], v[80:81]
	v_pk_mul_f32 v[80:81], v[84:85], s[4:5]
	v_add_f32_e32 v74, 1.0, v74
	v_add_f32_e32 v75, 1.0, v75
	v_rcp_f32_e32 v74, v74
	v_rcp_f32_e32 v75, v75
	v_pk_mul_f32 v[78:79], v[78:79], s[4:5]
	v_mov_b32_e32 v95, v86
	v_pk_mul_f32 v[146:147], v[82:83], v[90:91]
	v_pk_mul_f32 v[72:73], v[72:73], v[74:75]
	v_pk_mul_f32 v[74:75], v[82:83], s[4:5]
	v_pk_mul_f32 v[72:73], v[72:73], s[4:5]
	s_and_b32 s4, s22, 0x1fffffe2
	s_lshl_b32 s4, s4, 1
	s_add_i32 s4, s38, s4
	s_add_i32 s4, s4, s19
	v_pk_mul_f32 v[90:91], v[84:85], v[90:91]
	v_pk_mul_f32 v[80:81], v[80:81], v[94:95]
	s_add_i32 s4, s4, s17
	v_cvt_pk_bf16_f32 v72, v72, v73
	v_pk_mul_f32 v[74:75], v[74:75], v[94:95]
	v_cvt_pk_bf16_f32 v80, v80, v81
	ds_write_b32 v58, v72 offset:34820
	v_cvt_pk_bf16_f32 v72, v90, v91
	v_add_u32_e32 v73, s4, v88
	ds_write_b32 v58, v80 offset:53252
	ds_write_b32 v73, v72
	v_cvt_pk_bf16_f32 v72, v74, v75
	ds_write_b32 v58, v72 offset:53396
	v_cvt_pk_bf16_f32 v72, v78, v79
	ds_write_b32 v58, v72 offset:34964
	v_cvt_pk_bf16_f32 v72, v146, v147
	v_add_u32_e32 v73, s4, v89
	ds_write_b32 v73, v72
	v_pk_mul_f32 v[72:73], v[22:23], v[64:65]
	v_mov_b32_e32 v79, v59
	v_pk_fma_f32 v[68:69], v[24:25], v[68:69], v[72:73]
	s_or_b32 s19, s16, 4
	v_pk_fma_f32 v[68:69], v[18:19], v[54:55], v[68:69]
	v_readlane_b32 s5, v153, s19
	v_pk_fma_f32 v[68:69], v[20:21], v[44:45], v[68:69]
	s_add_i32 s22, s19, s15
	v_mul_f32_e32 v72, 0xbfb8aa3b, v68
	v_mul_f32_e32 v73, 0xbfb8aa3b, v69
	v_exp_f32_e32 v72, v72
	v_exp_f32_e32 v73, v73
	v_mul_f32_e32 v74, s5, v101
	v_mov_b32_e32 v75, s5
	v_add_f32_e32 v72, 1.0, v72
	v_add_f32_e32 v73, 1.0, v73
	v_rcp_f32_e32 v72, v72
	v_rcp_f32_e32 v73, v73
	v_sub_f32_e32 v75, s44, v75
	v_exp_f32_e32 v74, v74
	s_ashr_i32 s23, s22, 31
	v_pk_mul_f32 v[68:69], v[68:69], v[72:73]
	s_lshl_b64 s[22:23], s[22:23], 11
	v_pk_mul_f32 v[72:73], v[68:69], v[68:69]
	v_readlane_b32 s4, v154, s19
	v_add_f32_e32 v72, v72, v73
	v_mov_b32_e32 v73, v59
	s_nop 0
	v_add_f32_dpp v72, v72, v72 row_ror:8 row_mask:0xf bank_mask:0xf bound_ctrl:1
	s_nop 1
	v_add_f32_dpp v72, v72, v72 row_ror:4 row_mask:0xf bank_mask:0xf bound_ctrl:1
	s_nop 1
	v_add_f32_dpp v72, v72, v72 quad_perm:[2,3,0,1] row_mask:0xf bank_mask:0xf bound_ctrl:1
	s_nop 1
	v_add_f32_dpp v72, v72, v72 quad_perm:[1,0,3,2] row_mask:0xf bank_mask:0xf bound_ctrl:1
	s_nop 1
	v_mov_b32_dpp v73, v72 row_bcast:15 row_mask:0xa bank_mask:0xf
	v_add_f32_e32 v78, v72, v73
	v_pk_mul_f32 v[72:73], v[14:15], v[62:63]
	s_nop 0
	v_pk_fma_f32 v[66:67], v[10:11], v[66:67], v[72:73]
	s_nop 0
	v_pk_fma_f32 v[66:67], v[12:13], v[52:53], v[66:67]
	v_add_f32_dpp v78, v78, v78 row_bcast:31 row_mask:0xc bank_mask:0xf
	v_pk_fma_f32 v[66:67], v[16:17], v[34:35], v[66:67]
	v_readlane_b32 s5, v78, 63
	v_mul_f32_e32 v72, 0xbfb8aa3b, v66
	v_mul_f32_e32 v73, 0xbfb8aa3b, v67
	v_exp_f32_e32 v72, v72
	v_exp_f32_e32 v73, v73
	v_add_f32_e32 v78, s5, v102
	v_rsq_f32_e32 v78, v78
	v_add_f32_e32 v72, 1.0, v72
	v_add_f32_e32 v73, 1.0, v73
	v_rcp_f32_e32 v72, v72
	v_rcp_f32_e32 v73, v73
	v_pk_mul_f32 v[68:69], v[68:69], v[78:79] op_sel_hi:[1,0]
	v_pk_mul_f32 v[66:67], v[66:67], v[72:73]
	s_nop 0
	v_pk_mul_f32 v[72:73], v[66:67], v[66:67]
	s_nop 0
	v_add_f32_e32 v72, v72, v73
	s_nop 0
	s_nop 0
	v_add_f32_dpp v72, v72, v72 row_ror:8 row_mask:0xf bank_mask:0xf bound_ctrl:1
	s_nop 1
	v_add_f32_dpp v72, v72, v72 row_ror:4 row_mask:0xf bank_mask:0xf bound_ctrl:1
	s_nop 1
	v_add_f32_dpp v72, v72, v72 quad_perm:[2,3,0,1] row_mask:0xf bank_mask:0xf bound_ctrl:1
	s_nop 1
	v_add_f32_dpp v72, v72, v72 quad_perm:[1,0,3,2] row_mask:0xf bank_mask:0xf bound_ctrl:1
	s_nop 1
	s_nop 0
	v_add_f32_dpp v72, v72, v72 row_bcast:15 row_mask:0xa bank_mask:0xf
	s_nop 0
	s_nop 1
	s_nop 0
	v_add_f32_dpp v72, v72, v72 row_bcast:31 row_mask:0xc bank_mask:0xf
	v_mul_f32_e32 v73, 0x3fb8aa3b, v75
	v_readlane_b32 s5, v72, 63
	v_exp_f32_e32 v80, v73
	v_cvt_pk_bf16_f32 v75, v68, v69
	v_add_f32_e32 v72, s5, v102
	v_rsq_f32_e32 v72, v72
	v_pk_mul_f32 v[68:69], v[68:69], v[74:75] op_sel_hi:[1,0]
	v_pk_mul_f32 v[66:67], v[66:67], v[72:73] op_sel_hi:[1,0]
	v_pk_mul_f32 v[72:73], v[22:23], v[54:55]
	v_pk_mul_f32 v[68:69], v[68:69], s[8:9] op_sel_hi:[1,0]
	v_pk_fma_f32 v[64:65], v[24:25], v[64:65], v[72:73]
	v_cvt_pk_bf16_f32 v78, v68, v69
	v_pk_fma_f32 v[64:65], v[18:19], v[44:45], v[64:65]
	v_lshl_add_u64 v[68:69], v[36:37], 0, s[22:23]
	v_pk_fma_f32 v[64:65], v[20:21], v[46:47], v[64:65]
	global_store_dword v[68:69], v78, off
	v_mul_f32_e32 v72, 0xbfb8aa3b, v64
	v_mul_f32_e32 v73, 0xbfb8aa3b, v65
	v_exp_f32_e32 v72, v72
	v_exp_f32_e32 v73, v73
	s_or_b32 s22, s16, 5
	v_readlane_b32 s47, v153, s22
	v_add_f32_e32 v68, 1.0, v72
	v_add_f32_e32 v69, 1.0, v73
	v_rcp_f32_e32 v68, v68
	v_rcp_f32_e32 v69, v69
	v_mov_b32_e32 v73, v59
	v_cvt_pk_bf16_f32 v79, v66, v67
	v_readlane_b32 s5, v154, s22
	v_pk_mul_f32 v[64:65], v[64:65], v[68:69]
	s_add_i32 s22, s22, s15
	v_pk_mul_f32 v[68:69], v[64:65], v[64:65]
	s_nop 0
	v_add_f32_e32 v68, v68, v69
	v_mov_b32_e32 v69, v59
	s_nop 0
	v_add_f32_dpp v68, v68, v68 row_ror:8 row_mask:0xf bank_mask:0xf bound_ctrl:1
	s_nop 1
	v_add_f32_dpp v68, v68, v68 row_ror:4 row_mask:0xf bank_mask:0xf bound_ctrl:1
	s_nop 1
	v_add_f32_dpp v68, v68, v68 quad_perm:[2,3,0,1] row_mask:0xf bank_mask:0xf bound_ctrl:1
	s_nop 1
	v_add_f32_dpp v68, v68, v68 quad_perm:[1,0,3,2] row_mask:0xf bank_mask:0xf bound_ctrl:1
	s_nop 1
	v_mov_b32_dpp v69, v68 row_bcast:15 row_mask:0xa bank_mask:0xf
	v_add_f32_e32 v72, v68, v69
	v_pk_mul_f32 v[68:69], v[14:15], v[52:53]
	s_nop 0
	v_pk_fma_f32 v[62:63], v[10:11], v[62:63], v[68:69]
	s_nop 0
	v_pk_fma_f32 v[62:63], v[12:13], v[34:35], v[62:63]
	v_add_f32_dpp v72, v72, v72 row_bcast:31 row_mask:0xc bank_mask:0xf
	v_pk_fma_f32 v[62:63], v[16:17], v[38:39], v[62:63]
	v_readlane_b32 s23, v72, 63
	v_mul_f32_e32 v68, 0xbfb8aa3b, v62
	v_mul_f32_e32 v69, 0xbfb8aa3b, v63
	v_exp_f32_e32 v68, v68
	v_exp_f32_e32 v69, v69
	v_add_f32_e32 v72, s23, v102
	v_rsq_f32_e32 v72, v72
	v_add_f32_e32 v68, 1.0, v68
	v_add_f32_e32 v69, 1.0, v69
	v_rcp_f32_e32 v68, v68
	v_rcp_f32_e32 v69, v69
	v_pk_mul_f32 v[64:65], v[64:65], v[72:73] op_sel_hi:[1,0]
	v_pk_mul_f32 v[72:73], v[6:7], v[60:61] op_sel:[1,0]
	v_pk_mov_b32 v[60:61], v[60:61], v[30:31] op_sel:[1,0]
	v_pk_mul_f32 v[62:63], v[62:63], v[68:69]
	v_pk_fma_f32 v[72:73], v[2:3], v[76:77], v[72:73] op_sel:[1,0,0]
	v_pk_mul_f32 v[68:69], v[62:63], v[62:63]
	v_pk_fma_f32 v[72:73], v[4:5], v[60:61], v[72:73] op_sel:[1,0,0]
	v_add_f32_e32 v68, v68, v69
	s_nop 0
	v_pk_fma_f32 v[72:73], v[8:9], v[30:31], v[72:73] op_sel:[1,0,0]
	v_add_f32_dpp v68, v68, v68 row_ror:8 row_mask:0xf bank_mask:0xf bound_ctrl:1
	v_pk_mul_f32 v[76:77], v[6:7], v[56:57] op_sel_hi:[0,1]
	v_pk_fma_f32 v[70:71], v[2:3], v[70:71], v[76:77] op_sel_hi:[0,1,1]
	v_add_f32_dpp v68, v68, v68 row_ror:4 row_mask:0xf bank_mask:0xf bound_ctrl:1
	v_pk_mov_b32 v[56:57], v[56:57], v[26:27] op_sel:[1,0]
	s_nop 0
	v_add_f32_dpp v68, v68, v68 quad_perm:[2,3,0,1] row_mask:0xf bank_mask:0xf bound_ctrl:1
	v_pk_fma_f32 v[70:71], v[4:5], v[56:57], v[70:71] op_sel_hi:[0,1,1]
	v_pk_fma_f32 v[70:71], v[8:9], v[26:27], v[70:71] op_sel_hi:[0,1,1]
	v_add_f32_dpp v68, v68, v68 quad_perm:[1,0,3,2] row_mask:0xf bank_mask:0xf bound_ctrl:1
	v_mul_f32_e32 v76, 0xbfb8aa3b, v71
	v_exp_f32_e32 v77, v76
	s_nop 0
	v_add_f32_dpp v68, v68, v68 row_bcast:15 row_mask:0xa bank_mask:0xf
	s_nop 0
	s_nop 1
	s_nop 0
	v_add_f32_dpp v68, v68, v68 row_bcast:31 row_mask:0xc bank_mask:0xf
	v_mul_f32_e32 v69, s47, v101
	v_readlane_b32 s23, v68, 63
	v_exp_f32_e32 v78, v69
	s_nop 0
	v_add_f32_e32 v68, s23, v102
	v_rsq_f32_e32 v68, v68
	s_ashr_i32 s23, s22, 31
	s_lshl_b64 s[22:23], s[22:23], 11
	v_pk_mul_f32 v[62:63], v[62:63], v[68:69] op_sel_hi:[1,0]
	v_cvt_pk_bf16_f32 v68, v64, v65
	v_add_u32_e32 v69, 0x200, v92
	v_pk_mul_f32 v[64:65], v[64:65], v[78:79] op_sel_hi:[1,0]
	ds_write2_b32 v69, v75, v68 offset0:76 offset1:144
	v_cvt_pk_bf16_f32 v68, v62, v63
	v_add_u32_e32 v69, 0x4600, v92
	v_pk_mul_f32 v[64:65], v[64:65], s[8:9] op_sel_hi:[1,0]
	ds_write2_b32 v69, v79, v68 offset0:76 offset1:144
	v_cvt_pk_bf16_f32 v68, v64, v65
	v_lshl_add_u64 v[64:65], v[36:37], 0, s[22:23]
	global_store_dword v[64:65], v68, off
	v_mov_b32_e32 v64, v67
	v_mov_b32_e32 v65, v63
	v_mul_f32_e32 v63, 0xbfb8aa3b, v72
	v_mul_f32_e32 v67, 0xbfb8aa3b, v73
	v_exp_f32_e32 v63, v63
	v_exp_f32_e32 v75, v67
	v_mov_b32_e32 v67, v62
	v_mov_b32_e32 v69, s47
	v_add_f32_e32 v62, 1.0, v63
	v_add_f32_e32 v63, 1.0, v75
	v_mul_f32_e32 v75, 0xbfb8aa3b, v70
	v_exp_f32_e32 v75, v75
	v_sub_f32_e32 v69, s44, v69
	v_mul_f32_e32 v69, 0x3fb8aa3b, v69
	v_rcp_f32_e32 v62, v62
	v_add_f32_e32 v75, 1.0, v75
	v_rcp_f32_e32 v76, v75
	v_add_f32_e32 v75, 1.0, v77
	v_rcp_f32_e32 v63, v63
	v_rcp_f32_e32 v77, v75
	v_exp_f32_e32 v81, v69
	v_mov_b32_e32 v75, v78
	v_pk_mul_f32 v[62:63], v[72:73], v[62:63]
	v_pk_mul_f32 v[70:71], v[70:71], v[76:77]
	v_pk_mul_f32 v[68:69], v[64:65], v[80:81]
	v_pk_mul_f32 v[80:81], v[66:67], v[80:81]
	v_pk_mul_f32 v[62:63], v[62:63], s[4:5]
	v_pk_mul_f32 v[70:71], v[70:71], s[4:5]
	v_pk_mul_f32 v[64:65], v[64:65], s[4:5]
	v_pk_mul_f32 v[66:67], v[66:67], s[4:5]
	s_lshl_b32 s4, s19, 2
	v_pk_mul_f32 v[66:67], v[66:67], v[74:75]
	s_and_b32 s4, s4, 48
	s_add_i32 s4, s18, s4
	v_cvt_pk_bf16_f32 v66, v66, v67
	s_add_i32 s4, s4, s17
	ds_write_b32 v58, v66 offset:53256
	v_cvt_pk_bf16_f32 v66, v70, v71
	v_pk_mul_f32 v[64:65], v[64:65], v[74:75]
	ds_write_b32 v58, v66 offset:34824
	v_cvt_pk_bf16_f32 v66, v80, v81
	v_add_u32_e32 v67, s4, v88
	v_cvt_pk_bf16_f32 v62, v62, v63
	ds_write_b32 v67, v66
	v_cvt_pk_bf16_f32 v64, v64, v65
	ds_write_b32 v58, v62 offset:34968
	v_cvt_pk_bf16_f32 v62, v68, v69
	v_add_u32_e32 v63, s4, v89
	ds_write_b32 v58, v64 offset:53400
	ds_write_b32 v63, v62
	v_pk_mul_f32 v[62:63], v[22:23], v[44:45]
	v_pk_mul_f32 v[22:23], v[22:23], v[46:47]
	v_pk_fma_f32 v[54:55], v[24:25], v[54:55], v[62:63]
	v_pk_fma_f32 v[22:23], v[24:25], v[44:45], v[22:23]
	v_pk_fma_f32 v[54:55], v[18:19], v[46:47], v[54:55]
	v_pk_fma_f32 v[18:19], v[18:19], v[48:49], v[22:23]
	v_pk_fma_f32 v[54:55], v[20:21], v[48:49], v[54:55]
	v_pk_fma_f32 v[18:19], v[20:21], v[50:51], v[18:19]
	v_mul_f32_e32 v62, 0xbfb8aa3b, v54
	v_mul_f32_e32 v63, 0xbfb8aa3b, v55
	v_exp_f32_e32 v62, v62
	v_exp_f32_e32 v63, v63
	v_mul_f32_e32 v20, 0xbfb8aa3b, v18
	v_mul_f32_e32 v21, 0xbfb8aa3b, v19
	v_add_f32_e32 v62, 1.0, v62
	v_add_f32_e32 v63, 1.0, v63
	v_rcp_f32_e32 v62, v62
	v_rcp_f32_e32 v63, v63
	v_exp_f32_e32 v20, v20
	v_exp_f32_e32 v21, v21
	v_mov_b32_e32 v67, v59
	v_pk_mul_f32 v[54:55], v[54:55], v[62:63]
	v_add_f32_e32 v20, 1.0, v20
	v_pk_mul_f32 v[62:63], v[54:55], v[54:55]
	v_add_f32_e32 v21, 1.0, v21
	v_add_f32_e32 v62, v62, v63
	v_mov_b32_e32 v63, v59
	v_rcp_f32_e32 v20, v20
	v_add_f32_dpp v62, v62, v62 row_ror:8 row_mask:0xf bank_mask:0xf bound_ctrl:1
	v_rcp_f32_e32 v21, v21
	s_or_b32 s18, s16, 6
	v_add_f32_dpp v62, v62, v62 row_ror:4 row_mask:0xf bank_mask:0xf bound_ctrl:1
	v_readlane_b32 s5, v153, s18
	v_pk_mul_f32 v[18:19], v[18:19], v[20:21]
	v_add_f32_dpp v62, v62, v62 quad_perm:[2,3,0,1] row_mask:0xf bank_mask:0xf bound_ctrl:1
	v_pk_mul_f32 v[20:21], v[18:19], v[18:19]
	v_mul_f32_e32 v64, s5, v101
	v_add_f32_dpp v62, v62, v62 quad_perm:[1,0,3,2] row_mask:0xf bank_mask:0xf bound_ctrl:1
	v_mov_b32_e32 v65, s5
	v_add_f32_e32 v20, v20, v21
	v_mov_b32_dpp v63, v62 row_bcast:15 row_mask:0xa bank_mask:0xf
	v_add_f32_e32 v66, v62, v63
	v_pk_mul_f32 v[62:63], v[14:15], v[34:35]
	v_pk_mul_f32 v[14:15], v[14:15], v[38:39]
	v_pk_fma_f32 v[52:53], v[10:11], v[52:53], v[62:63]
	v_pk_fma_f32 v[10:11], v[10:11], v[34:35], v[14:15]
	v_pk_fma_f32 v[52:53], v[12:13], v[38:39], v[52:53]
	v_pk_fma_f32 v[10:11], v[12:13], v[40:41], v[10:11]
	v_pk_fma_f32 v[52:53], v[16:17], v[40:41], v[52:53]
	v_pk_fma_f32 v[10:11], v[16:17], v[42:43], v[10:11]
	v_mul_f32_e32 v62, 0xbfb8aa3b, v52
	v_mul_f32_e32 v63, 0xbfb8aa3b, v53
	v_exp_f32_e32 v62, v62
	v_exp_f32_e32 v63, v63
	v_mul_f32_e32 v12, 0xbfb8aa3b, v10
	v_mul_f32_e32 v13, 0xbfb8aa3b, v11
	v_add_f32_e32 v62, 1.0, v62
	v_add_f32_e32 v63, 1.0, v63
	v_rcp_f32_e32 v62, v62
	v_rcp_f32_e32 v63, v63
	v_exp_f32_e32 v12, v12
	v_exp_f32_e32 v13, v13
	v_mov_b32_dpp v67, v66 row_bcast:31 row_mask:0xc bank_mask:0xf
	v_pk_mul_f32 v[52:53], v[52:53], v[62:63]
	v_add_f32_e32 v12, 1.0, v12
	v_pk_mul_f32 v[62:63], v[52:53], v[52:53]
	v_add_f32_e32 v13, 1.0, v13
	v_add_f32_e32 v62, v62, v63
	v_rcp_f32_e32 v12, v12
	v_rcp_f32_e32 v13, v13
	v_add_f32_dpp v62, v62, v62 row_ror:8 row_mask:0xf bank_mask:0xf bound_ctrl:1
	s_nop 0
	v_add_f32_e32 v66, v66, v67
	v_add_f32_dpp v62, v62, v62 row_ror:4 row_mask:0xf bank_mask:0xf bound_ctrl:1
	v_pk_mul_f32 v[10:11], v[10:11], v[12:13]
	v_readlane_b32 s5, v66, 63
	v_add_f32_dpp v62, v62, v62 quad_perm:[2,3,0,1] row_mask:0xf bank_mask:0xf bound_ctrl:1
	v_pk_mul_f32 v[12:13], v[10:11], v[10:11]
	v_add_f32_e32 v66, s5, v102
	v_add_f32_dpp v62, v62, v62 quad_perm:[1,0,3,2] row_mask:0xf bank_mask:0xf bound_ctrl:1
	v_add_f32_dpp v20, v20, v20 row_ror:8 row_mask:0xf bank_mask:0xf bound_ctrl:1
	v_add_f32_e32 v12, v12, v13
	s_nop 0
	v_add_f32_dpp v62, v62, v62 row_bcast:15 row_mask:0xa bank_mask:0xf
	s_nop 0
	v_rsq_f32_e32 v66, v66
	v_add_f32_dpp v20, v20, v20 row_ror:4 row_mask:0xf bank_mask:0xf bound_ctrl:1
	s_nop 0
	v_add_f32_dpp v62, v62, v62 row_bcast:31 row_mask:0xc bank_mask:0xf
	v_add_f32_dpp v12, v12, v12 row_ror:8 row_mask:0xf bank_mask:0xf bound_ctrl:1
	v_readlane_b32 s5, v62, 63
	v_exp_f32_e32 v64, v64
	v_add_f32_dpp v20, v20, v20 quad_perm:[2,3,0,1] row_mask:0xf bank_mask:0xf bound_ctrl:1
	v_add_f32_e32 v62, s5, v102
	v_rsq_f32_e32 v62, v62
	v_add_f32_dpp v12, v12, v12 row_ror:4 row_mask:0xf bank_mask:0xf bound_ctrl:1
	v_add_f32_dpp v20, v20, v20 quad_perm:[1,0,3,2] row_mask:0xf bank_mask:0xf bound_ctrl:1
	s_nop 0
	v_add_f32_dpp v12, v12, v12 quad_perm:[2,3,0,1] row_mask:0xf bank_mask:0xf bound_ctrl:1
	v_sub_f32_e32 v65, s44, v65
	s_nop 0
	v_add_f32_dpp v12, v12, v12 quad_perm:[1,0,3,2] row_mask:0xf bank_mask:0xf bound_ctrl:1
	s_nop 0
	v_mul_f32_e32 v63, 0x3fb8aa3b, v65
	v_pk_mul_f32 v[54:55], v[54:55], v[66:67] op_sel_hi:[1,0]
	s_add_i32 s22, s18, s15
	v_add_f32_dpp v20, v20, v20 row_bcast:15 row_mask:0xa bank_mask:0xf
	v_mov_b32_e32 v21, v59
	s_nop 0
	v_pk_mul_f32 v[52:53], v[52:53], v[62:63] op_sel_hi:[1,0]
	v_cvt_pk_bf16_f32 v62, v54, v55
	v_pk_mul_f32 v[54:55], v[54:55], v[64:65] op_sel_hi:[1,0]
	s_ashr_i32 s23, s22, 31
	v_mov_b32_dpp v21, v20 row_bcast:31 row_mask:0xc bank_mask:0xf
	v_add_f32_dpp v12, v12, v12 row_bcast:15 row_mask:0xa bank_mask:0xf
	s_nop 0
	v_pk_mul_f32 v[54:55], v[54:55], s[8:9] op_sel_hi:[1,0]
	s_lshl_b64 s[22:23], s[22:23], 11
	v_add_f32_e32 v14, v20, v21
	s_nop 0
	v_cvt_pk_bf16_f32 v65, v54, v55
	v_lshl_add_u64 v[54:55], v[36:37], 0, s[22:23]
	v_readlane_b32 s22, v14, 63
	v_add_f32_dpp v12, v12, v12 row_bcast:31 row_mask:0xc bank_mask:0xf
	s_or_b32 s16, s16, 7
	v_add_f32_e32 v14, s22, v102
	v_readlane_b32 s22, v12, 63
	v_rsq_f32_e32 v14, v14
	v_readlane_b32 s19, v153, s16
	v_add_f32_e32 v12, s22, v102
	v_rsq_f32_e32 v12, v12
	v_mul_f32_e32 v13, s19, v101
	v_exp_f32_e32 v16, v13
	v_pk_mul_f32 v[14:15], v[18:19], v[14:15] op_sel_hi:[1,0]
	v_pk_mul_f32 v[10:11], v[10:11], v[12:13] op_sel_hi:[1,0]
	v_cvt_pk_bf16_f32 v12, v14, v15
	v_add_u32_e32 v13, 0x400, v92
	v_exp_f32_e32 v68, v63
	v_cvt_pk_bf16_f32 v63, v52, v53
	ds_write2_b32 v13, v62, v12 offset0:84 offset1:152
	v_cvt_pk_bf16_f32 v12, v10, v11
	v_add_u32_e32 v13, 0x4800, v92
	s_add_i32 s22, s16, s15
	v_pk_mul_f32 v[18:19], v[6:7], v[30:31] op_sel:[1,0]
	v_pk_mul_f32 v[6:7], v[6:7], v[26:27] op_sel_hi:[0,1]
	ds_write2_b32 v13, v63, v12 offset0:84 offset1:152
	v_pk_mul_f32 v[12:13], v[14:15], v[16:17] op_sel_hi:[1,0]
	s_ashr_i32 s23, s22, 31
	v_pk_fma_f32 v[18:19], v[2:3], v[60:61], v[18:19] op_sel:[1,0,0]
	v_pk_mov_b32 v[20:21], v[30:31], v[32:33] op_sel:[1,0]
	v_pk_fma_f32 v[2:3], v[2:3], v[56:57], v[6:7] op_sel_hi:[0,1,1]
	v_pk_mov_b32 v[6:7], v[26:27], v[28:29] op_sel:[1,0]
	v_pk_mul_f32 v[12:13], v[12:13], s[8:9] op_sel_hi:[1,0]
	s_lshl_b64 s[22:23], s[22:23], 11
	v_pk_fma_f32 v[18:19], v[4:5], v[20:21], v[18:19] op_sel:[1,0,0]
	v_pk_fma_f32 v[2:3], v[4:5], v[6:7], v[2:3] op_sel_hi:[0,1,1]
	v_cvt_pk_bf16_f32 v14, v12, v13
	v_lshl_add_u64 v[12:13], v[36:37], 0, s[22:23]
	v_pk_fma_f32 v[18:19], v[8:9], v[32:33], v[18:19] op_sel:[1,0,0]
	v_pk_fma_f32 v[2:3], v[8:9], v[28:29], v[2:3] op_sel_hi:[0,1,1]
	global_store_dword v[12:13], v14, off
	v_mov_b32_e32 v13, v11
	v_mul_f32_e32 v11, 0xbfb8aa3b, v18
	v_mul_f32_e32 v17, 0xbfb8aa3b, v19
	v_mul_f32_e32 v4, 0xbfb8aa3b, v2
	v_mul_f32_e32 v5, 0xbfb8aa3b, v3
	v_exp_f32_e32 v11, v11
	v_exp_f32_e32 v17, v17
	v_exp_f32_e32 v4, v4
	v_exp_f32_e32 v5, v5
	v_mov_b32_e32 v12, v53
	v_mov_b32_e32 v53, v10
	v_add_f32_e32 v10, 1.0, v11
	v_add_f32_e32 v11, 1.0, v17
	v_add_f32_e32 v4, 1.0, v4
	v_add_f32_e32 v5, 1.0, v5
	v_rcp_f32_e32 v10, v10
	v_rcp_f32_e32 v11, v11
	v_rcp_f32_e32 v4, v4
	v_rcp_f32_e32 v5, v5
	v_mov_b32_e32 v15, s19
	v_sub_f32_e32 v15, s44, v15
	v_readlane_b32 s4, v154, s18
	v_readlane_b32 s5, v154, s16
	v_mul_f32_e32 v15, 0x3fb8aa3b, v15
	v_pk_mul_f32 v[8:9], v[18:19], v[10:11]
	v_pk_mul_f32 v[2:3], v[2:3], v[4:5]
	v_exp_f32_e32 v69, v15
	v_pk_mul_f32 v[8:9], v[8:9], s[4:5]
	v_pk_mul_f32 v[2:3], v[2:3], s[4:5]
	v_pk_mul_f32 v[4:5], v[12:13], s[4:5]
	v_pk_mul_f32 v[10:11], v[52:53], s[4:5]
	s_and_b32 s4, s18, 0x1fffffe2
	s_lshl_b32 s4, s4, 1
	s_lshl_b32 s5, s18, 2
	s_add_i32 s4, s38, s4
	s_and_b32 s5, s5, 48
	global_store_dword v[54:55], v65, off
	v_mov_b32_e32 v65, v16
	s_add_i32 s4, s4, s5
	v_pk_mul_f32 v[6:7], v[52:53], v[68:69]
	v_pk_mul_f32 v[10:11], v[10:11], v[64:65]
	s_add_i32 s4, s4, s17
	v_cvt_pk_bf16_f32 v2, v2, v3
	v_pk_mul_f32 v[4:5], v[4:5], v[64:65]
	v_cvt_pk_bf16_f32 v10, v10, v11
	ds_write_b32 v58, v2 offset:34828
	v_cvt_pk_bf16_f32 v2, v6, v7
	v_add_u32_e32 v3, s4, v88
	ds_write_b32 v58, v10 offset:53260
	ds_write_b32 v3, v2
	v_cvt_pk_bf16_f32 v2, v4, v5
	v_pk_mul_f32 v[14:15], v[12:13], v[68:69]
	ds_write_b32 v58, v2 offset:53404
	v_cvt_pk_bf16_f32 v2, v8, v9
	ds_write_b32 v58, v2 offset:34972
	v_cvt_pk_bf16_f32 v2, v14, v15
	v_add_u32_e32 v3, s4, v89
	s_bfe_u32 s19, s45, 0x20006
	v_and_b32_e32 v60, 48, v106
	ds_write_b32 v3, v2
	v_lshl_or_b32 v58, s19, 4, v144
	v_add_u32_e32 v2, 0, v60
	s_waitcnt lgkmcnt(0)
	s_barrier
	v_mad_u32_u24 v3, v58, s37, v2
	ds_read_b128 v[6:9], v3
	ds_read_b128 v[10:13], v3 offset:64
	ds_read_b128 v[14:17], v3 offset:128
	ds_read_b128 v[18:21], v3 offset:192
	s_lshr_b32 s18, s45, 8
	s_lshl_b32 s22, s18, 1
	s_cmp_ge_u32 s19, s22
	s_cselect_b64 s[4:5], -1, 0
	s_cmp_lt_u32 s19, s22
	v_lshl_or_b32 v3, s18, 5, v144
	s_cbranch_scc1 .LBB0_543
	v_mad_u64_u32 v[4:5], s[16:17], v3, s37, v[2:3]
	ds_read_b128 v[22:25], v4 offset:17408
	ds_read_b128 v[26:29], v4 offset:17472
	ds_read_b128 v[30:33], v4 offset:17536
	ds_read_b128 v[34:37], v4 offset:17600

.LBB0_1161:
	s_ashr_i32 s4, s14, 31
	s_lshr_b32 s4, s4, 25
	s_add_i32 s4, s14, s4
	s_and_b32 s4, s4, 0xffffff80
	s_sub_i32 s14, s14, s4
	s_ashr_i32 s4, s14, 4
	s_ashr_i32 s5, s4, 31
	s_lshl_b64 s[12:13], s[4:5], 11
	s_lshl_b32 s4, s14, 7
	v_readfirstlane_b32 s16, v0
	s_and_b32 s4, s4, 0x780
	s_or_b32 s12, s12, s4
	s_lshr_b32 s4, s16, 2
	s_and_b32 s25, s4, 0x3ffffff0
	s_add_u32 s14, s12, s25
	s_addc_u32 s15, s13, 0
	v_mov_b32_e32 v102, v0
	s_lshl_b64 s[14:15], s[14:15], 11
	s_add_u32 s14, s28, s14
	v_and_b32_e32 v6, 63, v102
	s_addc_u32 s15, s29, s15
	s_waitcnt vmcnt(24)
	v_lshlrev_b32_e32 v96, 4, v6
	v_lshl_add_u64 v[2:3], s[14:15], 0, v[96:97]
	s_movk_i32 s5, 0x1000
	v_add_co_u32_e32 v4, vcc, s5, v2
	s_movk_i32 s5, 0x2000
	s_nop 0
	v_addc_co_u32_e32 v5, vcc, 0, v3, vcc
	s_barrier
	global_load_dwordx4 v[58:61], v96, s[14:15] offset:1024 nt
	global_load_dwordx4 v[62:65], v96, s[14:15] offset:3072 nt
	global_load_dwordx4 v[88:91], v[4:5], off offset:1024 nt
	global_load_dwordx4 v[92:95], v[4:5], off offset:3072 nt
	v_add_co_u32_e32 v4, vcc, s5, v2
	s_movk_i32 s5, 0x3000
	s_nop 0
	v_addc_co_u32_e32 v5, vcc, 0, v3, vcc
	global_load_dwordx4 v[50:53], v[4:5], off offset:1024 nt
	global_load_dwordx4 v[54:57], v[4:5], off offset:3072 nt
	v_add_co_u32_e32 v4, vcc, s5, v2
	s_movk_i32 s5, 0x4000
	s_nop 0
	v_addc_co_u32_e32 v5, vcc, 0, v3, vcc
	global_load_dwordx4 v[42:45], v[4:5], off offset:1024 nt
	global_load_dwordx4 v[46:49], v[4:5], off offset:3072 nt
	v_add_co_u32_e32 v4, vcc, s5, v2
	s_movk_i32 s5, 0x5000
	s_nop 0
	v_addc_co_u32_e32 v5, vcc, 0, v3, vcc
	global_load_dwordx4 v[34:37], v[4:5], off offset:1024 nt
	global_load_dwordx4 v[38:41], v[4:5], off offset:3072 nt
	v_add_co_u32_e32 v4, vcc, s5, v2
	s_movk_i32 s5, 0x6000
	s_nop 0
	v_addc_co_u32_e32 v5, vcc, 0, v3, vcc
	global_load_dwordx4 v[26:29], v[4:5], off offset:1024 nt
	global_load_dwordx4 v[30:33], v[4:5], off offset:3072 nt
	v_add_co_u32_e32 v4, vcc, s5, v2
	s_movk_i32 s5, 0x7000
	s_nop 0
	v_addc_co_u32_e32 v5, vcc, 0, v3, vcc
	v_add_co_u32_e32 v2, vcc, s5, v2
	v_readlane_b32 s36, v245, 26
	s_nop 0
	v_addc_co_u32_e32 v3, vcc, 0, v3, vcc
	v_lshlrev_b32_e32 v6, 5, v6
	v_readlane_b32 s46, v245, 36
	v_readlane_b32 s47, v245, 37
	global_load_dwordx4 v[18:21], v[4:5], off offset:1024 nt
	global_load_dwordx4 v[22:25], v[4:5], off offset:3072 nt
	global_load_dwordx4 v[10:13], v[2:3], off offset:1024 nt
	global_load_dwordx4 v[14:17], v[2:3], off offset:3072 nt
	s_nop 0
	global_load_dwordx4 v[2:5], v6, s[46:47] offset:16
	s_nop 0
	global_load_dwordx4 v[6:9], v6, s[46:47]
	v_and_b32_e32 v103, 15, v102
	v_lshlrev_b32_e32 v106, 3, v103
	v_bfe_u32 v104, v102, 4, 2
	s_mov_b32 s5, 0x8800
	v_mad_u32_u24 v105, v104, s5, 0
	v_mul_u32_u24_e32 v107, 0x880, v103
	v_readlane_b32 s50, v245, 40
	v_readlane_b32 s51, v245, 41
	s_cmpk_gt_u32 s16, 0x7f
	v_readlane_b32 s37, v245, 27
	v_readlane_b32 s38, v245, 28
	v_readlane_b32 s39, v245, 29
	v_readlane_b32 s40, v245, 30
	v_readlane_b32 s41, v245, 31
	v_readlane_b32 s42, v245, 32
	v_readlane_b32 s43, v245, 33
	v_readlane_b32 s44, v245, 34
	v_readlane_b32 s45, v245, 35
	v_readlane_b32 s48, v245, 38
	v_readlane_b32 s49, v245, 39
	s_waitcnt vmcnt(17)
	v_and_b32_e32 v76, 0xffff0000, v58
	s_waitcnt vmcnt(16)
	v_and_b32_e32 v77, 0xffff0000, v62
	v_lshlrev_b32_e32 v67, 16, v62
	v_lshlrev_b32_e32 v66, 16, v58
	v_pk_mul_f32 v[78:79], v[76:77], v[76:77]
	v_lshlrev_b32_e32 v81, 16, v63
	v_pk_fma_f32 v[78:79], v[66:67], v[66:67], v[78:79]
	v_lshlrev_b32_e32 v80, 16, v59
	v_and_b32_e32 v68, 0xffff0000, v61
	v_lshlrev_b32_e32 v69, 16, v61
	v_bitop3_b32 v61, s4, v106, v1 bitop3:0x6c
	v_pk_fma_f32 v[78:79], v[80:81], v[80:81], v[78:79]
	v_and_b32_e32 v63, 0xffff0000, v63
	v_and_b32_e32 v62, 0xffff0000, v59
	v_lshlrev_b32_e32 v61, 1, v61
	v_pk_fma_f32 v[58:59], v[62:63], v[62:63], v[78:79]
	v_lshlrev_b32_e32 v85, 16, v64
	v_lshlrev_b32_e32 v84, 16, v60
	v_add3_u32 v108, v105, v61, v107
	v_pk_fma_f32 v[58:59], v[84:85], v[84:85], v[58:59]
	v_and_b32_e32 v61, 0xffff0000, v64
	v_and_b32_e32 v60, 0xffff0000, v60
	v_pk_mul_f32 v[70:71], v[68:69], v[68:69]
	v_pk_fma_f32 v[58:59], v[60:61], v[60:61], v[58:59]
	v_and_b32_e32 v72, 0xffff0000, v65
	v_lshlrev_b32_e32 v73, 16, v65
	v_pk_mul_f32 v[74:75], v[72:73], v[72:73]
	s_waitcnt vmcnt(14)
	v_lshlrev_b32_e32 v111, 16, v93
	v_lshlrev_b32_e32 v110, 16, v89
	v_and_b32_e32 v93, 0xffff0000, v93
	s_waitcnt vmcnt(1)
	v_mov_b32_e32 v98, v5
	s_waitcnt vmcnt(0)
	v_mov_b32_e32 v96, v9
	v_add_f32_e32 v9, v71, v58
	v_add_f32_e32 v9, v70, v9
	v_add_f32_e32 v58, v75, v59
	v_mov_b32_e32 v59, v97
	v_add_f32_dpp v9, v9, v9 row_ror:8 row_mask:0xf bank_mask:0xf bound_ctrl:1
	v_add_f32_e32 v58, v74, v58
	s_nop 0
	v_add_f32_dpp v9, v9, v9 row_ror:4 row_mask:0xf bank_mask:0xf bound_ctrl:1
	v_add_f32_dpp v58, v58, v58 row_ror:8 row_mask:0xf bank_mask:0xf bound_ctrl:1
	s_nop 0
	v_add_f32_dpp v9, v9, v9 quad_perm:[2,3,0,1] row_mask:0xf bank_mask:0xf bound_ctrl:1
	v_add_f32_dpp v58, v58, v58 row_ror:4 row_mask:0xf bank_mask:0xf bound_ctrl:1
	s_nop 0
	v_add_f32_dpp v9, v9, v9 quad_perm:[1,0,3,2] row_mask:0xf bank_mask:0xf bound_ctrl:1
	v_add_f32_dpp v58, v58, v58 quad_perm:[2,3,0,1] row_mask:0xf bank_mask:0xf bound_ctrl:1
	s_nop 0
	s_nop 0
	v_add_f32_dpp v9, v9, v9 row_bcast:15 row_mask:0xa bank_mask:0xf
	v_mov_b32_e32 v59, v97
	v_add_f32_dpp v58, v58, v58 quad_perm:[1,0,3,2] row_mask:0xf bank_mask:0xf bound_ctrl:1
	s_nop 0
	s_nop 0
	v_add_f32_dpp v9, v9, v9 row_bcast:31 row_mask:0xc bank_mask:0xf
	s_nop 0
	v_readlane_b32 s4, v9, 63
	s_nop 1
	v_fma_f32 v9, s4, v100, v99
	v_cmp_gt_f32_e32 vcc, s2, v9
	v_mul_f32_e32 v59, 0x4f800000, v9
	s_nop 0
	v_cndmask_b32_e32 v9, v9, v59, vcc
	v_sqrt_f32_e32 v59, v9
	s_nop 0
	v_add_u32_e32 v64, -1, v59
	v_fma_f32 v65, -v64, v59, v9
	v_cmp_ge_f32_e64 s[4:5], 0, v65
	v_add_u32_e32 v65, 1, v59
	s_nop 0
	v_cndmask_b32_e64 v64, v59, v64, s[4:5]
	v_fma_f32 v59, -v65, v59, v9
	v_cmp_lt_f32_e64 s[4:5], 0, v59
	s_nop 1
	v_cndmask_b32_e64 v59, v64, v65, s[4:5]
	v_mul_f32_e32 v64, 0x37800000, v59
	v_cndmask_b32_e32 v59, v59, v64, vcc
	v_cmp_class_f32_e32 vcc, v9, v101
	s_nop 1
	v_cndmask_b32_e32 v9, v59, v9, vcc
	v_mov_b32_e32 v59, v97
	s_nop 1
	s_nop 0
	s_nop 1
	v_add_f32_dpp v58, v58, v58 row_bcast:15 row_mask:0xa bank_mask:0xf
	v_mov_b32_e32 v59, v97
	s_nop 1
	s_nop 0
	v_add_f32_dpp v58, v58, v58 row_bcast:31 row_mask:0xc bank_mask:0xf
	s_nop 0
	v_readlane_b32 s4, v58, 63
	s_nop 1
	v_fma_f32 v58, s4, v100, v99
	v_cmp_gt_f32_e32 vcc, s2, v58
	v_mul_f32_e32 v59, 0x4f800000, v58
	s_nop 0
	v_cndmask_b32_e32 v58, v58, v59, vcc
	v_sqrt_f32_e32 v59, v58
	s_nop 0
	v_add_u32_e32 v64, -1, v59
	v_fma_f32 v65, -v64, v59, v58
	v_cmp_ge_f32_e64 s[4:5], 0, v65
	v_add_u32_e32 v65, 1, v59
	s_nop 0
	v_cndmask_b32_e64 v64, v59, v64, s[4:5]
	v_fma_f32 v59, -v65, v59, v58
	v_cmp_lt_f32_e64 s[4:5], 0, v59
	s_nop 1
	v_cndmask_b32_e64 v59, v64, v65, s[4:5]
	v_mul_f32_e32 v64, 0x37800000, v59
	v_cndmask_b32_e32 v59, v59, v64, vcc
	v_cmp_class_f32_e32 vcc, v58, v101
	s_nop 1
	v_cndmask_b32_e32 v58, v59, v58, vcc
	v_div_scale_f32 v59, s[4:5], v58, v58, 1.0
	v_rcp_f32_e32 v64, v59
	s_nop 0
	v_fma_f32 v65, -v59, v64, 1.0
	v_fmac_f32_e32 v64, v65, v64
	v_div_scale_f32 v65, vcc, 1.0, v58, 1.0
	v_mul_f32_e32 v70, v65, v64
	v_fma_f32 v71, -v59, v70, v65
	v_fmac_f32_e32 v70, v71, v64
	v_fma_f32 v59, -v59, v70, v65
	v_div_fmas_f32 v59, v59, v64, v70
	v_div_fixup_f32 v59, v59, v58, 1.0
	v_div_scale_f32 v58, s[4:5], v9, v9, 1.0
	v_rcp_f32_e32 v64, v58
	s_nop 0
	v_fma_f32 v65, -v58, v64, 1.0
	v_fmac_f32_e32 v64, v65, v64
	v_div_scale_f32 v65, vcc, 1.0, v9, 1.0
	v_mul_f32_e32 v70, v65, v64
	v_fma_f32 v71, -v58, v70, v65
	v_fmac_f32_e32 v70, v71, v64
	v_fma_f32 v58, -v58, v70, v65
	v_div_fmas_f32 v58, v58, v64, v70
	v_div_fixup_f32 v58, v58, v9, 1.0
	v_pk_mul_f32 v[64:65], v[58:59], v[66:67]
	v_pk_mul_f32 v[62:63], v[58:59], v[62:63]
	v_pk_mul_f32 v[64:65], v[6:7], v[64:65] op_sel_hi:[0,1]
	v_cvt_pk_bf16_f32 v86, v64, v65
	v_pk_mul_f32 v[64:65], v[58:59], v[76:77]
	v_pk_mul_f32 v[62:63], v[96:97], v[62:63] op_sel_hi:[0,1]
	v_pk_mul_f32 v[64:65], v[6:7], v[64:65] op_sel:[1,0]
	v_pk_mul_f32 v[60:61], v[58:59], v[60:61]
	v_cvt_pk_bf16_f32 v82, v64, v65
	v_pk_mul_f32 v[64:65], v[58:59], v[80:81]
	v_and_b32_e32 v81, 0xffff0000, v92
	v_and_b32_e32 v80, 0xffff0000, v88
	v_cvt_pk_bf16_f32 v74, v62, v63
	v_pk_mul_f32 v[62:63], v[58:59], v[84:85]
	v_pk_mul_f32 v[60:61], v[2:3], v[60:61] op_sel:[1,0]
	v_lshlrev_b32_e32 v77, 16, v92
	v_lshlrev_b32_e32 v76, 16, v88
	v_pk_mul_f32 v[84:85], v[80:81], v[80:81]
	v_cvt_pk_bf16_f32 v66, v60, v61
	v_mov_b32_e32 v60, v69
	v_mov_b32_e32 v61, v73
	v_pk_fma_f32 v[84:85], v[76:77], v[76:77], v[84:85]
	v_pk_mul_f32 v[60:61], v[58:59], v[60:61]
	v_pk_fma_f32 v[84:85], v[110:111], v[110:111], v[84:85]
	v_and_b32_e32 v92, 0xffff0000, v89
	v_pk_mul_f32 v[62:63], v[2:3], v[62:63] op_sel_hi:[0,1]
	v_pk_mul_f32 v[60:61], v[4:5], v[60:61] op_sel_hi:[0,1]
	v_pk_fma_f32 v[84:85], v[92:93], v[92:93], v[84:85]
	v_lshlrev_b32_e32 v89, 16, v94
	v_lshlrev_b32_e32 v88, 16, v90
	v_cvt_pk_bf16_f32 v70, v62, v63
	v_cvt_pk_bf16_f32 v62, v60, v61
	v_mov_b32_e32 v69, v72
	v_and_b32_e32 v60, 0xffff0000, v91
	v_lshlrev_b32_e32 v61, 16, v91
	v_pk_fma_f32 v[84:85], v[88:89], v[88:89], v[84:85]
	v_and_b32_e32 v91, 0xffff0000, v94
	v_and_b32_e32 v90, 0xffff0000, v90
	v_pk_mul_f32 v[58:59], v[58:59], v[68:69]
	v_pk_mul_f32 v[68:69], v[60:61], v[60:61]
	v_pk_fma_f32 v[84:85], v[90:91], v[90:91], v[84:85]
	v_pk_mul_f32 v[58:59], v[98:99], v[58:59] op_sel_hi:[0,1]
	v_add_f32_e32 v5, v69, v84
	v_add_f32_e32 v5, v68, v5
	v_cvt_pk_bf16_f32 v58, v58, v59
	v_mov_b32_e32 v59, v97
	v_add_f32_dpp v5, v5, v5 row_ror:8 row_mask:0xf bank_mask:0xf bound_ctrl:1
	v_pk_mul_f32 v[64:65], v[8:9], v[64:65] op_sel_hi:[0,1]
	v_cvt_pk_bf16_f32 v78, v64, v65
	v_add_f32_dpp v5, v5, v5 row_ror:4 row_mask:0xf bank_mask:0xf bound_ctrl:1
	v_and_b32_e32 v64, 0xffff0000, v95
	v_lshlrev_b32_e32 v65, 16, v95
	v_add_f32_dpp v5, v5, v5 quad_perm:[2,3,0,1] row_mask:0xf bank_mask:0xf bound_ctrl:1
	v_pk_mul_f32 v[72:73], v[64:65], v[64:65]
	v_lshlrev_b32_e32 v95, 16, v56
	v_add_f32_dpp v5, v5, v5 quad_perm:[1,0,3,2] row_mask:0xf bank_mask:0xf bound_ctrl:1
	v_add_f32_e32 v9, v73, v85
	v_add_f32_e32 v9, v72, v9
	s_nop 0
	v_add_f32_dpp v5, v5, v5 row_bcast:15 row_mask:0xa bank_mask:0xf
	v_mov_b32_e32 v59, v97
	v_add_f32_dpp v9, v9, v9 row_ror:8 row_mask:0xf bank_mask:0xf bound_ctrl:1
	v_lshlrev_b32_e32 v94, 16, v52
	s_nop 0
	v_add_f32_dpp v5, v5, v5 row_bcast:31 row_mask:0xc bank_mask:0xf
	v_add_f32_dpp v9, v9, v9 row_ror:4 row_mask:0xf bank_mask:0xf bound_ctrl:1
	v_readlane_b32 s4, v5, 63
	v_and_b32_e32 v52, 0xffff0000, v52
	v_add_f32_dpp v9, v9, v9 quad_perm:[2,3,0,1] row_mask:0xf bank_mask:0xf bound_ctrl:1
	v_fma_f32 v5, s4, v100, v99
	v_cmp_gt_f32_e32 vcc, s2, v5
	v_mul_f32_e32 v59, 0x4f800000, v5
	v_add_f32_dpp v9, v9, v9 quad_perm:[1,0,3,2] row_mask:0xf bank_mask:0xf bound_ctrl:1
	v_cndmask_b32_e32 v5, v5, v59, vcc
	v_sqrt_f32_e32 v59, v5
	s_nop 0
	v_add_u32_e32 v63, -1, v59
	v_fma_f32 v67, -v63, v59, v5
	v_cmp_ge_f32_e64 s[4:5], 0, v67
	v_add_u32_e32 v67, 1, v59
	s_nop 0
	v_cndmask_b32_e64 v63, v59, v63, s[4:5]
	v_fma_f32 v59, -v67, v59, v5
	v_cmp_lt_f32_e64 s[4:5], 0, v59
	s_nop 1
	v_cndmask_b32_e64 v59, v63, v67, s[4:5]
	v_mul_f32_e32 v63, 0x37800000, v59
	v_cndmask_b32_e32 v59, v59, v63, vcc
	v_cmp_class_f32_e32 vcc, v5, v101
	s_nop 1
	v_cndmask_b32_e32 v5, v59, v5, vcc
	v_mov_b32_e32 v59, v97
	s_nop 1
	s_nop 0
	s_nop 1
	v_add_f32_dpp v9, v9, v9 row_bcast:15 row_mask:0xa bank_mask:0xf
	v_mov_b32_e32 v59, v97
	s_nop 1
	s_nop 0
	v_add_f32_dpp v9, v9, v9 row_bcast:31 row_mask:0xc bank_mask:0xf
	s_nop 0
	v_readlane_b32 s4, v9, 63
	s_nop 1
	v_fma_f32 v9, s4, v100, v99
	v_cmp_gt_f32_e32 vcc, s2, v9
	v_mul_f32_e32 v59, 0x4f800000, v9
	s_nop 0
	v_cndmask_b32_e32 v9, v9, v59, vcc
	v_sqrt_f32_e32 v59, v9
	s_nop 0
	v_add_u32_e32 v63, -1, v59
	v_fma_f32 v67, -v63, v59, v9
	v_cmp_ge_f32_e64 s[4:5], 0, v67
	v_add_u32_e32 v67, 1, v59
	s_nop 0
	v_cndmask_b32_e64 v63, v59, v63, s[4:5]
	v_fma_f32 v59, -v67, v59, v9
	v_cmp_lt_f32_e64 s[4:5], 0, v59
	s_nop 1
	v_cndmask_b32_e64 v59, v63, v67, s[4:5]
	v_mul_f32_e32 v63, 0x37800000, v59
	v_cndmask_b32_e32 v59, v59, v63, vcc
	v_cmp_class_f32_e32 vcc, v9, v101
	s_nop 1
	v_cndmask_b32_e32 v9, v59, v9, vcc
	v_div_scale_f32 v59, s[4:5], v9, v9, 1.0
	v_rcp_f32_e32 v63, v59
	s_nop 0
	v_fma_f32 v67, -v59, v63, 1.0
	v_fmac_f32_e32 v63, v67, v63
	v_div_scale_f32 v67, vcc, 1.0, v9, 1.0
	v_mul_f32_e32 v68, v67, v63
	v_fma_f32 v69, -v59, v68, v67
	v_fmac_f32_e32 v68, v69, v63
	v_fma_f32 v59, -v59, v68, v67
	v_div_fmas_f32 v59, v59, v63, v68
	v_div_fixup_f32 v69, v59, v9, 1.0
	v_div_scale_f32 v9, s[4:5], v5, v5, 1.0
	v_rcp_f32_e32 v59, v9
	s_nop 0
	v_fma_f32 v63, -v9, v59, 1.0
	v_fmac_f32_e32 v59, v63, v59
	v_div_scale_f32 v63, vcc, 1.0, v5, 1.0
	v_mul_f32_e32 v67, v63, v59
	v_fma_f32 v68, -v9, v67, v63
	v_fmac_f32_e32 v67, v68, v59
	v_fma_f32 v9, -v9, v67, v63
	v_div_fmas_f32 v9, v9, v59, v67
	v_div_fixup_f32 v68, v9, v5, 1.0
	v_pk_mul_f32 v[72:73], v[68:69], v[76:77]
	v_and_b32_e32 v77, 0xffff0000, v54
	v_pk_mul_f32 v[72:73], v[6:7], v[72:73] op_sel_hi:[0,1]
	v_cvt_pk_bf16_f32 v87, v72, v73
	v_pk_mul_f32 v[72:73], v[68:69], v[80:81]
	v_and_b32_e32 v76, 0xffff0000, v50
	v_pk_mul_f32 v[72:73], v[6:7], v[72:73] op_sel:[1,0]
	v_pk_mul_f32 v[80:81], v[76:77], v[76:77]
	v_cvt_pk_bf16_f32 v83, v72, v73
	v_pk_mul_f32 v[72:73], v[68:69], v[110:111]
	v_lshlrev_b32_e32 v111, 16, v47
	v_pk_mul_f32 v[72:73], v[8:9], v[72:73] op_sel_hi:[0,1]
	v_cvt_pk_bf16_f32 v79, v72, v73
	v_pk_mul_f32 v[72:73], v[68:69], v[92:93]
	v_lshlrev_b32_e32 v93, 16, v55
	v_pk_mul_f32 v[72:73], v[96:97], v[72:73] op_sel_hi:[0,1]
	v_cvt_pk_bf16_f32 v75, v72, v73
	v_pk_mul_f32 v[72:73], v[68:69], v[88:89]
	v_lshlrev_b32_e32 v92, 16, v51
	v_pk_mul_f32 v[72:73], v[2:3], v[72:73] op_sel_hi:[0,1]
	v_cvt_pk_bf16_f32 v71, v72, v73
	v_pk_mul_f32 v[72:73], v[68:69], v[90:91]
	v_and_b32_e32 v55, 0xffff0000, v55
	v_pk_mul_f32 v[72:73], v[2:3], v[72:73] op_sel:[1,0]
	v_and_b32_e32 v90, 0xffff0000, v57
	v_cvt_pk_bf16_f32 v67, v72, v73
	v_mov_b32_e32 v72, v61
	v_mov_b32_e32 v73, v65
	v_pk_mul_f32 v[72:73], v[68:69], v[72:73]
	v_mov_b32_e32 v61, v64
	v_pk_mul_f32 v[72:73], v[4:5], v[72:73] op_sel_hi:[0,1]
	v_cvt_pk_bf16_f32 v63, v72, v73
	v_lshlrev_b32_e32 v73, 16, v54
	v_lshlrev_b32_e32 v72, 16, v50
	v_pk_fma_f32 v[80:81], v[72:73], v[72:73], v[80:81]
	v_pk_mul_f32 v[60:61], v[68:69], v[60:61]
	v_pk_fma_f32 v[80:81], v[92:93], v[92:93], v[80:81]
	v_and_b32_e32 v54, 0xffff0000, v51
	v_pk_mul_f32 v[60:61], v[98:99], v[60:61] op_sel_hi:[0,1]
	v_pk_fma_f32 v[50:51], v[54:55], v[54:55], v[80:81]
	v_cvt_pk_bf16_f32 v59, v60, v61
	v_and_b32_e32 v60, 0xffff0000, v53
	v_lshlrev_b32_e32 v61, 16, v53
	v_pk_fma_f32 v[50:51], v[94:95], v[94:95], v[50:51]
	v_and_b32_e32 v53, 0xffff0000, v56
	v_pk_mul_f32 v[64:65], v[60:61], v[60:61]
	v_pk_fma_f32 v[50:51], v[52:53], v[52:53], v[50:51]
	v_lshlrev_b32_e32 v91, 16, v57
	v_add_f32_e32 v5, v65, v50
	v_add_f32_e32 v5, v64, v5
	v_mov_b32_e32 v50, v97
	v_pk_mul_f32 v[68:69], v[90:91], v[90:91]
	v_add_f32_dpp v5, v5, v5 row_ror:8 row_mask:0xf bank_mask:0xf bound_ctrl:1
	v_add_f32_e32 v9, v69, v51
	v_add_f32_e32 v9, v68, v9
	v_add_f32_dpp v5, v5, v5 row_ror:4 row_mask:0xf bank_mask:0xf bound_ctrl:1
	v_lshlrev_b32_e32 v110, 16, v43
	v_add_f32_dpp v9, v9, v9 row_ror:8 row_mask:0xf bank_mask:0xf bound_ctrl:1
	v_add_f32_dpp v5, v5, v5 quad_perm:[2,3,0,1] row_mask:0xf bank_mask:0xf bound_ctrl:1
	v_and_b32_e32 v47, 0xffff0000, v47
	v_add_f32_dpp v9, v9, v9 row_ror:4 row_mask:0xf bank_mask:0xf bound_ctrl:1
	v_add_f32_dpp v5, v5, v5 quad_perm:[1,0,3,2] row_mask:0xf bank_mask:0xf bound_ctrl:1
	s_nop 0
	v_add_f32_dpp v9, v9, v9 quad_perm:[2,3,0,1] row_mask:0xf bank_mask:0xf bound_ctrl:1
	s_nop 0
	v_add_f32_dpp v5, v5, v5 row_bcast:15 row_mask:0xa bank_mask:0xf
	v_mov_b32_e32 v50, v97
	v_add_f32_dpp v9, v9, v9 quad_perm:[1,0,3,2] row_mask:0xf bank_mask:0xf bound_ctrl:1
	s_nop 0
	s_nop 0
	v_add_f32_dpp v5, v5, v5 row_bcast:31 row_mask:0xc bank_mask:0xf
	s_nop 0
	v_readlane_b32 s4, v5, 63
	s_nop 1
	v_fma_f32 v5, s4, v100, v99
	v_cmp_gt_f32_e32 vcc, s2, v5
	v_mul_f32_e32 v50, 0x4f800000, v5
	s_nop 0
	v_cndmask_b32_e32 v5, v5, v50, vcc
	v_sqrt_f32_e32 v50, v5
	s_nop 0
	v_add_u32_e32 v51, -1, v50
	v_fma_f32 v56, -v51, v50, v5
	v_cmp_ge_f32_e64 s[4:5], 0, v56
	v_add_u32_e32 v56, 1, v50
	s_nop 0
	v_cndmask_b32_e64 v51, v50, v51, s[4:5]
	v_fma_f32 v50, -v56, v50, v5
	v_cmp_lt_f32_e64 s[4:5], 0, v50
	s_nop 1
	v_cndmask_b32_e64 v50, v51, v56, s[4:5]
	v_mul_f32_e32 v51, 0x37800000, v50
	v_cndmask_b32_e32 v50, v50, v51, vcc
	v_cmp_class_f32_e32 vcc, v5, v101
	s_nop 1
	v_cndmask_b32_e32 v5, v50, v5, vcc
	v_mov_b32_e32 v50, v97
	s_nop 1
	s_nop 0
	s_nop 1
	v_add_f32_dpp v9, v9, v9 row_bcast:15 row_mask:0xa bank_mask:0xf
	v_mov_b32_e32 v50, v97
	s_nop 1
	s_nop 0
	v_add_f32_dpp v9, v9, v9 row_bcast:31 row_mask:0xc bank_mask:0xf
	s_nop 0
	v_readlane_b32 s4, v9, 63
	s_nop 1
	v_fma_f32 v9, s4, v100, v99
	v_cmp_gt_f32_e32 vcc, s2, v9
	v_mul_f32_e32 v50, 0x4f800000, v9
	s_nop 0
	v_cndmask_b32_e32 v9, v9, v50, vcc
	v_sqrt_f32_e32 v50, v9
	s_nop 0
	v_add_u32_e32 v51, -1, v50
	v_fma_f32 v56, -v51, v50, v9
	v_cmp_ge_f32_e64 s[4:5], 0, v56
	v_add_u32_e32 v56, 1, v50
	s_nop 0
	v_cndmask_b32_e64 v51, v50, v51, s[4:5]
	v_fma_f32 v50, -v56, v50, v9
	v_cmp_lt_f32_e64 s[4:5], 0, v50
	s_nop 1
	v_cndmask_b32_e64 v50, v51, v56, s[4:5]
	v_mul_f32_e32 v51, 0x37800000, v50
	v_cndmask_b32_e32 v50, v50, v51, vcc
	v_cmp_class_f32_e32 vcc, v9, v101
	s_nop 1
	v_cndmask_b32_e32 v9, v50, v9, vcc
	v_div_scale_f32 v50, s[4:5], v9, v9, 1.0
	v_rcp_f32_e32 v51, v50
	s_nop 0
	v_fma_f32 v56, -v50, v51, 1.0
	v_fmac_f32_e32 v51, v56, v51
	v_div_scale_f32 v56, vcc, 1.0, v9, 1.0
	v_mul_f32_e32 v57, v56, v51
	v_fma_f32 v64, -v50, v57, v56
	v_fmac_f32_e32 v57, v64, v51
	v_fma_f32 v50, -v50, v57, v56
	v_div_fmas_f32 v50, v50, v51, v57
	v_div_fixup_f32 v51, v50, v9, 1.0
	v_div_scale_f32 v9, s[4:5], v5, v5, 1.0
	v_rcp_f32_e32 v50, v9
	s_nop 0
	v_fma_f32 v56, -v9, v50, 1.0
	v_fmac_f32_e32 v50, v56, v50
	v_div_scale_f32 v56, vcc, 1.0, v5, 1.0
	v_mul_f32_e32 v57, v56, v50
	v_fma_f32 v64, -v9, v57, v56
	v_fmac_f32_e32 v57, v64, v50
	v_fma_f32 v9, -v9, v57, v56
	v_div_fmas_f32 v9, v9, v50, v57
	v_div_fixup_f32 v50, v9, v5, 1.0
	v_pk_mul_f32 v[56:57], v[50:51], v[72:73]
	v_pk_mul_f32 v[54:55], v[50:51], v[54:55]
	v_pk_mul_f32 v[56:57], v[6:7], v[56:57] op_sel_hi:[0,1]
	v_cvt_pk_bf16_f32 v88, v56, v57
	v_pk_mul_f32 v[56:57], v[50:51], v[76:77]
	v_pk_mul_f32 v[52:53], v[50:51], v[52:53]
	v_pk_mul_f32 v[56:57], v[6:7], v[56:57] op_sel:[1,0]
	v_pk_mul_f32 v[54:55], v[96:97], v[54:55] op_sel_hi:[0,1]
	v_cvt_pk_bf16_f32 v84, v56, v57
	v_pk_mul_f32 v[56:57], v[50:51], v[92:93]
	v_pk_mul_f32 v[52:53], v[2:3], v[52:53] op_sel:[1,0]
	v_and_b32_e32 v93, 0xffff0000, v46
	v_and_b32_e32 v92, 0xffff0000, v42
	v_cvt_pk_bf16_f32 v76, v54, v55
	v_pk_mul_f32 v[54:55], v[50:51], v[94:95]
	v_cvt_pk_bf16_f32 v68, v52, v53
	v_mov_b32_e32 v52, v61
	v_mov_b32_e32 v53, v91
	v_mov_b32_e32 v61, v90
	v_lshlrev_b32_e32 v91, 16, v46
	v_lshlrev_b32_e32 v90, 16, v42
	v_pk_mul_f32 v[94:95], v[92:93], v[92:93]
	v_pk_mul_f32 v[52:53], v[50:51], v[52:53]
	v_pk_fma_f32 v[94:95], v[90:91], v[90:91], v[94:95]
	v_pk_mul_f32 v[50:51], v[50:51], v[60:61]
	v_pk_fma_f32 v[94:95], v[110:111], v[110:111], v[94:95]
	v_and_b32_e32 v46, 0xffff0000, v43
	v_pk_mul_f32 v[50:51], v[98:99], v[50:51] op_sel_hi:[0,1]
	v_pk_fma_f32 v[42:43], v[46:47], v[46:47], v[94:95]
	v_lshlrev_b32_e32 v95, 16, v48
	v_lshlrev_b32_e32 v94, 16, v44
	v_pk_mul_f32 v[54:55], v[2:3], v[54:55] op_sel_hi:[0,1]
	v_cvt_pk_bf16_f32 v60, v50, v51
	v_and_b32_e32 v50, 0xffff0000, v45
	v_lshlrev_b32_e32 v51, 16, v45
	v_pk_fma_f32 v[42:43], v[94:95], v[94:95], v[42:43]
	v_and_b32_e32 v45, 0xffff0000, v48
	v_and_b32_e32 v44, 0xffff0000, v44
	v_cvt_pk_bf16_f32 v72, v54, v55
	v_pk_mul_f32 v[54:55], v[50:51], v[50:51]
	v_pk_fma_f32 v[42:43], v[44:45], v[44:45], v[42:43]
	v_pk_mul_f32 v[52:53], v[4:5], v[52:53] op_sel_hi:[0,1]
	v_add_f32_e32 v5, v55, v42
	v_add_f32_e32 v5, v54, v5
	v_mov_b32_e32 v42, v97
	v_pk_mul_f32 v[56:57], v[8:9], v[56:57] op_sel_hi:[0,1]
	v_add_f32_dpp v5, v5, v5 row_ror:8 row_mask:0xf bank_mask:0xf bound_ctrl:1
	v_cvt_pk_bf16_f32 v64, v52, v53
	v_and_b32_e32 v52, 0xffff0000, v49
	v_add_f32_dpp v5, v5, v5 row_ror:4 row_mask:0xf bank_mask:0xf bound_ctrl:1
	v_lshlrev_b32_e32 v53, 16, v49
	v_cvt_pk_bf16_f32 v80, v56, v57
	v_add_f32_dpp v5, v5, v5 quad_perm:[2,3,0,1] row_mask:0xf bank_mask:0xf bound_ctrl:1
	v_pk_mul_f32 v[56:57], v[52:53], v[52:53]
	s_nop 0
	v_add_f32_dpp v5, v5, v5 quad_perm:[1,0,3,2] row_mask:0xf bank_mask:0xf bound_ctrl:1
	v_add_f32_e32 v9, v57, v43
	v_add_f32_e32 v9, v56, v9
	s_nop 0
	v_add_f32_dpp v5, v5, v5 row_bcast:15 row_mask:0xa bank_mask:0xf
	v_mov_b32_e32 v42, v97
	v_add_f32_dpp v9, v9, v9 row_ror:8 row_mask:0xf bank_mask:0xf bound_ctrl:1
	v_lshlrev_b32_e32 v57, 16, v39
	s_nop 0
	v_add_f32_dpp v5, v5, v5 row_bcast:31 row_mask:0xc bank_mask:0xf
	v_add_f32_dpp v9, v9, v9 row_ror:4 row_mask:0xf bank_mask:0xf bound_ctrl:1
	v_readlane_b32 s4, v5, 63
	v_lshlrev_b32_e32 v56, 16, v35
	v_add_f32_dpp v9, v9, v9 quad_perm:[2,3,0,1] row_mask:0xf bank_mask:0xf bound_ctrl:1
	v_fma_f32 v5, s4, v100, v99
	v_cmp_gt_f32_e32 vcc, s2, v5
	v_mul_f32_e32 v42, 0x4f800000, v5
	v_add_f32_dpp v9, v9, v9 quad_perm:[1,0,3,2] row_mask:0xf bank_mask:0xf bound_ctrl:1
	v_cndmask_b32_e32 v5, v5, v42, vcc
	v_sqrt_f32_e32 v42, v5
	v_and_b32_e32 v39, 0xffff0000, v39
	v_add_u32_e32 v43, -1, v42
	v_fma_f32 v48, -v43, v42, v5
	v_cmp_ge_f32_e64 s[4:5], 0, v48
	v_add_u32_e32 v48, 1, v42
	s_nop 0
	v_cndmask_b32_e64 v43, v42, v43, s[4:5]
	v_fma_f32 v42, -v48, v42, v5
	v_cmp_lt_f32_e64 s[4:5], 0, v42
	s_nop 1
	v_cndmask_b32_e64 v42, v43, v48, s[4:5]
	v_mul_f32_e32 v43, 0x37800000, v42
	v_cndmask_b32_e32 v42, v42, v43, vcc
	v_cmp_class_f32_e32 vcc, v5, v101
	s_nop 1
	v_cndmask_b32_e32 v5, v42, v5, vcc
	v_mov_b32_e32 v42, v97
	s_nop 1
	s_nop 0
	s_nop 1
	v_add_f32_dpp v9, v9, v9 row_bcast:15 row_mask:0xa bank_mask:0xf
	v_mov_b32_e32 v42, v97
	s_nop 1
	s_nop 0
	v_add_f32_dpp v9, v9, v9 row_bcast:31 row_mask:0xc bank_mask:0xf
	s_nop 0
	v_readlane_b32 s4, v9, 63
	s_nop 1
	v_fma_f32 v9, s4, v100, v99
	v_cmp_gt_f32_e32 vcc, s2, v9
	v_mul_f32_e32 v42, 0x4f800000, v9
	s_nop 0
	v_cndmask_b32_e32 v9, v9, v42, vcc
	v_sqrt_f32_e32 v42, v9
	s_nop 0
	v_add_u32_e32 v43, -1, v42
	v_fma_f32 v48, -v43, v42, v9
	v_cmp_ge_f32_e64 s[4:5], 0, v48
	v_add_u32_e32 v48, 1, v42
	s_nop 0
	v_cndmask_b32_e64 v43, v42, v43, s[4:5]
	v_fma_f32 v42, -v48, v42, v9
	v_cmp_lt_f32_e64 s[4:5], 0, v42
	s_nop 1
	v_cndmask_b32_e64 v42, v43, v48, s[4:5]
	v_mul_f32_e32 v43, 0x37800000, v42
	v_cndmask_b32_e32 v42, v42, v43, vcc
	v_cmp_class_f32_e32 vcc, v9, v101
	s_nop 1
	v_cndmask_b32_e32 v9, v42, v9, vcc
	v_div_scale_f32 v42, s[4:5], v9, v9, 1.0
	v_rcp_f32_e32 v43, v42
	s_nop 0
	v_fma_f32 v48, -v42, v43, 1.0
	v_fmac_f32_e32 v43, v48, v43
	v_div_scale_f32 v48, vcc, 1.0, v9, 1.0
	v_mul_f32_e32 v49, v48, v43
	v_fma_f32 v54, -v42, v49, v48
	v_fmac_f32_e32 v49, v54, v43
	v_fma_f32 v42, -v42, v49, v48
	v_div_fmas_f32 v42, v42, v43, v49
	v_div_fixup_f32 v43, v42, v9, 1.0
	v_div_scale_f32 v9, s[4:5], v5, v5, 1.0
	v_rcp_f32_e32 v42, v9
	s_nop 0
	v_fma_f32 v48, -v9, v42, 1.0
	v_fmac_f32_e32 v42, v48, v42
	v_div_scale_f32 v48, vcc, 1.0, v5, 1.0
	v_mul_f32_e32 v49, v48, v42
	v_fma_f32 v54, -v9, v49, v48
	v_fmac_f32_e32 v49, v54, v42
	v_fma_f32 v9, -v9, v49, v48
	v_div_fmas_f32 v9, v9, v42, v49
	v_div_fixup_f32 v42, v9, v5, 1.0
	v_pk_mul_f32 v[48:49], v[42:43], v[90:91]
	v_pk_mul_f32 v[44:45], v[42:43], v[44:45]
	v_pk_mul_f32 v[48:49], v[6:7], v[48:49] op_sel_hi:[0,1]
	v_cvt_pk_bf16_f32 v89, v48, v49
	v_pk_mul_f32 v[48:49], v[42:43], v[92:93]
	v_pk_mul_f32 v[46:47], v[42:43], v[46:47]
	v_pk_mul_f32 v[44:45], v[2:3], v[44:45] op_sel:[1,0]
	v_pk_mul_f32 v[48:49], v[6:7], v[48:49] op_sel:[1,0]
	v_pk_mul_f32 v[46:47], v[96:97], v[46:47] op_sel_hi:[0,1]
	v_cvt_pk_bf16_f32 v69, v44, v45
	v_mov_b32_e32 v44, v51
	v_mov_b32_e32 v45, v53
	v_mov_b32_e32 v51, v52
	v_and_b32_e32 v53, 0xffff0000, v38
	v_and_b32_e32 v52, 0xffff0000, v34
	v_cvt_pk_bf16_f32 v85, v48, v49
	v_pk_mul_f32 v[48:49], v[42:43], v[110:111]
	v_cvt_pk_bf16_f32 v77, v46, v47
	v_pk_mul_f32 v[46:47], v[42:43], v[94:95]
	v_pk_mul_f32 v[44:45], v[42:43], v[44:45]
	v_pk_mul_f32 v[42:43], v[42:43], v[50:51]
	v_lshlrev_b32_e32 v51, 16, v38
	v_lshlrev_b32_e32 v50, 16, v34
	v_pk_mul_f32 v[54:55], v[52:53], v[52:53]
	v_pk_mul_f32 v[42:43], v[98:99], v[42:43] op_sel_hi:[0,1]
	v_pk_fma_f32 v[54:55], v[50:51], v[50:51], v[54:55]
	v_cvt_pk_bf16_f32 v61, v42, v43
	v_pk_fma_f32 v[54:55], v[56:57], v[56:57], v[54:55]
	v_and_b32_e32 v38, 0xffff0000, v35
	v_pk_mul_f32 v[44:45], v[4:5], v[44:45] op_sel_hi:[0,1]
	ds_write_b128 v108, v[58:61] offset:1904
	v_pk_fma_f32 v[34:35], v[38:39], v[38:39], v[54:55]
	v_lshlrev_b32_e32 v61, 16, v40
	v_lshlrev_b32_e32 v60, 16, v36
	v_cvt_pk_bf16_f32 v65, v44, v45
	v_and_b32_e32 v44, 0xffff0000, v37
	v_lshlrev_b32_e32 v45, 16, v37
	v_pk_fma_f32 v[34:35], v[60:61], v[60:61], v[34:35]
	v_and_b32_e32 v37, 0xffff0000, v40
	v_and_b32_e32 v36, 0xffff0000, v36
	v_pk_mul_f32 v[42:43], v[44:45], v[44:45]
	v_pk_fma_f32 v[34:35], v[36:37], v[36:37], v[34:35]
	v_pk_mul_f32 v[48:49], v[8:9], v[48:49] op_sel_hi:[0,1]
	v_add_f32_e32 v9, v43, v34
	v_add_f32_e32 v9, v42, v9
	v_cvt_pk_bf16_f32 v81, v48, v49
	v_pk_mul_f32 v[46:47], v[2:3], v[46:47] op_sel_hi:[0,1]
	v_add_f32_dpp v9, v9, v9 row_ror:8 row_mask:0xf bank_mask:0xf bound_ctrl:1
	v_and_b32_e32 v48, 0xffff0000, v41
	v_lshlrev_b32_e32 v49, 16, v41
	v_add_f32_dpp v9, v9, v9 row_ror:4 row_mask:0xf bank_mask:0xf bound_ctrl:1
	v_cvt_pk_bf16_f32 v73, v46, v47
	v_pk_mul_f32 v[46:47], v[48:49], v[48:49]
	v_add_f32_dpp v9, v9, v9 quad_perm:[2,3,0,1] row_mask:0xf bank_mask:0xf bound_ctrl:1
	v_add_f32_e32 v34, v47, v35
	v_mov_b32_e32 v35, v97
	v_add_f32_dpp v9, v9, v9 quad_perm:[1,0,3,2] row_mask:0xf bank_mask:0xf bound_ctrl:1
	v_add_f32_e32 v34, v46, v34
	ds_write_b128 v108, v[62:65] offset:1632
	s_nop 0
	v_add_f32_dpp v9, v9, v9 row_bcast:15 row_mask:0xa bank_mask:0xf
	v_mov_b32_e32 v35, v97
	v_add_f32_dpp v34, v34, v34 row_ror:8 row_mask:0xf bank_mask:0xf bound_ctrl:1
	v_bitop3_b32 v5, s25, v106, 8 bitop3:0x36
	s_nop 0
	v_add_f32_dpp v9, v9, v9 row_bcast:31 row_mask:0xc bank_mask:0xf
	v_add_f32_dpp v34, v34, v34 row_ror:4 row_mask:0xf bank_mask:0xf bound_ctrl:1
	v_readlane_b32 s4, v9, 63
	v_lshlrev_b32_e32 v5, 1, v5
	v_add_f32_dpp v34, v34, v34 quad_perm:[2,3,0,1] row_mask:0xf bank_mask:0xf bound_ctrl:1
	v_fma_f32 v9, s4, v100, v99
	v_cmp_gt_f32_e32 vcc, s2, v9
	v_mul_f32_e32 v35, 0x4f800000, v9
	v_add_f32_dpp v34, v34, v34 quad_perm:[1,0,3,2] row_mask:0xf bank_mask:0xf bound_ctrl:1
	v_cndmask_b32_e32 v9, v9, v35, vcc
	v_sqrt_f32_e32 v35, v9
	v_lshlrev_b32_e32 v65, 16, v31
	v_lshlrev_b32_e32 v64, 16, v27
	v_add3_u32 v5, v105, v5, v107
	v_add_u32_e32 v40, -1, v35
	v_fma_f32 v41, -v40, v35, v9
	v_cmp_ge_f32_e64 s[4:5], 0, v41
	v_add_u32_e32 v41, 1, v35
	v_and_b32_e32 v31, 0xffff0000, v31
	v_cndmask_b32_e64 v40, v35, v40, s[4:5]
	v_fma_f32 v35, -v41, v35, v9
	v_cmp_lt_f32_e64 s[4:5], 0, v35
	ds_write_b128 v108, v[86:89]
	ds_write_b128 v108, v[82:85] offset:272
	v_cndmask_b32_e64 v35, v40, v41, s[4:5]
	v_mul_f32_e32 v40, 0x37800000, v35
	v_cndmask_b32_e32 v35, v35, v40, vcc
	v_cmp_class_f32_e32 vcc, v9, v101
	ds_write_b128 v108, v[78:81] offset:544
	ds_write_b128 v108, v[74:77] offset:816
	v_cndmask_b32_e32 v9, v35, v9, vcc
	v_mov_b32_e32 v35, v97
	ds_write_b128 v108, v[70:73] offset:1088
	ds_write_b128 v108, v[66:69] offset:1360
	s_nop 0
	s_nop 1
	v_add_f32_dpp v34, v34, v34 row_bcast:15 row_mask:0xa bank_mask:0xf
	v_mov_b32_e32 v35, v97
	s_nop 1
	s_nop 0
	v_add_f32_dpp v34, v34, v34 row_bcast:31 row_mask:0xc bank_mask:0xf
	s_nop 0
	v_readlane_b32 s4, v34, 63
	s_nop 1
	v_fma_f32 v34, s4, v100, v99
	v_cmp_gt_f32_e32 vcc, s2, v34
	v_mul_f32_e32 v35, 0x4f800000, v34
	s_nop 0
	v_cndmask_b32_e32 v34, v34, v35, vcc
	v_sqrt_f32_e32 v35, v34
	s_nop 0
	v_add_u32_e32 v40, -1, v35
	v_fma_f32 v41, -v40, v35, v34
	v_cmp_ge_f32_e64 s[4:5], 0, v41
	v_add_u32_e32 v41, 1, v35
	s_nop 0
	v_cndmask_b32_e64 v40, v35, v40, s[4:5]
	v_fma_f32 v35, -v41, v35, v34
	v_cmp_lt_f32_e64 s[4:5], 0, v35
	s_nop 1
	v_cndmask_b32_e64 v35, v40, v41, s[4:5]
	v_mul_f32_e32 v40, 0x37800000, v35
	v_cndmask_b32_e32 v35, v35, v40, vcc
	v_cmp_class_f32_e32 vcc, v34, v101
	s_nop 1
	v_cndmask_b32_e32 v34, v35, v34, vcc
	v_div_scale_f32 v35, s[4:5], v34, v34, 1.0
	v_rcp_f32_e32 v40, v35
	s_nop 0
	v_fma_f32 v41, -v35, v40, 1.0
	v_fmac_f32_e32 v40, v41, v40
	v_div_scale_f32 v41, vcc, 1.0, v34, 1.0
	v_mul_f32_e32 v42, v41, v40
	v_fma_f32 v43, -v35, v42, v41
	v_fmac_f32_e32 v42, v43, v40
	v_fma_f32 v35, -v35, v42, v41
	v_div_fmas_f32 v35, v35, v40, v42
	v_div_fixup_f32 v35, v35, v34, 1.0
	v_div_scale_f32 v34, s[4:5], v9, v9, 1.0
	v_rcp_f32_e32 v40, v34
	s_nop 0
	v_fma_f32 v41, -v34, v40, 1.0
	v_fmac_f32_e32 v40, v41, v40
	v_div_scale_f32 v41, vcc, 1.0, v9, 1.0
	v_mul_f32_e32 v42, v41, v40
	v_fma_f32 v43, -v34, v42, v41
	v_fmac_f32_e32 v42, v43, v40
	v_fma_f32 v34, -v34, v42, v41
	v_div_fmas_f32 v34, v34, v40, v42
	v_div_fixup_f32 v34, v34, v9, 1.0
	v_pk_mul_f32 v[40:41], v[34:35], v[50:51]
	v_pk_mul_f32 v[38:39], v[34:35], v[38:39]
	v_pk_mul_f32 v[40:41], v[6:7], v[40:41] op_sel_hi:[0,1]
	v_cvt_pk_bf16_f32 v62, v40, v41
	v_pk_mul_f32 v[40:41], v[34:35], v[52:53]
	v_pk_mul_f32 v[38:39], v[96:97], v[38:39] op_sel_hi:[0,1]
	v_pk_mul_f32 v[40:41], v[6:7], v[40:41] op_sel:[1,0]
	v_pk_mul_f32 v[36:37], v[34:35], v[36:37]
	v_cvt_pk_bf16_f32 v58, v40, v41
	v_pk_mul_f32 v[40:41], v[34:35], v[56:57]
	v_and_b32_e32 v57, 0xffff0000, v30
	v_and_b32_e32 v56, 0xffff0000, v26
	v_cvt_pk_bf16_f32 v50, v38, v39
	v_pk_mul_f32 v[38:39], v[34:35], v[60:61]
	v_pk_mul_f32 v[36:37], v[2:3], v[36:37] op_sel:[1,0]
	v_lshlrev_b32_e32 v53, 16, v30
	v_lshlrev_b32_e32 v52, 16, v26
	v_pk_mul_f32 v[60:61], v[56:57], v[56:57]
	v_cvt_pk_bf16_f32 v42, v36, v37
	v_mov_b32_e32 v36, v45
	v_mov_b32_e32 v37, v49
	v_pk_fma_f32 v[60:61], v[52:53], v[52:53], v[60:61]
	v_pk_mul_f32 v[36:37], v[34:35], v[36:37]
	v_pk_fma_f32 v[60:61], v[64:65], v[64:65], v[60:61]
	v_and_b32_e32 v30, 0xffff0000, v27
	v_pk_mul_f32 v[38:39], v[2:3], v[38:39] op_sel_hi:[0,1]
	v_pk_mul_f32 v[36:37], v[4:5], v[36:37] op_sel_hi:[0,1]
	v_pk_fma_f32 v[26:27], v[30:31], v[30:31], v[60:61]
	v_lshlrev_b32_e32 v61, 16, v32
	v_lshlrev_b32_e32 v60, 16, v28
	v_cvt_pk_bf16_f32 v46, v38, v39
	v_cvt_pk_bf16_f32 v38, v36, v37
	v_mov_b32_e32 v45, v48
	v_and_b32_e32 v36, 0xffff0000, v29
	v_lshlrev_b32_e32 v37, 16, v29
	v_pk_fma_f32 v[26:27], v[60:61], v[60:61], v[26:27]
	v_and_b32_e32 v29, 0xffff0000, v32
	v_and_b32_e32 v28, 0xffff0000, v28
	v_pk_mul_f32 v[34:35], v[34:35], v[44:45]
	v_pk_mul_f32 v[44:45], v[36:37], v[36:37]
	v_pk_fma_f32 v[26:27], v[28:29], v[28:29], v[26:27]
	v_pk_mul_f32 v[40:41], v[8:9], v[40:41] op_sel_hi:[0,1]
	v_add_f32_e32 v9, v45, v26
	v_add_f32_e32 v9, v44, v9
	v_cvt_pk_bf16_f32 v54, v40, v41
	v_and_b32_e32 v40, 0xffff0000, v33
	v_add_f32_dpp v9, v9, v9 row_ror:8 row_mask:0xf bank_mask:0xf bound_ctrl:1
	v_lshlrev_b32_e32 v41, 16, v33
	v_pk_mul_f32 v[48:49], v[40:41], v[40:41]
	v_add_f32_dpp v9, v9, v9 row_ror:4 row_mask:0xf bank_mask:0xf bound_ctrl:1
	v_add_f32_e32 v26, v49, v27
	v_mov_b32_e32 v27, v97
	v_add_f32_dpp v9, v9, v9 quad_perm:[2,3,0,1] row_mask:0xf bank_mask:0xf bound_ctrl:1
	v_add_f32_e32 v26, v48, v26
	v_pk_mul_f32 v[34:35], v[98:99], v[34:35] op_sel_hi:[0,1]
	v_add_f32_dpp v9, v9, v9 quad_perm:[1,0,3,2] row_mask:0xf bank_mask:0xf bound_ctrl:1
	v_add_f32_dpp v26, v26, v26 row_ror:8 row_mask:0xf bank_mask:0xf bound_ctrl:1
	v_cvt_pk_bf16_f32 v34, v34, v35
	s_nop 0
	v_add_f32_dpp v9, v9, v9 row_bcast:15 row_mask:0xa bank_mask:0xf
	v_mov_b32_e32 v27, v97
	v_add_f32_dpp v26, v26, v26 row_ror:4 row_mask:0xf bank_mask:0xf bound_ctrl:1
	v_lshlrev_b32_e32 v49, 16, v23
	s_nop 0
	v_add_f32_dpp v9, v9, v9 row_bcast:31 row_mask:0xc bank_mask:0xf
	v_add_f32_dpp v26, v26, v26 quad_perm:[2,3,0,1] row_mask:0xf bank_mask:0xf bound_ctrl:1
	v_readlane_b32 s4, v9, 63
	v_lshlrev_b32_e32 v48, 16, v19
	v_add_f32_dpp v26, v26, v26 quad_perm:[1,0,3,2] row_mask:0xf bank_mask:0xf bound_ctrl:1
	v_fma_f32 v9, s4, v100, v99
	v_cmp_gt_f32_e32 vcc, s2, v9
	v_mul_f32_e32 v27, 0x4f800000, v9
	v_and_b32_e32 v23, 0xffff0000, v23
	v_cndmask_b32_e32 v9, v9, v27, vcc
	v_sqrt_f32_e32 v27, v9
	s_nop 0
	v_add_u32_e32 v32, -1, v27
	v_fma_f32 v33, -v32, v27, v9
	v_cmp_ge_f32_e64 s[4:5], 0, v33
	v_add_u32_e32 v33, 1, v27
	s_nop 0
	v_cndmask_b32_e64 v32, v27, v32, s[4:5]
	v_fma_f32 v27, -v33, v27, v9
	v_cmp_lt_f32_e64 s[4:5], 0, v27
	s_nop 1
	v_cndmask_b32_e64 v27, v32, v33, s[4:5]
	v_mul_f32_e32 v32, 0x37800000, v27
	v_cndmask_b32_e32 v27, v27, v32, vcc
	v_cmp_class_f32_e32 vcc, v9, v101
	s_nop 1
	v_cndmask_b32_e32 v9, v27, v9, vcc
	v_mov_b32_e32 v27, v97
	s_nop 1
	s_nop 0
	s_nop 1
	v_add_f32_dpp v26, v26, v26 row_bcast:15 row_mask:0xa bank_mask:0xf
	v_mov_b32_e32 v27, v97
	s_nop 1
	s_nop 0
	v_add_f32_dpp v26, v26, v26 row_bcast:31 row_mask:0xc bank_mask:0xf
	s_nop 0
	v_readlane_b32 s4, v26, 63
	s_nop 1
	v_fma_f32 v26, s4, v100, v99
	v_cmp_gt_f32_e32 vcc, s2, v26
	v_mul_f32_e32 v27, 0x4f800000, v26
	s_nop 0
	v_cndmask_b32_e32 v26, v26, v27, vcc
	v_sqrt_f32_e32 v27, v26
	s_nop 0
	v_add_u32_e32 v32, -1, v27
	v_fma_f32 v33, -v32, v27, v26
	v_cmp_ge_f32_e64 s[4:5], 0, v33
	v_add_u32_e32 v33, 1, v27
	s_nop 0
	v_cndmask_b32_e64 v32, v27, v32, s[4:5]
	v_fma_f32 v27, -v33, v27, v26
	v_cmp_lt_f32_e64 s[4:5], 0, v27
	s_nop 1
	v_cndmask_b32_e64 v27, v32, v33, s[4:5]
	v_mul_f32_e32 v32, 0x37800000, v27
	v_cndmask_b32_e32 v27, v27, v32, vcc
	v_cmp_class_f32_e32 vcc, v26, v101
	s_nop 1
	v_cndmask_b32_e32 v26, v27, v26, vcc
	v_div_scale_f32 v27, s[4:5], v26, v26, 1.0
	v_rcp_f32_e32 v32, v27
	s_nop 0
	v_fma_f32 v33, -v27, v32, 1.0
	v_fmac_f32_e32 v32, v33, v32
	v_div_scale_f32 v33, vcc, 1.0, v26, 1.0
	v_mul_f32_e32 v35, v33, v32
	v_fma_f32 v39, -v27, v35, v33
	v_fmac_f32_e32 v35, v39, v32
	v_fma_f32 v27, -v27, v35, v33
	v_div_fmas_f32 v27, v27, v32, v35
	v_div_fixup_f32 v27, v27, v26, 1.0
	v_div_scale_f32 v26, s[4:5], v9, v9, 1.0
	v_rcp_f32_e32 v32, v26
	s_nop 0
	v_fma_f32 v33, -v26, v32, 1.0
	v_fmac_f32_e32 v32, v33, v32
	v_div_scale_f32 v33, vcc, 1.0, v9, 1.0
	v_mul_f32_e32 v35, v33, v32
	v_fma_f32 v39, -v26, v35, v33
	v_fmac_f32_e32 v35, v39, v32
	v_fma_f32 v26, -v26, v35, v33
	v_div_fmas_f32 v26, v26, v32, v35
	v_div_fixup_f32 v26, v26, v9, 1.0
	v_pk_mul_f32 v[32:33], v[26:27], v[52:53]
	v_pk_mul_f32 v[28:29], v[26:27], v[28:29]
	v_pk_mul_f32 v[32:33], v[6:7], v[32:33] op_sel_hi:[0,1]
	v_cvt_pk_bf16_f32 v63, v32, v33
	v_pk_mul_f32 v[32:33], v[26:27], v[56:57]
	v_pk_mul_f32 v[30:31], v[26:27], v[30:31]
	v_pk_mul_f32 v[28:29], v[2:3], v[28:29] op_sel:[1,0]
	v_pk_mul_f32 v[32:33], v[6:7], v[32:33] op_sel:[1,0]
	v_pk_mul_f32 v[30:31], v[96:97], v[30:31] op_sel_hi:[0,1]
	v_cvt_pk_bf16_f32 v43, v28, v29
	v_mov_b32_e32 v28, v37
	v_mov_b32_e32 v29, v41
	v_mov_b32_e32 v37, v40
	v_and_b32_e32 v41, 0xffff0000, v22
	v_and_b32_e32 v40, 0xffff0000, v18
	v_cvt_pk_bf16_f32 v59, v32, v33
	v_pk_mul_f32 v[32:33], v[26:27], v[64:65]
	v_cvt_pk_bf16_f32 v51, v30, v31
	v_pk_mul_f32 v[30:31], v[26:27], v[60:61]
	v_pk_mul_f32 v[28:29], v[26:27], v[28:29]
	v_pk_mul_f32 v[26:27], v[26:27], v[36:37]
	v_lshlrev_b32_e32 v37, 16, v22
	v_lshlrev_b32_e32 v36, 16, v18
	v_pk_mul_f32 v[44:45], v[40:41], v[40:41]
	v_and_b32_e32 v22, 0xffff0000, v19
	v_pk_fma_f32 v[44:45], v[36:37], v[36:37], v[44:45]
	v_pk_mul_f32 v[26:27], v[98:99], v[26:27] op_sel_hi:[0,1]
	v_pk_fma_f32 v[44:45], v[48:49], v[48:49], v[44:45]
	v_pk_mul_f32 v[30:31], v[2:3], v[30:31] op_sel_hi:[0,1]
	v_pk_fma_f32 v[18:19], v[22:23], v[22:23], v[44:45]
	v_lshlrev_b32_e32 v45, 16, v24
	v_lshlrev_b32_e32 v44, 16, v20
	v_cvt_pk_bf16_f32 v35, v26, v27
	v_and_b32_e32 v26, 0xffff0000, v21
	v_lshlrev_b32_e32 v27, 16, v21
	v_pk_fma_f32 v[18:19], v[44:45], v[44:45], v[18:19]
	v_and_b32_e32 v21, 0xffff0000, v24
	v_and_b32_e32 v20, 0xffff0000, v20
	v_cvt_pk_bf16_f32 v47, v30, v31
	v_pk_mul_f32 v[30:31], v[26:27], v[26:27]
	v_pk_fma_f32 v[18:19], v[20:21], v[20:21], v[18:19]
	v_pk_mul_f32 v[32:33], v[8:9], v[32:33] op_sel_hi:[0,1]
	v_add_f32_e32 v9, v31, v18
	v_add_f32_e32 v9, v30, v9
	v_pk_mul_f32 v[28:29], v[4:5], v[28:29] op_sel_hi:[0,1]
	v_cvt_pk_bf16_f32 v39, v28, v29
	v_add_f32_dpp v9, v9, v9 row_ror:8 row_mask:0xf bank_mask:0xf bound_ctrl:1
	v_and_b32_e32 v28, 0xffff0000, v25
	v_lshlrev_b32_e32 v29, 16, v25
	v_add_f32_dpp v9, v9, v9 row_ror:4 row_mask:0xf bank_mask:0xf bound_ctrl:1
	v_cvt_pk_bf16_f32 v55, v32, v33
	v_pk_mul_f32 v[32:33], v[28:29], v[28:29]
	v_add_f32_dpp v9, v9, v9 quad_perm:[2,3,0,1] row_mask:0xf bank_mask:0xf bound_ctrl:1
	v_add_f32_e32 v18, v33, v19
	v_mov_b32_e32 v19, v97
	v_add_f32_dpp v9, v9, v9 quad_perm:[1,0,3,2] row_mask:0xf bank_mask:0xf bound_ctrl:1
	v_add_f32_e32 v18, v32, v18
	v_lshlrev_b32_e32 v33, 16, v15
	s_nop 0
	v_add_f32_dpp v9, v9, v9 row_bcast:15 row_mask:0xa bank_mask:0xf
	v_mov_b32_e32 v19, v97
	v_add_f32_dpp v18, v18, v18 row_ror:8 row_mask:0xf bank_mask:0xf bound_ctrl:1
	v_lshlrev_b32_e32 v32, 16, v11
	s_nop 0
	v_add_f32_dpp v9, v9, v9 row_bcast:31 row_mask:0xc bank_mask:0xf
	v_add_f32_dpp v18, v18, v18 row_ror:4 row_mask:0xf bank_mask:0xf bound_ctrl:1
	v_readlane_b32 s4, v9, 63
	v_and_b32_e32 v15, 0xffff0000, v15
	v_add_f32_dpp v18, v18, v18 quad_perm:[2,3,0,1] row_mask:0xf bank_mask:0xf bound_ctrl:1
	v_fma_f32 v9, s4, v100, v99
	v_cmp_gt_f32_e32 vcc, s2, v9
	v_mul_f32_e32 v19, 0x4f800000, v9
	v_add_f32_dpp v18, v18, v18 quad_perm:[1,0,3,2] row_mask:0xf bank_mask:0xf bound_ctrl:1
	v_cndmask_b32_e32 v9, v9, v19, vcc
	v_sqrt_f32_e32 v19, v9
	s_nop 0
	v_add_u32_e32 v24, -1, v19
	v_fma_f32 v25, -v24, v19, v9
	v_cmp_ge_f32_e64 s[4:5], 0, v25
	v_add_u32_e32 v25, 1, v19
	s_nop 0
	v_cndmask_b32_e64 v24, v19, v24, s[4:5]
	v_fma_f32 v19, -v25, v19, v9
	v_cmp_lt_f32_e64 s[4:5], 0, v19
	s_nop 1
	v_cndmask_b32_e64 v19, v24, v25, s[4:5]
	v_mul_f32_e32 v24, 0x37800000, v19
	v_cndmask_b32_e32 v19, v19, v24, vcc
	v_cmp_class_f32_e32 vcc, v9, v101
	s_nop 1
	v_cndmask_b32_e32 v9, v19, v9, vcc
	v_mov_b32_e32 v19, v97
	s_nop 1
	s_nop 0
	s_nop 1
	v_add_f32_dpp v18, v18, v18 row_bcast:15 row_mask:0xa bank_mask:0xf
	v_mov_b32_e32 v19, v97
	s_nop 1
	s_nop 0
	v_add_f32_dpp v18, v18, v18 row_bcast:31 row_mask:0xc bank_mask:0xf
	s_nop 0
	v_readlane_b32 s4, v18, 63
	s_nop 1
	v_fma_f32 v18, s4, v100, v99
	v_cmp_gt_f32_e32 vcc, s2, v18
	v_mul_f32_e32 v19, 0x4f800000, v18
	s_nop 0
	v_cndmask_b32_e32 v18, v18, v19, vcc
	v_sqrt_f32_e32 v19, v18
	s_nop 0
	v_add_u32_e32 v24, -1, v19
	v_fma_f32 v25, -v24, v19, v18
	v_cmp_ge_f32_e64 s[4:5], 0, v25
	v_add_u32_e32 v25, 1, v19
	s_nop 0
	v_cndmask_b32_e64 v24, v19, v24, s[4:5]
	v_fma_f32 v19, -v25, v19, v18
	v_cmp_lt_f32_e64 s[4:5], 0, v19
	s_nop 1
	v_cndmask_b32_e64 v19, v24, v25, s[4:5]
	v_mul_f32_e32 v24, 0x37800000, v19
	v_cndmask_b32_e32 v19, v19, v24, vcc
	v_cmp_class_f32_e32 vcc, v18, v101
	s_nop 1
	v_cndmask_b32_e32 v18, v19, v18, vcc
	v_div_scale_f32 v19, s[4:5], v18, v18, 1.0
	v_rcp_f32_e32 v24, v19
	s_nop 0
	v_fma_f32 v25, -v19, v24, 1.0
	v_fmac_f32_e32 v24, v25, v24
	v_div_scale_f32 v25, vcc, 1.0, v18, 1.0
	v_mul_f32_e32 v30, v25, v24
	v_fma_f32 v31, -v19, v30, v25
	v_fmac_f32_e32 v30, v31, v24
	v_fma_f32 v19, -v19, v30, v25
	v_div_fmas_f32 v19, v19, v24, v30
	v_div_fixup_f32 v19, v19, v18, 1.0
	v_div_scale_f32 v18, s[4:5], v9, v9, 1.0
	v_rcp_f32_e32 v24, v18
	s_nop 0
	v_fma_f32 v25, -v18, v24, 1.0
	v_fmac_f32_e32 v24, v25, v24
	v_div_scale_f32 v25, vcc, 1.0, v9, 1.0
	v_mul_f32_e32 v30, v25, v24
	v_fma_f32 v31, -v18, v30, v25
	v_fmac_f32_e32 v30, v31, v24
	v_fma_f32 v18, -v18, v30, v25
	v_div_fmas_f32 v18, v18, v24, v30
	v_div_fixup_f32 v18, v18, v9, 1.0
	v_pk_mul_f32 v[24:25], v[18:19], v[36:37]
	v_pk_mul_f32 v[22:23], v[18:19], v[22:23]
	v_pk_mul_f32 v[24:25], v[6:7], v[24:25] op_sel_hi:[0,1]
	v_pk_mul_f32 v[20:21], v[18:19], v[20:21]
	v_cvt_pk_bf16_f32 v64, v24, v25
	v_pk_mul_f32 v[24:25], v[18:19], v[40:41]
	v_pk_mul_f32 v[22:23], v[96:97], v[22:23] op_sel_hi:[0,1]
	v_pk_mul_f32 v[20:21], v[2:3], v[20:21] op_sel:[1,0]
	v_pk_mul_f32 v[24:25], v[6:7], v[24:25] op_sel:[1,0]
	v_cvt_pk_bf16_f32 v52, v22, v23
	v_pk_mul_f32 v[22:23], v[18:19], v[44:45]
	v_cvt_pk_bf16_f32 v44, v20, v21
	v_mov_b32_e32 v20, v27
	v_mov_b32_e32 v21, v29
	v_mov_b32_e32 v27, v28
	v_and_b32_e32 v29, 0xffff0000, v14
	v_and_b32_e32 v28, 0xffff0000, v10
	v_cvt_pk_bf16_f32 v60, v24, v25
	v_pk_mul_f32 v[24:25], v[18:19], v[48:49]
	v_pk_mul_f32 v[20:21], v[18:19], v[20:21]
	v_pk_mul_f32 v[18:19], v[18:19], v[26:27]
	v_lshlrev_b32_e32 v27, 16, v14
	v_lshlrev_b32_e32 v26, 16, v10
	v_pk_mul_f32 v[30:31], v[28:29], v[28:29]
	v_and_b32_e32 v14, 0xffff0000, v11
	v_pk_fma_f32 v[30:31], v[26:27], v[26:27], v[30:31]
	v_pk_mul_f32 v[18:19], v[98:99], v[18:19] op_sel_hi:[0,1]
	v_pk_fma_f32 v[30:31], v[32:33], v[32:33], v[30:31]
	v_pk_mul_f32 v[22:23], v[2:3], v[22:23] op_sel_hi:[0,1]
	v_pk_fma_f32 v[10:11], v[14:15], v[14:15], v[30:31]
	v_lshlrev_b32_e32 v31, 16, v16
	v_lshlrev_b32_e32 v30, 16, v12
	v_cvt_pk_bf16_f32 v36, v18, v19
	v_and_b32_e32 v18, 0xffff0000, v13
	v_lshlrev_b32_e32 v19, 16, v13
	v_pk_fma_f32 v[10:11], v[30:31], v[30:31], v[10:11]
	v_and_b32_e32 v13, 0xffff0000, v16
	v_and_b32_e32 v12, 0xffff0000, v12
	v_cvt_pk_bf16_f32 v48, v22, v23
	v_pk_mul_f32 v[22:23], v[18:19], v[18:19]
	v_pk_fma_f32 v[10:11], v[12:13], v[12:13], v[10:11]
	v_pk_mul_f32 v[24:25], v[8:9], v[24:25] op_sel_hi:[0,1]
	v_add_f32_e32 v9, v23, v10
	v_add_f32_e32 v9, v22, v9
	v_pk_mul_f32 v[20:21], v[4:5], v[20:21] op_sel_hi:[0,1]
	v_cvt_pk_bf16_f32 v40, v20, v21
	v_add_f32_dpp v9, v9, v9 row_ror:8 row_mask:0xf bank_mask:0xf bound_ctrl:1
	v_and_b32_e32 v20, 0xffff0000, v17
	v_lshlrev_b32_e32 v21, 16, v17
	v_add_f32_dpp v9, v9, v9 row_ror:4 row_mask:0xf bank_mask:0xf bound_ctrl:1
	v_cvt_pk_bf16_f32 v56, v24, v25
	v_pk_mul_f32 v[24:25], v[20:21], v[20:21]
	v_add_f32_dpp v9, v9, v9 quad_perm:[2,3,0,1] row_mask:0xf bank_mask:0xf bound_ctrl:1
	v_add_f32_e32 v10, v25, v11
	v_mov_b32_e32 v11, v97
	v_add_f32_dpp v9, v9, v9 quad_perm:[1,0,3,2] row_mask:0xf bank_mask:0xf bound_ctrl:1
	v_add_f32_e32 v10, v24, v10
	s_nop 0
	s_nop 0
	v_add_f32_dpp v9, v9, v9 row_bcast:15 row_mask:0xa bank_mask:0xf
	v_mov_b32_e32 v11, v97
	v_add_f32_dpp v10, v10, v10 row_ror:8 row_mask:0xf bank_mask:0xf bound_ctrl:1
	s_nop 0
	s_nop 0
	v_add_f32_dpp v9, v9, v9 row_bcast:31 row_mask:0xc bank_mask:0xf
	v_add_f32_dpp v10, v10, v10 row_ror:4 row_mask:0xf bank_mask:0xf bound_ctrl:1
	v_readlane_b32 s4, v9, 63
	s_nop 0
	v_add_f32_dpp v10, v10, v10 quad_perm:[2,3,0,1] row_mask:0xf bank_mask:0xf bound_ctrl:1
	v_fma_f32 v9, s4, v100, v99
	v_cmp_gt_f32_e32 vcc, s2, v9
	v_mul_f32_e32 v11, 0x4f800000, v9
	v_add_f32_dpp v10, v10, v10 quad_perm:[1,0,3,2] row_mask:0xf bank_mask:0xf bound_ctrl:1
	v_cndmask_b32_e32 v9, v9, v11, vcc
	v_sqrt_f32_e32 v11, v9
	s_nop 0
	v_add_u32_e32 v16, -1, v11
	v_fma_f32 v17, -v16, v11, v9
	v_cmp_ge_f32_e64 s[4:5], 0, v17
	v_add_u32_e32 v17, 1, v11
	s_nop 0
	v_cndmask_b32_e64 v16, v11, v16, s[4:5]
	v_fma_f32 v11, -v17, v11, v9
	v_cmp_lt_f32_e64 s[4:5], 0, v11
	s_nop 1
	v_cndmask_b32_e64 v11, v16, v17, s[4:5]
	v_mul_f32_e32 v16, 0x37800000, v11
	v_cndmask_b32_e32 v11, v11, v16, vcc
	v_cmp_class_f32_e32 vcc, v9, v101
	s_nop 1
	v_cndmask_b32_e32 v9, v11, v9, vcc
	v_mov_b32_e32 v11, v97
	s_nop 1
	s_nop 0
	s_nop 1
	v_add_f32_dpp v10, v10, v10 row_bcast:15 row_mask:0xa bank_mask:0xf
	v_mov_b32_e32 v11, v97
	s_nop 1
	s_nop 0
	v_add_f32_dpp v10, v10, v10 row_bcast:31 row_mask:0xc bank_mask:0xf
	s_nop 0
	v_readlane_b32 s4, v10, 63
	s_nop 1
	v_fma_f32 v10, s4, v100, v99
	v_cmp_gt_f32_e32 vcc, s2, v10
	v_mul_f32_e32 v11, 0x4f800000, v10
	s_nop 0
	v_cndmask_b32_e32 v10, v10, v11, vcc
	v_sqrt_f32_e32 v11, v10
	s_nop 0
	v_add_u32_e32 v16, -1, v11
	v_fma_f32 v17, -v16, v11, v10
	v_cmp_ge_f32_e64 s[4:5], 0, v17
	v_add_u32_e32 v17, 1, v11
	s_nop 0
	v_cndmask_b32_e64 v16, v11, v16, s[4:5]
	v_fma_f32 v11, -v17, v11, v10
	v_cmp_lt_f32_e64 s[4:5], 0, v11
	s_nop 1
	v_cndmask_b32_e64 v11, v16, v17, s[4:5]
	v_mul_f32_e32 v16, 0x37800000, v11
	v_cndmask_b32_e32 v11, v11, v16, vcc
	v_cmp_class_f32_e32 vcc, v10, v101
	s_nop 1
	v_cndmask_b32_e32 v10, v11, v10, vcc
	v_div_scale_f32 v11, s[4:5], v10, v10, 1.0
	v_rcp_f32_e32 v16, v11
	s_nop 0
	v_fma_f32 v17, -v11, v16, 1.0
	v_fmac_f32_e32 v16, v17, v16
	v_div_scale_f32 v17, vcc, 1.0, v10, 1.0
	v_mul_f32_e32 v22, v17, v16
	v_fma_f32 v23, -v11, v22, v17
	v_fmac_f32_e32 v22, v23, v16
	v_fma_f32 v11, -v11, v22, v17
	v_div_fmas_f32 v11, v11, v16, v22
	v_div_fixup_f32 v11, v11, v10, 1.0
	v_div_scale_f32 v10, s[4:5], v9, v9, 1.0
	v_rcp_f32_e32 v16, v10
	s_cselect_b64 s[4:5], -1, 0
	s_cmpk_gt_u32 s16, 0xff
	s_cselect_b64 s[14:15], -1, 0
	v_fma_f32 v17, -v10, v16, 1.0
	v_fmac_f32_e32 v16, v17, v16
	v_div_scale_f32 v17, vcc, 1.0, v9, 1.0
	v_mul_f32_e32 v22, v17, v16
	v_fma_f32 v23, -v10, v22, v17
	v_fmac_f32_e32 v22, v23, v16
	v_fma_f32 v10, -v10, v22, v17
	v_div_fmas_f32 v10, v10, v16, v22
	v_div_fixup_f32 v10, v10, v9, 1.0
	v_pk_mul_f32 v[16:17], v[10:11], v[26:27]
	s_cmpk_gt_u32 s16, 0x17f
	v_pk_mul_f32 v[16:17], v[6:7], v[16:17] op_sel_hi:[0,1]
	v_cvt_pk_bf16_f32 v65, v16, v17
	v_pk_mul_f32 v[16:17], v[10:11], v[28:29]
	v_or_b32_e32 v29, 12, v104
	v_pk_mul_f32 v[6:7], v[6:7], v[16:17] op_sel:[1,0]
	ds_write_b128 v5, v[62:65]
	v_cvt_pk_bf16_f32 v61, v6, v7
	v_pk_mul_f32 v[6:7], v[10:11], v[32:33]
	ds_write_b128 v5, v[58:61] offset:272
	v_pk_mul_f32 v[6:7], v[8:9], v[6:7] op_sel_hi:[0,1]
	v_cvt_pk_bf16_f32 v57, v6, v7
	v_pk_mul_f32 v[6:7], v[10:11], v[14:15]
	ds_write_b128 v5, v[54:57] offset:544
	v_pk_mul_f32 v[6:7], v[96:97], v[6:7] op_sel_hi:[0,1]
	v_cvt_pk_bf16_f32 v53, v6, v7
	v_pk_mul_f32 v[6:7], v[10:11], v[30:31]
	ds_write_b128 v5, v[50:53] offset:816
	v_pk_mul_f32 v[6:7], v[2:3], v[6:7] op_sel_hi:[0,1]
	v_cvt_pk_bf16_f32 v49, v6, v7
	v_pk_mul_f32 v[6:7], v[10:11], v[12:13]
	v_or_b32_e32 v13, 4, v104
	v_pk_mul_f32 v[2:3], v[2:3], v[6:7] op_sel:[1,0]
	ds_write_b128 v5, v[46:49] offset:1088
	v_cvt_pk_bf16_f32 v45, v2, v3
	v_mov_b32_e32 v2, v19
	v_mov_b32_e32 v3, v21
	v_pk_mul_f32 v[2:3], v[10:11], v[2:3]
	v_mov_b32_e32 v19, v20
	v_pk_mul_f32 v[2:3], v[4:5], v[2:3] op_sel_hi:[0,1]
	v_cvt_pk_bf16_f32 v41, v2, v3
	v_pk_mul_f32 v[2:3], v[10:11], v[18:19]
	v_or_b32_e32 v21, 8, v104
	v_pk_mul_f32 v[2:3], v[98:99], v[2:3] op_sel_hi:[0,1]
	v_cvt_pk_bf16_f32 v37, v2, v3
	v_bfe_u32 v2, v102, 3, 1
	ds_write_b128 v5, v[42:45] offset:1360
	ds_write_b128 v5, v[38:41] offset:1632
	ds_write_b128 v5, v[34:37] offset:1904
	v_xor_b32_e32 v4, v2, v104
	v_bitop3_b32 v5, v2, v104, 2 bitop3:0x36
	v_bitop3_b32 v7, v2, v104, 4 bitop3:0x36
	v_bitop3_b32 v8, v2, v104, 6 bitop3:0x36
	v_bitop3_b32 v9, v2, v104, 8 bitop3:0x36
	v_bitop3_b32 v10, v2, v104, 10 bitop3:0x36
	v_bitop3_b32 v11, v2, v104, 12 bitop3:0x36
	v_bitop3_b32 v12, v2, v104, 14 bitop3:0x36
	v_bitop3_b32 v14, v104, v2, 4 bitop3:0x36
	v_bitop3_b32 v15, v2, v13, 2 bitop3:0x36
	v_bitop3_b32 v16, v2, v104, 4 bitop3:0x14
	v_bitop3_b32 v17, v2, v13, 6 bitop3:0x36
	v_bitop3_b32 v18, v2, v13, 8 bitop3:0x36
	v_bitop3_b32 v19, v2, v13, 10 bitop3:0x36
	v_bitop3_b32 v20, v2, v13, 12 bitop3:0x36
	v_bitop3_b32 v13, v2, v13, 14 bitop3:0x36
	v_bitop3_b32 v22, v104, v2, 8 bitop3:0x36
	v_bitop3_b32 v23, v2, v21, 2 bitop3:0x36
	v_bitop3_b32 v24, v2, v21, 4 bitop3:0x36
	v_bitop3_b32 v25, v2, v21, 6 bitop3:0x36
	v_bitop3_b32 v26, v2, v104, 8 bitop3:0x14
	v_bitop3_b32 v27, v2, v21, 10 bitop3:0x36
	v_bitop3_b32 v28, v2, v21, 12 bitop3:0x36
	v_bitop3_b32 v21, v2, v21, 14 bitop3:0x36
	v_bitop3_b32 v30, v104, v2, 12 bitop3:0x36
	v_bitop3_b32 v31, v2, v29, 2 bitop3:0x36
	v_bitop3_b32 v32, v2, v29, 4 bitop3:0x36
	v_bitop3_b32 v33, v2, v29, 6 bitop3:0x36
	v_bitop3_b32 v34, v2, v29, 8 bitop3:0x36
	v_bitop3_b32 v35, v2, v29, 10 bitop3:0x36
	v_bitop3_b32 v36, v2, v104, 12 bitop3:0x14
	v_bitop3_b32 v2, v2, v29, 14 bitop3:0x36
	v_mul_u32_u24_e32 v3, 0x110, v103
	v_lshlrev_b32_e32 v4, 4, v4
	v_lshlrev_b32_e32 v5, 4, v5
	v_lshlrev_b32_e32 v7, 4, v7
	v_lshlrev_b32_e32 v8, 4, v8
	v_lshlrev_b32_e32 v9, 4, v9
	v_lshlrev_b32_e32 v10, 4, v10
	v_lshlrev_b32_e32 v11, 4, v11
	v_lshlrev_b32_e32 v12, 4, v12
	v_lshlrev_b32_e32 v14, 4, v14
	v_lshlrev_b32_e32 v15, 4, v15
	v_lshlrev_b32_e32 v16, 4, v16
	v_lshlrev_b32_e32 v17, 4, v17
	v_lshlrev_b32_e32 v18, 4, v18
	v_lshlrev_b32_e32 v19, 4, v19
	v_lshlrev_b32_e32 v20, 4, v20
	v_lshlrev_b32_e32 v13, 4, v13
	v_lshlrev_b32_e32 v22, 4, v22
	v_lshlrev_b32_e32 v23, 4, v23
	v_lshlrev_b32_e32 v24, 4, v24
	v_lshlrev_b32_e32 v25, 4, v25
	v_lshlrev_b32_e32 v26, 4, v26
	v_lshlrev_b32_e32 v27, 4, v27
	v_lshlrev_b32_e32 v28, 4, v28
	v_lshlrev_b32_e32 v21, 4, v21
	v_lshlrev_b32_e32 v30, 4, v30
	v_lshlrev_b32_e32 v31, 4, v31
	v_lshlrev_b32_e32 v32, 4, v32
	v_lshlrev_b32_e32 v33, 4, v33
	v_lshlrev_b32_e32 v34, 4, v34
	v_lshlrev_b32_e32 v35, 4, v35
	v_lshlrev_b32_e32 v36, 4, v36
	v_lshlrev_b32_e32 v2, 4, v2
	v_or_b32_e32 v96, s25, v103
	v_lshlrev_b32_e32 v6, 3, v104
	v_add3_u32 v51, v3, v2, s3
	v_add3_u32 v70, v3, v36, s18
	v_add3_u32 v71, v3, v35, s19
	v_add3_u32 v72, v3, v34, s20
	v_add3_u32 v73, v3, v33, s21
	v_add3_u32 v74, v3, v32, s22
	v_add3_u32 v75, v3, v31, s23
	v_add3_u32 v76, v3, v21, s3
	v_add3_u32 v77, v3, v28, s18
	v_add3_u32 v78, v3, v27, s19
	v_add3_u32 v79, v3, v26, s20
	v_add3_u32 v80, v3, v25, s21
	v_add3_u32 v81, v3, v24, s22
	v_add3_u32 v82, v3, v23, s23
	v_add3_u32 v83, v3, v13, s3
	v_add3_u32 v84, v3, v20, s18
	v_add3_u32 v85, v3, v19, s19
	v_add3_u32 v86, v3, v18, s20
	v_add3_u32 v87, v3, v17, s21
	v_add3_u32 v88, v3, v16, s22
	v_add3_u32 v89, v3, v15, s23
	v_add3_u32 v90, v3, v12, s3
	v_add3_u32 v91, v3, v11, s18
	v_add3_u32 v92, v3, v10, s19
	v_add3_u32 v93, v3, v9, s20
	v_add3_u32 v94, v3, v8, s21
	v_add3_u32 v95, v3, v7, s22
	v_add3_u32 v98, v3, v5, s23
	v_add3_u32 v104, v3, v4, 0
	v_add3_u32 v105, v3, v30, 0
	v_add3_u32 v106, v3, v22, 0
	v_add3_u32 v107, v3, v14, 0
	v_lshlrev_b32_e32 v2, 2, v96
	v_mov_b32_e32 v3, v97
	v_lshl_add_u64 v[42:43], s[50:51], 0, v[2:3]
	v_lshl_add_u64 v[2:3], s[12:13], 0, v[96:97]
	v_lshlrev_b64 v[4:5], 11, v[2:3]
	v_lshlrev_b64 v[2:3], 12, v[2:3]
	v_lshlrev_b64 v[44:45], 8, v[96:97]
	v_or_b32_e32 v4, v4, v6
	v_or_b32_e32 v2, v2, v6
	s_mov_b64 s[12:13], 0x6b00880
	s_cselect_b64 s[16:17], -1, 0
	v_and_or_b32 v44, v102, 48, v44
	v_lshl_add_u64 v[46:47], s[8:9], 0, v[4:5]
	v_lshl_add_u64 v[48:49], v[2:3], 0, s[12:13]
	s_mov_b32 s12, 0
	s_waitcnt lgkmcnt(0)
	s_barrier
	s_branch .LBB0_1163

.LBB0_1178:
	s_sub_i32 s0, s14, s41
	s_addk_i32 s0, 0xff80
	v_readfirstlane_b32 s1, v0
	s_ashr_i32 s6, s0, 1
	s_lshl_b32 s0, s14, 2
	s_and_b32 s0, s0, 4
	s_lshr_b32 s46, s1, 7
	s_lshr_b32 s45, s1, 6
	s_add_i32 s46, s46, s0
	s_mul_i32 s0, s45, 0x2840
	s_and_b32 s42, s1, 64
	s_lshl_b32 s43, s46, 7
	v_mov_b32_e32 v130, v0
	s_add_i32 s44, s0, 0
	s_or_b32 s0, s43, s42
	s_addk_i32 s0, 0x800
	v_and_b32_e32 v131, 63, v130
	v_readlane_b32 s12, v245, 6
	s_lshl_b32 s47, s6, 3
	s_waitcnt vmcnt(24)
	v_lshlrev_b32_e32 v37, 1, v131
	v_or_b32_e32 v4, s0, v131
	s_mul_i32 s0, s6, 0x9000
	v_readlane_b32 s18, v245, 12
	v_or_b32_e32 v162, s43, v37
	s_mul_hi_i32 s1, s6, 0x9000
	v_readlane_b32 s19, v245, 13
	s_add_u32 s0, s18, s0
	s_addc_u32 s1, s19, s1
	v_lshlrev_b64 v[2:3], 2, v[162:163]
	v_lshl_add_u64 v[6:7], s[0:1], 0, v[2:3]
	s_barrier
	global_load_dwordx2 v[28:29], v[6:7], off
	v_add_co_u32_e32 v6, vcc, s76, v6
	v_mov_b32_e32 v5, v163
	s_nop 0
	v_addc_co_u32_e32 v7, vcc, 0, v7, vcc
	global_load_dwordx2 v[26:27], v[6:7], off
	v_lshlrev_b64 v[6:7], 2, v[4:5]
	s_add_u32 s4, s0, 0x3000
	v_lshl_add_u64 v[8:9], s[0:1], 0, v[6:7]
	s_addc_u32 s5, s1, 0
	global_load_dword v58, v[8:9], off
	v_lshl_add_u64 v[8:9], s[4:5], 0, v[2:3]
	global_load_dwordx2 v[24:25], v[8:9], off
	v_add_co_u32_e32 v8, vcc, s76, v8
	s_add_u32 s0, s0, 0x6000
	s_nop 0
	v_addc_co_u32_e32 v9, vcc, 0, v9, vcc
	global_load_dwordx2 v[22:23], v[8:9], off
	v_lshl_add_u64 v[8:9], s[4:5], 0, v[6:7]
	s_addc_u32 s1, s1, 0
	global_load_dword v56, v[8:9], off
	v_lshl_add_u64 v[8:9], s[0:1], 0, v[2:3]
	global_load_dwordx2 v[20:21], v[8:9], off
	v_add_co_u32_e32 v8, vcc, s76, v8
	v_readlane_b32 s26, v245, 20
	s_nop 0
	v_addc_co_u32_e32 v9, vcc, 0, v9, vcc
	v_readlane_b32 s27, v245, 21
	global_load_dwordx2 v[18:19], v[8:9], off
	v_lshl_add_u64 v[8:9], s[0:1], 0, v[6:7]
	s_mul_i32 s0, s6, 0xc000
	s_add_i32 s26, s47, 0x4000
	s_ashr_i32 s27, s26, 31
	s_add_i32 s1, s0, 0x6000000
	s_mul_hi_i32 s5, s26, 0x1800
	s_add_u32 s4, s82, s1
	s_addc_u32 s5, s83, s5
	v_lshlrev_b32_e32 v10, 1, v162
	global_load_dword v57, v[8:9], off
	s_nop 0
	global_load_dword v8, v10, s[4:5]
	global_load_dword v9, v10, s[4:5] offset:2048
	v_lshlrev_b64 v[4:5], 1, v[4:5]
	v_readlane_b32 s24, v245, 18
	s_add_i32 s24, s47, 0x4001
	v_readlane_b32 s22, v245, 16
	s_mul_hi_i32 s1, s24, 0x1800
	v_readlane_b32 s20, v245, 14
	v_readlane_b32 s16, v245, 10
	v_readlane_b32 s56, v245, 26
	v_readlane_b32 s14, v245, 8
	v_readlane_b32 s58, v245, 28
	v_readlane_b32 s59, v245, 29
	v_mov_b32_e32 v67, v163
	v_readlane_b32 s60, v245, 30
	v_lshl_add_u64 v[14:15], s[58:59], 0, v[2:3]
	v_add_co_u32_e32 v2, vcc, s76, v14
	v_lshl_add_u64 v[64:65], s[58:59], 0, v[6:7]
	s_nop 0
	v_addc_co_u32_e32 v3, vcc, 0, v15, vcc
	v_add_co_u32_e32 v6, vcc, s96, v14
	v_readlane_b32 s61, v245, 31
	s_nop 0
	v_addc_co_u32_e32 v7, vcc, 0, v15, vcc
	v_readlane_b32 s62, v245, 32
	v_mov_b32_e32 v68, v163
	v_readlane_b32 s63, v245, 33
	v_readlane_b32 s13, v245, 7
	v_readlane_b32 s15, v245, 9
	v_readlane_b32 s17, v245, 11
	v_readlane_b32 s21, v245, 15
	v_readlane_b32 s23, v245, 17
	v_readlane_b32 s25, v245, 19
	v_readlane_b32 s57, v245, 27
	v_readlane_b32 s64, v245, 34
	v_readlane_b32 s65, v245, 35
	v_readlane_b32 s66, v245, 36
	v_readlane_b32 s67, v245, 37
	v_readlane_b32 s68, v245, 38
	v_readlane_b32 s69, v245, 39
	v_readlane_b32 s70, v245, 40
	v_readlane_b32 s71, v245, 41
	s_waitcnt vmcnt(1)
	v_lshlrev_b32_e32 v51, 16, v8
	v_and_b32_e32 v48, 0xffff0000, v8
	s_waitcnt vmcnt(0)
	v_lshlrev_b32_e32 v50, 16, v9
	v_and_b32_e32 v47, 0xffff0000, v9
	v_lshl_add_u64 v[8:9], s[4:5], 0, v[4:5]
	global_load_ushort v8, v[8:9], off
	s_mul_i32 s4, s24, 0x1800
	s_add_u32 s4, s82, s4
	s_addc_u32 s5, s83, s1
	s_add_i32 s22, s47, 0x4002
	s_add_i32 s1, s0, 0x6003000
	global_load_dword v63, v10, s[4:5]
	global_load_dword v62, v10, s[4:5] offset:2048
	s_waitcnt vmcnt(2)
	v_lshlrev_b32_e32 v49, 16, v8
	v_lshl_add_u64 v[8:9], s[4:5], 0, v[4:5]
	s_mul_hi_i32 s5, s22, 0x1800
	s_add_u32 s4, s82, s1
	s_addc_u32 s5, s83, s5
	s_add_i32 s20, s47, 0x4003
	s_add_i32 s1, s0, 0x6004800
	global_load_ushort v59, v[8:9], off
	global_load_dword v55, v10, s[4:5]
	global_load_dword v61, v10, s[4:5] offset:2048
	v_lshl_add_u64 v[8:9], s[4:5], 0, v[4:5]
	s_mul_hi_i32 s5, s20, 0x1800
	s_add_u32 s4, s82, s1
	s_addc_u32 s5, s83, s5
	s_add_i32 s18, s47, 0x4004
	s_add_i32 s1, s0, 0x6006000
	global_load_ushort v60, v[8:9], off
	global_load_dword v54, v10, s[4:5]
	global_load_dword v53, v10, s[4:5] offset:2048
	v_lshl_add_u64 v[8:9], s[4:5], 0, v[4:5]
	s_mul_hi_i32 s5, s18, 0x1800
	s_add_u32 s4, s82, s1
	s_addc_u32 s5, s83, s5
	s_add_i32 s16, s47, 0x4005
	s_add_i32 s1, s0, 0x6007800
	global_load_ushort v52, v[8:9], off
	global_load_dword v46, v10, s[4:5]
	global_load_dword v45, v10, s[4:5] offset:2048
	v_lshl_add_u64 v[8:9], s[4:5], 0, v[4:5]
	s_mul_hi_i32 s5, s16, 0x1800
	s_add_u32 s4, s82, s1
	s_addc_u32 s5, s83, s5
	s_add_i32 s14, s47, 0x4006
	s_add_i32 s1, s0, 0x6009000
	global_load_ushort v44, v[8:9], off
	global_load_dword v43, v10, s[4:5]
	global_load_dword v42, v10, s[4:5] offset:2048
	v_lshl_add_u64 v[8:9], s[4:5], 0, v[4:5]
	s_mul_hi_i32 s5, s14, 0x1800
	s_add_u32 s4, s82, s1
	s_addc_u32 s5, s83, s5
	s_add_i32 s12, s47, 0x4007
	s_add_i32 s0, s0, 0x600a800
	s_mul_hi_i32 s1, s12, 0x1800
	s_add_u32 s0, s82, s0
	global_load_ushort v41, v[8:9], off
	v_lshl_add_u64 v[8:9], s[4:5], 0, v[4:5]
	s_addc_u32 s1, s83, s1
	global_load_dword v40, v10, s[4:5]
	global_load_dword v39, v10, s[4:5] offset:2048
	global_load_ushort v38, v[8:9], off
	global_load_dword v32, v10, s[0:1]
	global_load_dword v31, v10, s[0:1] offset:2048
	v_add_co_u32_e32 v10, vcc, s97, v64
	v_lshl_add_u64 v[4:5], s[0:1], 0, v[4:5]
	s_nop 0
	v_addc_co_u32_e32 v11, vcc, 0, v65, vcc
	global_load_ushort v30, v[4:5], off
	global_load_dword v33, v[64:65], off
	s_lshl_b32 s0, s46, 2
	global_load_dwordx2 v[4:5], v[14:15], off
	s_add_u32 s48, s86, s0
	global_load_dwordx2 v[2:3], v[2:3], off
	s_nop 0
	global_load_dwordx2 v[8:9], v[6:7], off offset:-4096
	s_nop 0
	global_load_dwordx2 v[6:7], v[6:7], off
	s_addc_u32 s49, s87, 0
	global_load_dword v34, v[10:11], off
	v_add_co_u32_e32 v10, vcc, s85, v14
	s_add_u32 s28, s60, s0
	s_nop 0
	v_addc_co_u32_e32 v11, vcc, 0, v15, vcc
	v_add_co_u32_e32 v16, vcc, s84, v64
	global_load_dwordx2 v[12:13], v[10:11], off offset:-4096
	s_nop 0
	global_load_dwordx2 v[10:11], v[10:11], off
	v_addc_co_u32_e32 v17, vcc, 0, v65, vcc
	global_load_dword v35, v[16:17], off
	v_add_co_u32_e32 v16, vcc, s80, v14
	s_addc_u32 s29, s61, 0
	s_nop 0
	v_addc_co_u32_e32 v17, vcc, 0, v15, vcc
	global_load_dwordx2 v[14:15], v[16:17], off offset:-4096
	s_nop 0
	global_load_dwordx2 v[16:17], v[16:17], off
	v_add_co_u32_e32 v64, vcc, s75, v64
	s_add_u32 s6, s62, s0
	s_nop 0
	v_addc_co_u32_e32 v65, vcc, 0, v65, vcc
	global_load_dword v36, v[64:65], off
	v_and_b32_e32 v64, 0x7c, v37
	v_lshl_add_u32 v37, v131, 2, s44
	v_cmp_eq_u32_e64 s[4:5], 0, v131
	s_addc_u32 s7, s63, 0
	s_waitcnt vmcnt(8)
	v_mul_f32_e32 v65, v24, v8
	v_fmac_f32_e32 v65, v28, v4
	s_waitcnt vmcnt(6)
	v_mul_f32_e32 v66, v56, v34
	v_fmac_f32_e32 v66, v58, v33
	s_waitcnt vmcnt(5)
	v_fmac_f32_e32 v65, v20, v12
	s_waitcnt vmcnt(3)
	v_fmac_f32_e32 v66, v57, v35
	s_waitcnt vmcnt(2)
	v_fmac_f32_e32 v65, v14, v51
	v_mul_f32_e32 v28, 0xbfb8aa3b, v65
	v_exp_f32_e32 v28, v28
	s_waitcnt vmcnt(0)
	v_fmac_f32_e32 v66, v36, v49
	v_add_f32_e32 v28, 1.0, v28
	v_rcp_f32_e32 v28, v28
	s_nop 0
	v_mul_f32_e32 v65, v65, v28
	v_mul_f32_e32 v28, v22, v6
	v_fmac_f32_e32 v28, v26, v2
	v_fmac_f32_e32 v28, v18, v10
	v_fmac_f32_e32 v28, v16, v50
	v_mul_f32_e32 v26, 0xbfb8aa3b, v28
	v_exp_f32_e32 v26, v26
	s_nop 0
	v_add_f32_e32 v26, 1.0, v26
	v_rcp_f32_e32 v26, v26
	s_nop 0
	v_mul_f32_e32 v26, v28, v26
	v_mul_f32_e32 v28, v25, v9
	v_fmac_f32_e32 v28, v29, v5
	v_fmac_f32_e32 v28, v21, v13
	v_fmac_f32_e32 v28, v15, v48
	v_mul_f32_e32 v29, 0xbfb8aa3b, v28
	v_exp_f32_e32 v29, v29
	s_nop 0
	v_add_f32_e32 v29, 1.0, v29
	v_rcp_f32_e32 v29, v29
	s_nop 0
	v_mul_f32_e32 v29, v28, v29
	v_mul_f32_e32 v28, v23, v7
	v_fmac_f32_e32 v28, v27, v3
	v_fmac_f32_e32 v28, v19, v11
	v_fmac_f32_e32 v28, v17, v47
	v_mul_f32_e32 v27, 0xbfb8aa3b, v28
	v_exp_f32_e32 v27, v27
	s_nop 0
	v_add_f32_e32 v27, 1.0, v27
	v_rcp_f32_e32 v27, v27
	s_nop 0
	v_mul_f32_e32 v27, v28, v27
	v_mul_f32_e32 v28, 0xbfb8aa3b, v66
	v_exp_f32_e32 v28, v28
	s_nop 0
	v_add_f32_e32 v28, 1.0, v28
	v_rcp_f32_e32 v58, v28
	v_mul_f32_e32 v28, v29, v29
	v_fmac_f32_e32 v28, v65, v65
	s_nop 1
	v_add_f32_dpp v28, v28, v28 row_ror:8 row_mask:0xf bank_mask:0xf bound_ctrl:1
	s_nop 1
	v_add_f32_dpp v28, v28, v28 row_ror:4 row_mask:0xf bank_mask:0xf bound_ctrl:1
	s_nop 1
	v_add_f32_dpp v28, v28, v28 quad_perm:[2,3,0,1] row_mask:0xf bank_mask:0xf bound_ctrl:1
	s_nop 1
	v_add_f32_dpp v28, v28, v28 quad_perm:[1,0,3,2] row_mask:0xf bank_mask:0xf bound_ctrl:1
	s_nop 1
	s_nop 0
	v_add_f32_dpp v28, v28, v28 row_bcast:15 row_mask:0xa bank_mask:0xf
	v_mov_b32_e32 v67, v163
	s_nop 1
	s_nop 0
	v_add_f32_dpp v28, v28, v28 row_bcast:31 row_mask:0xc bank_mask:0xf
	s_nop 0
	v_readlane_b32 s0, v28, 63
	s_nop 1
	v_add_f32_e32 v28, s0, v171
	v_rsq_f32_e32 v28, v28
	s_nop 0
	v_mul_f32_e32 v67, 0x3db504f3, v28
	v_mul_f32_e32 v28, v27, v27
	v_fmac_f32_e32 v28, v26, v26
	s_nop 1
	v_add_f32_dpp v28, v28, v28 row_ror:8 row_mask:0xf bank_mask:0xf bound_ctrl:1
	s_nop 1
	v_add_f32_dpp v28, v28, v28 row_ror:4 row_mask:0xf bank_mask:0xf bound_ctrl:1
	s_nop 1
	v_add_f32_dpp v28, v28, v28 quad_perm:[2,3,0,1] row_mask:0xf bank_mask:0xf bound_ctrl:1
	s_nop 1
	v_add_f32_dpp v28, v28, v28 quad_perm:[1,0,3,2] row_mask:0xf bank_mask:0xf bound_ctrl:1
	s_nop 1
	s_nop 0
	v_add_f32_dpp v28, v28, v28 row_bcast:15 row_mask:0xa bank_mask:0xf
	v_mov_b32_e32 v68, v163
	s_nop 1
	s_nop 0
	v_add_f32_dpp v28, v28, v28 row_bcast:31 row_mask:0xc bank_mask:0xf
	s_nop 0
	v_readlane_b32 s0, v28, 63
	s_nop 1
	v_add_f32_e32 v28, s0, v171
	v_rsq_f32_e32 v68, v28
	v_lshlrev_b32_e32 v28, 8, v130
	v_and_b32_e32 v28, 0x100, v28
	v_add3_u32 v28, s44, v64, v28
	v_mul_f32_e32 v26, v26, v68
	v_mul_f32_e32 v27, v27, v68
	v_mul_f32_e32 v64, v65, v67
	ds_write2_b32 v28, v26, v27 offset1:32
	v_mul_f32_e32 v26, v29, v67
	ds_write2_b32 v28, v64, v26 offset0:128 offset1:160
	v_mul_f32_e32 v26, v66, v58
	ds_write_b32 v37, v26 offset:8192
	s_mov_b64 s[0:1], exec
	s_mov_b64 exec, 0xff
	s_cbranch_execz .LBB0_1180
	s_lshl_b64 s[30:31], s[26:27], 6
	s_add_u32 s30, s48, s30
	s_addc_u32 s31, s49, s31
	v_mbcnt_lo_u32_b32 v230, -1, 0
	v_lshlrev_b32_e32 v230, 6, v230
	global_load_dword v26, v230, s[30:31]
	global_load_dword v231, v163, s[28:29]
	global_load_dword v232, v230, s[30:31] offset:32
	global_load_dword v233, v163, s[6:7]
	s_waitcnt vmcnt(0)
	v_mul_f32_e32 v27, 0xbfb8aa3b, v26
	v_fma_f32 v29, v26, s81, -v27
	v_rndne_f32_e32 v58, v27
	v_fmac_f32_e32 v29, 0xb2a5705f, v26
	v_sub_f32_e32 v27, v27, v58
	v_add_f32_e32 v27, v27, v29
	v_exp_f32_e32 v27, v27
	v_cvt_i32_f32_e32 v29, v58
	v_cmp_nlt_f32_e32 vcc, s3, v26
	v_ldexp_f32 v27, v27, v29
	s_nop 0
	v_cndmask_b32_e32 v27, 0, v27, vcc
	v_cmp_ngt_f32_e32 vcc, s2, v26
	s_nop 1
	v_cndmask_b32_e32 v26, v179, v27, vcc
	v_add_f32_e32 v26, 1.0, v26
	v_div_scale_f32 v27, s[50:51], v26, v26, 1.0
	v_rcp_f32_e32 v29, v27
	s_nop 0
	v_fma_f32 v58, -v27, v29, 1.0
	v_fmac_f32_e32 v29, v58, v29
	v_div_scale_f32 v58, vcc, 1.0, v26, 1.0
	v_mul_f32_e32 v64, v58, v29
	v_fma_f32 v65, -v27, v64, v58
	v_fmac_f32_e32 v64, v65, v29
	v_fma_f32 v27, -v27, v64, v58
	v_div_fmas_f32 v27, v27, v29, v64
	v_div_fixup_f32 v26, v27, v26, 1.0
	v_mov_b32_e32 v27, v231
	s_waitcnt vmcnt(0)
	v_mul_f32_e32 v29, 0x3fb8aa3b, v27
	v_fma_f32 v58, v27, s38, -v29
	v_rndne_f32_e32 v64, v29
	v_fmac_f32_e32 v58, 0x32a5705f, v27
	v_sub_f32_e32 v29, v29, v64
	v_add_f32_e32 v29, v29, v58
	v_exp_f32_e32 v29, v29
	v_cvt_i32_f32_e32 v58, v64
	v_cmp_ngt_f32_e32 vcc, s39, v27
	v_ldexp_f32 v29, v29, v58
	s_nop 0
	v_cndmask_b32_e32 v29, 0, v29, vcc
	v_cmp_nlt_f32_e32 vcc, s78, v27
	s_nop 1
	v_cndmask_b32_e32 v27, v179, v29, vcc
	v_mov_b32_e32 v29, v232
	v_mov_b32_e32 v58, v233
	s_waitcnt vmcnt(0)
	v_add_f32_e32 v58, v29, v58
	v_mul_f32_e64 v64, |v58|, s81
	v_fma_f32 v65, |v58|, s81, -v64
	v_rndne_f32_e32 v66, v64
	v_fma_f32 v65, |v58|, s33, v65
	v_sub_f32_e32 v64, v64, v66
	v_add_f32_e32 v64, v64, v65
	v_exp_f32_e32 v64, v64
	v_cvt_i32_f32_e32 v65, v66
	v_cmp_ngt_f32_e64 vcc, |v58|, s3
	v_max_f32_e32 v29, 0, v58
	v_ldexp_f32 v64, v64, v65
	v_cndmask_b32_e32 v64, 0, v64, vcc
	v_cmp_nlt_f32_e64 vcc, |v58|, s2
	s_nop 1
	v_cndmask_b32_e32 v58, v179, v64, vcc
	v_add_f32_e32 v66, 1.0, v58
	v_add_f32_e32 v64, -1.0, v66
	v_sub_f32_e32 v65, v64, v66
	v_add_f32_e32 v65, 1.0, v65
	v_sub_f32_e32 v64, v58, v64
	v_add_f32_e32 v67, v64, v65
	v_frexp_mant_f32_e32 v64, v66
	v_cmp_gt_f32_e32 vcc, s79, v64
	v_cvt_f64_f32_e32 v[64:65], v66
	v_frexp_exp_i32_f64_e32 v64, v[64:65]
	v_subbrev_co_u32_e32 v64, vcc, 0, v64, vcc
	v_sub_u32_e32 v65, 0, v64
	v_ldexp_f32 v66, v66, v65
	v_ldexp_f32 v65, v67, v65
	v_add_f32_e32 v67, -1.0, v66
	v_add_f32_e32 v68, 1.0, v67
	v_sub_f32_e32 v68, v66, v68
	v_add_f32_e32 v68, v65, v68
	v_add_f32_e32 v69, v67, v68
	v_sub_f32_e32 v67, v67, v69
	v_add_f32_e32 v67, v68, v67
	v_add_f32_e32 v68, 1.0, v66
	v_add_f32_e32 v70, -1.0, v68
	v_sub_f32_e32 v66, v66, v70
	v_add_f32_e32 v65, v65, v66
	v_add_f32_e32 v66, v68, v65
	v_sub_f32_e32 v68, v68, v66
	v_add_f32_e32 v65, v65, v68
	v_rcp_f32_e32 v68, v66
	v_cvt_f32_i32_e32 v64, v64
	v_cmp_neq_f32_e32 vcc, s34, v58
	v_mul_f32_e32 v70, v69, v68
	v_mul_f32_e32 v71, v66, v70
	v_fma_f32 v72, v70, v66, -v71
	v_fmac_f32_e32 v72, v70, v65
	v_add_f32_e32 v73, v71, v72
	v_sub_f32_e32 v74, v69, v73
	v_sub_f32_e32 v69, v69, v74
	v_sub_f32_e32 v71, v73, v71
	v_sub_f32_e32 v69, v69, v73
	v_add_f32_e32 v67, v67, v69
	v_sub_f32_e32 v69, v71, v72
	v_add_f32_e32 v67, v69, v67
	v_add_f32_e32 v69, v74, v67
	v_mul_f32_e32 v71, v68, v69
	v_mul_f32_e32 v72, v66, v71
	v_fma_f32 v66, v71, v66, -v72
	v_fmac_f32_e32 v66, v71, v65
	v_sub_f32_e32 v65, v74, v69
	v_add_f32_e32 v65, v67, v65
	v_add_f32_e32 v67, v72, v66
	v_sub_f32_e32 v73, v69, v67
	v_sub_f32_e32 v69, v69, v73
	v_sub_f32_e32 v72, v67, v72
	v_sub_f32_e32 v67, v69, v67
	v_add_f32_e32 v65, v65, v67
	v_sub_f32_e32 v66, v72, v66
	v_add_f32_e32 v65, v66, v65
	v_add_f32_e32 v66, v70, v71
	v_add_f32_e32 v65, v73, v65
	v_sub_f32_e32 v67, v66, v70
	v_mul_f32_e32 v65, v68, v65
	v_sub_f32_e32 v67, v71, v67
	v_add_f32_e32 v65, v67, v65
	v_mul_f32_e32 v70, 0x3f317218, v64
	v_add_f32_e32 v67, v66, v65
	v_fma_f32 v71, v64, s8, -v70
	v_mul_f32_e32 v68, v67, v67
	v_fmac_f32_e32 v71, 0xb102e308, v64
	v_sub_f32_e32 v64, v67, v66
	v_fmamk_f32 v69, v68, 0x3e9b6dac, v169
	v_sub_f32_e32 v64, v65, v64
	v_add_f32_e32 v65, v70, v71
	v_fmaak_f32 v69, v68, v69, 0x3f2aaada
	v_sub_f32_e32 v66, v65, v70
	v_ldexp_f32 v70, v67, 1
	v_mul_f32_e32 v67, v67, v68
	v_mul_f32_e32 v67, v67, v69
	v_add_f32_e32 v68, v70, v67
	v_sub_f32_e32 v69, v68, v70
	v_ldexp_f32 v64, v64, 1
	v_sub_f32_e32 v67, v67, v69
	v_add_f32_e32 v64, v64, v67
	v_add_f32_e32 v67, v68, v64
	v_sub_f32_e32 v68, v67, v68
	v_sub_f32_e32 v64, v64, v68
	v_add_f32_e32 v68, v65, v67
	v_sub_f32_e32 v69, v68, v65
	v_sub_f32_e32 v70, v68, v69
	v_sub_f32_e32 v66, v71, v66
	v_sub_f32_e32 v65, v65, v70
	v_sub_f32_e32 v67, v67, v69
	v_add_f32_e32 v65, v67, v65
	v_add_f32_e32 v67, v66, v64
	v_sub_f32_e32 v69, v67, v66
	v_sub_f32_e32 v70, v67, v69
	v_sub_f32_e32 v66, v66, v70
	v_sub_f32_e32 v64, v64, v69
	v_add_f32_e32 v65, v67, v65
	v_add_f32_e32 v64, v64, v66
	v_add_f32_e32 v66, v68, v65
	v_sub_f32_e32 v67, v66, v68
	v_sub_f32_e32 v65, v65, v67
	v_add_f32_e32 v64, v64, v65
	v_add_f32_e32 v64, v66, v64
	v_cndmask_b32_e32 v64, v179, v64, vcc
	v_cmp_lt_f32_e64 vcc, |v58|, s9
	s_nop 1
	v_cndmask_b32_e32 v58, v64, v58, vcc
	v_add_f32_e32 v29, v29, v58
	v_mul_f32_e64 v27, v29, -v27
	v_mul_f32_e32 v29, 0x3fb8aa3b, v27
	v_fma_f32 v58, v27, s38, -v29
	v_rndne_f32_e32 v64, v29
	v_fmac_f32_e32 v58, 0x32a5705f, v27
	v_sub_f32_e32 v29, v29, v64
	v_add_f32_e32 v29, v29, v58
	v_exp_f32_e32 v29, v29
	v_cvt_i32_f32_e32 v58, v64
	v_cmp_ngt_f32_e32 vcc, s39, v27
	v_ldexp_f32 v29, v29, v58
	s_nop 0
	v_cndmask_b32_e32 v29, 0, v29, vcc
	v_cmp_nlt_f32_e32 vcc, s78, v27
	s_nop 1
	v_cndmask_b32_e32 v27, v179, v29, vcc
	v_lshrrev_b32_e32 v29, 3, v230
	v_add_u32_e32 v29, s44, v29
	ds_write_b64 v29, v[26:27] offset:10240
.LBB0_1180:
	s_or_b64 exec, exec, s[0:1]
	v_lshlrev_b32_e32 v27, 16, v62
	v_and_b32_e32 v26, 0xffff0000, v62
	v_mul_f32_e32 v62, v20, v8
	v_fmac_f32_e32 v62, v24, v4
	v_lshlrev_b32_e32 v58, 16, v63
	v_fmac_f32_e32 v62, v12, v51
	v_fmac_f32_e32 v62, v14, v58
	v_mul_f32_e32 v24, 0xbfb8aa3b, v62
	v_and_b32_e32 v29, 0xffff0000, v63
	v_exp_f32_e32 v63, v24
	v_lshlrev_b32_e32 v24, 16, v59
	v_mul_f32_e32 v64, v18, v6
	v_fmac_f32_e32 v64, v22, v2
	v_add_f32_e32 v59, 1.0, v63
	v_mul_f32_e32 v63, v21, v9
	v_fmac_f32_e32 v63, v25, v5
	v_fmac_f32_e32 v63, v13, v48
	v_fmac_f32_e32 v63, v15, v29
	v_mul_f32_e32 v25, 0xbfb8aa3b, v63
	v_exp_f32_e32 v25, v25
	v_fmac_f32_e32 v64, v10, v50
	v_fmac_f32_e32 v64, v16, v27
	v_mul_f32_e32 v65, v19, v7
	v_add_f32_e32 v25, 1.0, v25
	v_mul_f32_e32 v22, 0xbfb8aa3b, v64
	v_fmac_f32_e32 v65, v23, v3
	v_rcp_f32_e32 v25, v25
	v_exp_f32_e32 v22, v22
	v_rcp_f32_e32 v59, v59
	v_fmac_f32_e32 v65, v11, v47
	v_fmac_f32_e32 v65, v17, v26
	v_mul_f32_e32 v23, 0xbfb8aa3b, v65
	v_exp_f32_e32 v23, v23
	v_mul_f32_e32 v25, v63, v25
	v_add_f32_e32 v22, 1.0, v22
	v_mul_f32_e32 v59, v62, v59
	v_mul_f32_e32 v63, v25, v25
	v_rcp_f32_e32 v22, v22
	v_fmac_f32_e32 v63, v59, v59
	v_add_f32_e32 v23, 1.0, v23
	v_rcp_f32_e32 v23, v23
	v_add_f32_dpp v63, v63, v63 row_ror:8 row_mask:0xf bank_mask:0xf bound_ctrl:1
	v_mul_f32_e32 v22, v64, v22
	v_mov_b32_e32 v64, v163
	v_add_f32_dpp v63, v63, v63 row_ror:4 row_mask:0xf bank_mask:0xf bound_ctrl:1
	v_mul_f32_e32 v23, v65, v23
	v_mul_f32_e32 v62, v57, v34
	v_add_f32_dpp v63, v63, v63 quad_perm:[2,3,0,1] row_mask:0xf bank_mask:0xf bound_ctrl:1
	v_fmac_f32_e32 v62, v56, v33
	v_mov_b32_e32 v65, v163
	v_add_f32_dpp v63, v63, v63 quad_perm:[1,0,3,2] row_mask:0xf bank_mask:0xf bound_ctrl:1
	v_fmac_f32_e32 v62, v35, v49
	v_fmac_f32_e32 v62, v36, v24
	s_nop 0
	v_add_f32_dpp v63, v63, v63 row_bcast:15 row_mask:0xa bank_mask:0xf
	v_mov_b32_e32 v64, v163
	v_mul_f32_e32 v56, 0xbfb8aa3b, v62
	v_exp_f32_e32 v56, v56
	s_nop 0
	v_add_f32_dpp v63, v63, v63 row_bcast:31 row_mask:0xc bank_mask:0xf
	v_mul_f32_e32 v64, v23, v23
	v_fmac_f32_e32 v64, v22, v22
	v_readlane_b32 s0, v63, 63
	v_add_f32_e32 v56, 1.0, v56
	v_add_f32_dpp v64, v64, v64 row_ror:8 row_mask:0xf bank_mask:0xf bound_ctrl:1
	v_add_f32_e32 v63, s0, v171
	v_rsq_f32_e32 v63, v63
	v_add_f32_dpp v64, v64, v64 row_ror:4 row_mask:0xf bank_mask:0xf bound_ctrl:1
	v_rcp_f32_e32 v56, v56
	s_ashr_i32 s25, s24, 31
	v_add_f32_dpp v64, v64, v64 quad_perm:[2,3,0,1] row_mask:0xf bank_mask:0xf bound_ctrl:1
	v_mul_f32_e32 v63, 0x3db504f3, v63
	v_mul_f32_e32 v59, v59, v63
	v_add_f32_dpp v64, v64, v64 quad_perm:[1,0,3,2] row_mask:0xf bank_mask:0xf bound_ctrl:1
	s_nop 1
	s_nop 0
	v_add_f32_dpp v64, v64, v64 row_bcast:15 row_mask:0xa bank_mask:0xf
	v_mov_b32_e32 v65, v163
	s_nop 1
	s_nop 0
	v_add_f32_dpp v64, v64, v64 row_bcast:31 row_mask:0xc bank_mask:0xf
	s_nop 0
	v_readlane_b32 s0, v64, 63
	s_nop 1
	v_add_f32_e32 v64, s0, v171
	v_rsq_f32_e32 v64, v64
	s_nop 0
	v_mul_f32_e32 v22, v22, v64
	v_mul_f32_e32 v23, v23, v64
	v_add_u32_e32 v64, 0x400, v28
	ds_write2_b32 v64, v22, v23 offset1:32
	v_mul_f32_e32 v22, v25, v63
	ds_write2_b32 v64, v59, v22 offset0:128 offset1:160
	v_mul_f32_e32 v22, v62, v56
	ds_write_b32 v37, v22 offset:8448
	s_and_saveexec_b64 s[0:1], s[4:5]
	s_cbranch_execz .LBB0_1182
.LBB0_1182:
	s_or_b64 exec, exec, s[0:1]
	v_lshlrev_b32_e32 v23, 16, v60
	v_mul_f32_e32 v60, v9, v48
	v_mul_f32_e32 v25, v8, v51
	v_fmac_f32_e32 v60, v21, v5
	v_lshlrev_b32_e32 v59, 16, v55
	v_and_b32_e32 v55, 0xffff0000, v55
	v_fmac_f32_e32 v25, v20, v4
	v_fmac_f32_e32 v60, v13, v29
	v_fmac_f32_e32 v25, v12, v58
	v_fmac_f32_e32 v60, v15, v55
	v_fmac_f32_e32 v25, v14, v59
	v_mul_f32_e32 v21, 0xbfb8aa3b, v60
	v_mul_f32_e32 v20, 0xbfb8aa3b, v25
	v_exp_f32_e32 v21, v21
	v_lshlrev_b32_e32 v56, 16, v61
	v_and_b32_e32 v22, 0xffff0000, v61
	v_exp_f32_e32 v20, v20
	v_mul_f32_e32 v61, v6, v50
	v_fmac_f32_e32 v61, v18, v2
	v_fmac_f32_e32 v61, v10, v27
	v_fmac_f32_e32 v61, v16, v56
	v_mul_f32_e32 v62, v7, v47
	v_add_f32_e32 v21, 1.0, v21
	v_mul_f32_e32 v18, 0xbfb8aa3b, v61
	v_add_f32_e32 v20, 1.0, v20
	v_fmac_f32_e32 v62, v19, v3
	v_rcp_f32_e32 v21, v21
	v_exp_f32_e32 v18, v18
	v_rcp_f32_e32 v20, v20
	v_fmac_f32_e32 v62, v11, v26
	v_fmac_f32_e32 v62, v17, v22
	v_mul_f32_e32 v19, 0xbfb8aa3b, v62
	v_exp_f32_e32 v19, v19
	v_mul_f32_e32 v21, v60, v21
	v_add_f32_e32 v18, 1.0, v18
	v_mul_f32_e32 v20, v25, v20
	v_mul_f32_e32 v60, v21, v21
	v_rcp_f32_e32 v18, v18
	v_fmac_f32_e32 v60, v20, v20
	v_add_f32_e32 v19, 1.0, v19
	v_rcp_f32_e32 v19, v19
	v_add_f32_dpp v60, v60, v60 row_ror:8 row_mask:0xf bank_mask:0xf bound_ctrl:1
	v_mul_f32_e32 v18, v61, v18
	v_mov_b32_e32 v61, v163
	v_add_f32_dpp v60, v60, v60 row_ror:4 row_mask:0xf bank_mask:0xf bound_ctrl:1
	v_mul_f32_e32 v19, v62, v19
	v_mul_f32_e32 v25, v34, v49
	v_add_f32_dpp v60, v60, v60 quad_perm:[2,3,0,1] row_mask:0xf bank_mask:0xf bound_ctrl:1
	v_fmac_f32_e32 v25, v57, v33
	v_mov_b32_e32 v62, v163
	v_add_f32_dpp v60, v60, v60 quad_perm:[1,0,3,2] row_mask:0xf bank_mask:0xf bound_ctrl:1
	v_fmac_f32_e32 v25, v35, v24
	v_fmac_f32_e32 v25, v36, v23
	s_nop 0
	v_add_f32_dpp v60, v60, v60 row_bcast:15 row_mask:0xa bank_mask:0xf
	v_mov_b32_e32 v61, v163
	v_mul_f32_e32 v57, 0xbfb8aa3b, v25
	v_exp_f32_e32 v57, v57
	s_nop 0
	v_add_f32_dpp v60, v60, v60 row_bcast:31 row_mask:0xc bank_mask:0xf
	v_mul_f32_e32 v61, v19, v19
	v_fmac_f32_e32 v61, v18, v18
	v_readlane_b32 s0, v60, 63
	v_add_f32_e32 v57, 1.0, v57
	v_add_f32_dpp v61, v61, v61 row_ror:8 row_mask:0xf bank_mask:0xf bound_ctrl:1
	v_add_f32_e32 v60, s0, v171
	v_rsq_f32_e32 v60, v60
	v_add_f32_dpp v61, v61, v61 row_ror:4 row_mask:0xf bank_mask:0xf bound_ctrl:1
	v_rcp_f32_e32 v57, v57
	s_ashr_i32 s23, s22, 31
	v_add_f32_dpp v61, v61, v61 quad_perm:[2,3,0,1] row_mask:0xf bank_mask:0xf bound_ctrl:1
	v_mul_f32_e32 v60, 0x3db504f3, v60
	v_mul_f32_e32 v20, v20, v60
	v_add_f32_dpp v61, v61, v61 quad_perm:[1,0,3,2] row_mask:0xf bank_mask:0xf bound_ctrl:1
	s_nop 1
	s_nop 0
	v_add_f32_dpp v61, v61, v61 row_bcast:15 row_mask:0xa bank_mask:0xf
	v_mov_b32_e32 v62, v163
	s_nop 1
	s_nop 0
	v_add_f32_dpp v61, v61, v61 row_bcast:31 row_mask:0xc bank_mask:0xf
	s_nop 0
	v_readlane_b32 s0, v61, 63
	s_nop 1
	v_add_f32_e32 v61, s0, v171
	v_rsq_f32_e32 v61, v61
	s_nop 0
	v_mul_f32_e32 v18, v18, v61
	v_mul_f32_e32 v19, v19, v61
	v_add_u32_e32 v61, 0x800, v28
	ds_write2_b32 v61, v18, v19 offset1:32
	v_mul_f32_e32 v18, v21, v60
	ds_write2_b32 v61, v20, v18 offset0:128 offset1:160
	v_mul_f32_e32 v18, v25, v57
	ds_write_b32 v37, v18 offset:8704
	s_and_saveexec_b64 s[0:1], s[4:5]
	s_cbranch_execz .LBB0_1184
.LBB0_1184:
	s_or_b64 exec, exec, s[0:1]
	v_mul_f32_e32 v18, v8, v58
	v_fmac_f32_e32 v18, v4, v51
	v_mul_f32_e32 v21, v6, v27
	v_mul_f32_e32 v51, v9, v29
	v_fmac_f32_e32 v21, v2, v50
	v_fmac_f32_e32 v51, v5, v48
	v_lshlrev_b32_e32 v60, 16, v54
	v_and_b32_e32 v54, 0xffff0000, v54
	v_lshlrev_b32_e32 v57, 16, v53
	v_fmac_f32_e32 v18, v12, v59
	v_fmac_f32_e32 v21, v10, v56
	v_fmac_f32_e32 v51, v13, v55
	v_fmac_f32_e32 v18, v14, v60
	v_fmac_f32_e32 v21, v16, v57
	v_fmac_f32_e32 v51, v15, v54
	v_mul_f32_e32 v19, 0xbfb8aa3b, v18
	v_mul_f32_e32 v25, 0xbfb8aa3b, v21
	v_mul_f32_e32 v48, 0xbfb8aa3b, v51
	v_exp_f32_e32 v19, v19
	v_exp_f32_e32 v50, v25
	v_exp_f32_e32 v48, v48
	v_lshlrev_b32_e32 v25, 16, v52
	v_add_f32_e32 v19, 1.0, v19
	v_add_f32_e32 v50, 1.0, v50
	v_mul_f32_e32 v52, v7, v26
	v_add_f32_e32 v48, 1.0, v48
	v_rcp_f32_e32 v19, v19
	v_fmac_f32_e32 v52, v3, v47
	v_rcp_f32_e32 v50, v50
	v_rcp_f32_e32 v48, v48
	v_and_b32_e32 v20, 0xffff0000, v53
	v_fmac_f32_e32 v52, v11, v22
	v_fmac_f32_e32 v52, v17, v20
	v_mul_f32_e32 v47, 0xbfb8aa3b, v52
	v_exp_f32_e32 v47, v47
	v_mul_f32_e32 v18, v18, v19
	v_mul_f32_e32 v19, v21, v50
	v_mul_f32_e32 v21, v51, v48
	v_mul_f32_e32 v50, v21, v21
	v_fmac_f32_e32 v50, v18, v18
	v_add_f32_e32 v47, 1.0, v47
	v_rcp_f32_e32 v47, v47
	v_add_f32_dpp v50, v50, v50 row_ror:8 row_mask:0xf bank_mask:0xf bound_ctrl:1
	v_mov_b32_e32 v51, v163
	v_mul_f32_e32 v48, v34, v24
	v_add_f32_dpp v50, v50, v50 row_ror:4 row_mask:0xf bank_mask:0xf bound_ctrl:1
	v_mul_f32_e32 v47, v52, v47
	v_fmac_f32_e32 v48, v33, v49
	v_add_f32_dpp v50, v50, v50 quad_perm:[2,3,0,1] row_mask:0xf bank_mask:0xf bound_ctrl:1
	v_mov_b32_e32 v52, v163
	v_fmac_f32_e32 v48, v35, v23
	v_add_f32_dpp v50, v50, v50 quad_perm:[1,0,3,2] row_mask:0xf bank_mask:0xf bound_ctrl:1
	v_fmac_f32_e32 v48, v36, v25
	v_mul_f32_e32 v49, 0xbfb8aa3b, v48
	s_nop 0
	v_add_f32_dpp v50, v50, v50 row_bcast:15 row_mask:0xa bank_mask:0xf
	v_mov_b32_e32 v51, v163
	v_exp_f32_e32 v49, v49
	s_ashr_i32 s21, s20, 31
	s_nop 0
	v_add_f32_dpp v50, v50, v50 row_bcast:31 row_mask:0xc bank_mask:0xf
	v_mul_f32_e32 v51, v47, v47
	v_fmac_f32_e32 v51, v19, v19
	v_readlane_b32 s0, v50, 63
	v_add_f32_e32 v49, 1.0, v49
	v_add_f32_dpp v51, v51, v51 row_ror:8 row_mask:0xf bank_mask:0xf bound_ctrl:1
	v_add_f32_e32 v50, s0, v171
	v_rsq_f32_e32 v50, v50
	v_add_f32_dpp v51, v51, v51 row_ror:4 row_mask:0xf bank_mask:0xf bound_ctrl:1
	v_rcp_f32_e32 v49, v49
	v_mul_f32_e32 v50, 0x3db504f3, v50
	v_add_f32_dpp v51, v51, v51 quad_perm:[2,3,0,1] row_mask:0xf bank_mask:0xf bound_ctrl:1
	v_mul_f32_e32 v18, v18, v50
	s_nop 0
	v_add_f32_dpp v51, v51, v51 quad_perm:[1,0,3,2] row_mask:0xf bank_mask:0xf bound_ctrl:1
	s_nop 1
	s_nop 0
	v_add_f32_dpp v51, v51, v51 row_bcast:15 row_mask:0xa bank_mask:0xf
	v_mov_b32_e32 v52, v163
	s_nop 1
	s_nop 0
	v_add_f32_dpp v51, v51, v51 row_bcast:31 row_mask:0xc bank_mask:0xf
	s_nop 0
	v_readlane_b32 s0, v51, 63
	s_nop 1
	v_add_f32_e32 v51, s0, v171
	v_rsq_f32_e32 v51, v51
	s_nop 0
	v_mul_f32_e32 v19, v19, v51
	v_mul_f32_e32 v47, v47, v51
	v_add_u32_e32 v51, 0xc00, v28
	ds_write2_b32 v51, v19, v47 offset1:32
	v_mul_f32_e32 v19, v21, v50
	ds_write2_b32 v51, v18, v19 offset0:128 offset1:160
	v_mul_f32_e32 v18, v48, v49
	ds_write_b32 v37, v18 offset:8960
	s_and_saveexec_b64 s[0:1], s[4:5]
	s_cbranch_execz .LBB0_1186
.LBB0_1186:
	s_or_b64 exec, exec, s[0:1]
	v_lshlrev_b32_e32 v47, 16, v45
	v_and_b32_e32 v21, 0xffff0000, v45
	v_mul_f32_e32 v45, v6, v56
	v_fmac_f32_e32 v45, v2, v27
	v_fmac_f32_e32 v45, v10, v57
	v_fmac_f32_e32 v45, v16, v47
	v_mul_f32_e32 v27, 0xbfb8aa3b, v45
	v_exp_f32_e32 v49, v27
	v_lshlrev_b32_e32 v27, 16, v44
	v_mul_f32_e32 v18, v8, v59
	v_lshlrev_b32_e32 v48, 16, v46
	v_add_f32_e32 v44, 1.0, v49
	v_mul_f32_e32 v49, v9, v55
	v_fmac_f32_e32 v49, v5, v29
	v_and_b32_e32 v46, 0xffff0000, v46
	v_fmac_f32_e32 v18, v4, v58
	v_fmac_f32_e32 v49, v13, v54
	v_fmac_f32_e32 v18, v12, v60
	v_fmac_f32_e32 v49, v15, v46
	v_fmac_f32_e32 v18, v14, v48
	v_mul_f32_e32 v29, 0xbfb8aa3b, v49
	v_mul_f32_e32 v19, 0xbfb8aa3b, v18
	v_exp_f32_e32 v29, v29
	v_exp_f32_e32 v19, v19
	v_mul_f32_e32 v50, v7, v22
	v_fmac_f32_e32 v50, v3, v26
	v_add_f32_e32 v29, 1.0, v29
	v_add_f32_e32 v19, 1.0, v19
	v_rcp_f32_e32 v29, v29
	v_rcp_f32_e32 v19, v19
	v_fmac_f32_e32 v50, v11, v20
	v_rcp_f32_e32 v44, v44
	v_fmac_f32_e32 v50, v17, v21
	v_mul_f32_e32 v26, 0xbfb8aa3b, v50
	v_exp_f32_e32 v26, v26
	v_mul_f32_e32 v29, v49, v29
	v_mul_f32_e32 v18, v18, v19
	v_mul_f32_e32 v19, v45, v44
	v_mul_f32_e32 v45, v29, v29
	v_fmac_f32_e32 v45, v18, v18
	v_add_f32_e32 v26, 1.0, v26
	v_rcp_f32_e32 v26, v26
	v_add_f32_dpp v45, v45, v45 row_ror:8 row_mask:0xf bank_mask:0xf bound_ctrl:1
	v_mov_b32_e32 v49, v163
	v_mul_f32_e32 v44, v34, v23
	v_add_f32_dpp v45, v45, v45 row_ror:4 row_mask:0xf bank_mask:0xf bound_ctrl:1
	v_mul_f32_e32 v26, v50, v26
	v_fmac_f32_e32 v44, v33, v24
	v_add_f32_dpp v45, v45, v45 quad_perm:[2,3,0,1] row_mask:0xf bank_mask:0xf bound_ctrl:1
	v_mov_b32_e32 v50, v163
	v_fmac_f32_e32 v44, v35, v25
	v_add_f32_dpp v45, v45, v45 quad_perm:[1,0,3,2] row_mask:0xf bank_mask:0xf bound_ctrl:1
	v_fmac_f32_e32 v44, v36, v27
	v_mul_f32_e32 v24, 0xbfb8aa3b, v44
	s_nop 0
	v_add_f32_dpp v45, v45, v45 row_bcast:15 row_mask:0xa bank_mask:0xf
	v_mov_b32_e32 v49, v163
	v_exp_f32_e32 v24, v24
	s_ashr_i32 s19, s18, 31
	s_nop 0
	v_add_f32_dpp v45, v45, v45 row_bcast:31 row_mask:0xc bank_mask:0xf
	v_mul_f32_e32 v49, v26, v26
	v_fmac_f32_e32 v49, v19, v19
	v_readlane_b32 s0, v45, 63
	v_add_f32_e32 v24, 1.0, v24
	v_add_f32_dpp v49, v49, v49 row_ror:8 row_mask:0xf bank_mask:0xf bound_ctrl:1
	v_add_f32_e32 v45, s0, v171
	v_rsq_f32_e32 v45, v45
	v_add_f32_dpp v49, v49, v49 row_ror:4 row_mask:0xf bank_mask:0xf bound_ctrl:1
	v_rcp_f32_e32 v24, v24
	v_mul_f32_e32 v45, 0x3db504f3, v45
	v_add_f32_dpp v49, v49, v49 quad_perm:[2,3,0,1] row_mask:0xf bank_mask:0xf bound_ctrl:1
	v_mul_f32_e32 v18, v18, v45
	s_nop 0
	v_add_f32_dpp v49, v49, v49 quad_perm:[1,0,3,2] row_mask:0xf bank_mask:0xf bound_ctrl:1
	s_nop 1
	s_nop 0
	v_add_f32_dpp v49, v49, v49 row_bcast:15 row_mask:0xa bank_mask:0xf
	v_mov_b32_e32 v50, v163
	s_nop 1
	s_nop 0
	v_add_f32_dpp v49, v49, v49 row_bcast:31 row_mask:0xc bank_mask:0xf
	s_nop 0
	v_readlane_b32 s0, v49, 63
	s_nop 1
	v_add_f32_e32 v49, s0, v171
	v_rsq_f32_e32 v49, v49
	s_nop 0
	v_mul_f32_e32 v19, v19, v49
	v_mul_f32_e32 v26, v26, v49
	v_add_u32_e32 v49, 0x1000, v28
	ds_write2_b32 v49, v19, v26 offset1:32
	v_mul_f32_e32 v19, v29, v45
	ds_write2_b32 v49, v18, v19 offset0:128 offset1:160
	v_mul_f32_e32 v18, v44, v24
	ds_write_b32 v37, v18 offset:9216
	s_and_saveexec_b64 s[0:1], s[4:5]
	s_cbranch_execz .LBB0_1188
.LBB0_1188:
	s_or_b64 exec, exec, s[0:1]
	v_lshlrev_b32_e32 v44, 16, v43
	v_and_b32_e32 v29, 0xffff0000, v43
	v_lshlrev_b32_e32 v43, 16, v42
	v_and_b32_e32 v24, 0xffff0000, v42
	v_mul_f32_e32 v42, v6, v57
	v_fmac_f32_e32 v42, v2, v56
	v_fmac_f32_e32 v42, v10, v47
	v_fmac_f32_e32 v42, v16, v43
	v_mul_f32_e32 v26, 0xbfb8aa3b, v42
	v_exp_f32_e32 v45, v26
	v_mul_f32_e32 v18, v8, v60
	v_lshlrev_b32_e32 v26, 16, v41
	v_fmac_f32_e32 v18, v4, v59
	v_add_f32_e32 v41, 1.0, v45
	v_mul_f32_e32 v45, v9, v54
	v_fmac_f32_e32 v45, v5, v55
	v_fmac_f32_e32 v18, v12, v48
	v_fmac_f32_e32 v45, v13, v46
	v_fmac_f32_e32 v18, v14, v44
	v_fmac_f32_e32 v45, v15, v29
	v_mul_f32_e32 v19, 0xbfb8aa3b, v18
	v_mul_f32_e32 v49, 0xbfb8aa3b, v45
	v_exp_f32_e32 v19, v19
	v_exp_f32_e32 v49, v49
	v_mul_f32_e32 v50, v7, v20
	v_fmac_f32_e32 v50, v3, v22
	v_add_f32_e32 v19, 1.0, v19
	v_add_f32_e32 v49, 1.0, v49
	v_rcp_f32_e32 v19, v19
	v_rcp_f32_e32 v41, v41
	v_rcp_f32_e32 v49, v49
	v_fmac_f32_e32 v50, v11, v21
	v_fmac_f32_e32 v50, v17, v24
	v_mul_f32_e32 v22, 0xbfb8aa3b, v50
	v_exp_f32_e32 v22, v22
	v_mul_f32_e32 v18, v18, v19
	v_mul_f32_e32 v19, v42, v41
	v_mul_f32_e32 v41, v45, v49
	v_mul_f32_e32 v45, v41, v41
	v_fmac_f32_e32 v45, v18, v18
	v_add_f32_e32 v22, 1.0, v22
	v_rcp_f32_e32 v22, v22
	v_add_f32_dpp v45, v45, v45 row_ror:8 row_mask:0xf bank_mask:0xf bound_ctrl:1
	v_mov_b32_e32 v49, v163
	v_mul_f32_e32 v42, v34, v25
	v_add_f32_dpp v45, v45, v45 row_ror:4 row_mask:0xf bank_mask:0xf bound_ctrl:1
	v_mul_f32_e32 v22, v50, v22
	v_fmac_f32_e32 v42, v33, v23
	v_add_f32_dpp v45, v45, v45 quad_perm:[2,3,0,1] row_mask:0xf bank_mask:0xf bound_ctrl:1
	v_mov_b32_e32 v50, v163
	v_fmac_f32_e32 v42, v35, v27
	v_add_f32_dpp v45, v45, v45 quad_perm:[1,0,3,2] row_mask:0xf bank_mask:0xf bound_ctrl:1
	v_fmac_f32_e32 v42, v36, v26
	v_mul_f32_e32 v23, 0xbfb8aa3b, v42
	s_nop 0
	v_add_f32_dpp v45, v45, v45 row_bcast:15 row_mask:0xa bank_mask:0xf
	v_mov_b32_e32 v49, v163
	v_exp_f32_e32 v23, v23
	s_ashr_i32 s17, s16, 31
	s_nop 0
	v_add_f32_dpp v45, v45, v45 row_bcast:31 row_mask:0xc bank_mask:0xf
	v_mul_f32_e32 v49, v22, v22
	v_fmac_f32_e32 v49, v19, v19
	v_readlane_b32 s0, v45, 63
	v_add_f32_e32 v23, 1.0, v23
	v_add_f32_dpp v49, v49, v49 row_ror:8 row_mask:0xf bank_mask:0xf bound_ctrl:1
	v_add_f32_e32 v45, s0, v171
	v_rsq_f32_e32 v45, v45
	v_add_f32_dpp v49, v49, v49 row_ror:4 row_mask:0xf bank_mask:0xf bound_ctrl:1
	v_rcp_f32_e32 v23, v23
	v_mul_f32_e32 v45, 0x3db504f3, v45
	v_add_f32_dpp v49, v49, v49 quad_perm:[2,3,0,1] row_mask:0xf bank_mask:0xf bound_ctrl:1
	v_mul_f32_e32 v18, v18, v45
	s_nop 0
	v_add_f32_dpp v49, v49, v49 quad_perm:[1,0,3,2] row_mask:0xf bank_mask:0xf bound_ctrl:1
	s_nop 1
	s_nop 0
	v_add_f32_dpp v49, v49, v49 row_bcast:15 row_mask:0xa bank_mask:0xf
	v_mov_b32_e32 v50, v163
	s_nop 1
	s_nop 0
	v_add_f32_dpp v49, v49, v49 row_bcast:31 row_mask:0xc bank_mask:0xf
	s_nop 0
	v_readlane_b32 s0, v49, 63
	s_nop 1
	v_add_f32_e32 v49, s0, v171
	v_rsq_f32_e32 v49, v49
	s_nop 0
	v_mul_f32_e32 v19, v19, v49
	v_mul_f32_e32 v22, v22, v49
	v_add_u32_e32 v49, 0x1400, v28
	ds_write2_b32 v49, v19, v22 offset1:32
	v_mul_f32_e32 v19, v41, v45
	ds_write2_b32 v49, v18, v19 offset0:128 offset1:160
	v_mul_f32_e32 v18, v42, v23
	ds_write_b32 v37, v18 offset:9472
	s_and_saveexec_b64 s[0:1], s[4:5]
	s_cbranch_execz .LBB0_1190
.LBB0_1190:
	s_or_b64 exec, exec, s[0:1]
	v_lshlrev_b32_e32 v41, 16, v39
	v_and_b32_e32 v22, 0xffff0000, v39
	v_mul_f32_e32 v39, v6, v47
	v_fmac_f32_e32 v39, v2, v57
	v_fmac_f32_e32 v39, v10, v43
	v_fmac_f32_e32 v39, v16, v41
	v_mul_f32_e32 v23, 0xbfb8aa3b, v39
	v_exp_f32_e32 v45, v23
	v_mul_f32_e32 v18, v8, v48
	v_lshlrev_b32_e32 v23, 16, v38
	v_fmac_f32_e32 v18, v4, v60
	v_add_f32_e32 v38, 1.0, v45
	v_mul_f32_e32 v45, v9, v46
	v_fmac_f32_e32 v45, v5, v54
	v_lshlrev_b32_e32 v42, 16, v40
	v_and_b32_e32 v40, 0xffff0000, v40
	v_fmac_f32_e32 v18, v12, v44
	v_fmac_f32_e32 v45, v13, v29
	v_fmac_f32_e32 v18, v14, v42
	v_fmac_f32_e32 v45, v15, v40
	v_mul_f32_e32 v19, 0xbfb8aa3b, v18
	v_mul_f32_e32 v49, 0xbfb8aa3b, v45
	v_exp_f32_e32 v19, v19
	v_exp_f32_e32 v49, v49
	v_mul_f32_e32 v50, v7, v21
	v_fmac_f32_e32 v50, v3, v20
	v_add_f32_e32 v19, 1.0, v19
	v_add_f32_e32 v49, 1.0, v49
	v_rcp_f32_e32 v19, v19
	v_rcp_f32_e32 v38, v38
	v_rcp_f32_e32 v49, v49
	v_fmac_f32_e32 v50, v11, v24
	v_fmac_f32_e32 v50, v17, v22
	v_mul_f32_e32 v20, 0xbfb8aa3b, v50
	v_exp_f32_e32 v20, v20
	v_mul_f32_e32 v18, v18, v19
	v_mul_f32_e32 v19, v39, v38
	v_mul_f32_e32 v38, v45, v49
	v_mul_f32_e32 v45, v38, v38
	v_fmac_f32_e32 v45, v18, v18
	v_add_f32_e32 v20, 1.0, v20
	v_rcp_f32_e32 v20, v20
	v_add_f32_dpp v45, v45, v45 row_ror:8 row_mask:0xf bank_mask:0xf bound_ctrl:1
	v_mov_b32_e32 v49, v163
	v_mul_f32_e32 v39, v34, v27
	v_add_f32_dpp v45, v45, v45 row_ror:4 row_mask:0xf bank_mask:0xf bound_ctrl:1
	v_mul_f32_e32 v20, v50, v20
	v_fmac_f32_e32 v39, v33, v25
	v_add_f32_dpp v45, v45, v45 quad_perm:[2,3,0,1] row_mask:0xf bank_mask:0xf bound_ctrl:1
	v_mov_b32_e32 v50, v163
	v_fmac_f32_e32 v39, v35, v26
	v_add_f32_dpp v45, v45, v45 quad_perm:[1,0,3,2] row_mask:0xf bank_mask:0xf bound_ctrl:1
	v_fmac_f32_e32 v39, v36, v23
	v_mul_f32_e32 v25, 0xbfb8aa3b, v39
	s_nop 0
	v_add_f32_dpp v45, v45, v45 row_bcast:15 row_mask:0xa bank_mask:0xf
	v_mov_b32_e32 v49, v163
	v_exp_f32_e32 v25, v25
	s_ashr_i32 s15, s14, 31
	s_nop 0
	v_add_f32_dpp v45, v45, v45 row_bcast:31 row_mask:0xc bank_mask:0xf
	v_mul_f32_e32 v49, v20, v20
	v_fmac_f32_e32 v49, v19, v19
	v_readlane_b32 s0, v45, 63
	v_add_f32_e32 v25, 1.0, v25
	v_add_f32_dpp v49, v49, v49 row_ror:8 row_mask:0xf bank_mask:0xf bound_ctrl:1
	v_add_f32_e32 v45, s0, v171
	v_rsq_f32_e32 v45, v45
	v_add_f32_dpp v49, v49, v49 row_ror:4 row_mask:0xf bank_mask:0xf bound_ctrl:1
	v_rcp_f32_e32 v25, v25
	v_mul_f32_e32 v45, 0x3db504f3, v45
	v_add_f32_dpp v49, v49, v49 quad_perm:[2,3,0,1] row_mask:0xf bank_mask:0xf bound_ctrl:1
	v_mul_f32_e32 v18, v18, v45
	s_nop 0
	v_add_f32_dpp v49, v49, v49 quad_perm:[1,0,3,2] row_mask:0xf bank_mask:0xf bound_ctrl:1
	s_nop 1
	s_nop 0
	v_add_f32_dpp v49, v49, v49 row_bcast:15 row_mask:0xa bank_mask:0xf
	v_mov_b32_e32 v50, v163
	s_nop 1
	s_nop 0
	v_add_f32_dpp v49, v49, v49 row_bcast:31 row_mask:0xc bank_mask:0xf
	s_nop 0
	v_readlane_b32 s0, v49, 63
	s_nop 1
	v_add_f32_e32 v49, s0, v171
	v_rsq_f32_e32 v49, v49
	s_nop 0
	v_mul_f32_e32 v19, v19, v49
	v_mul_f32_e32 v20, v20, v49
	v_add_u32_e32 v49, 0x1800, v28
	ds_write2_b32 v49, v19, v20 offset1:32
	v_mul_f32_e32 v19, v38, v45
	ds_write2_b32 v49, v18, v19 offset0:128 offset1:160
	v_mul_f32_e32 v18, v39, v25
	ds_write_b32 v37, v18 offset:9728
	s_and_saveexec_b64 s[0:1], s[4:5]
	s_cbranch_execz .LBB0_1192
.LBB0_1192:
	s_or_b64 exec, exec, s[0:1]
	v_mul_f32_e32 v9, v9, v29
	v_mul_f32_e32 v8, v8, v44
	v_fmac_f32_e32 v9, v5, v46
	v_and_b32_e32 v19, 0xffff0000, v32
	v_fmac_f32_e32 v8, v4, v48
	v_fmac_f32_e32 v9, v13, v40
	v_lshlrev_b32_e32 v18, 16, v32
	v_fmac_f32_e32 v8, v12, v42
	v_fmac_f32_e32 v9, v15, v19
	v_fmac_f32_e32 v8, v14, v18
	v_mul_f32_e32 v5, 0xbfb8aa3b, v9
	v_mul_f32_e32 v4, 0xbfb8aa3b, v8
	v_exp_f32_e32 v5, v5
	v_exp_f32_e32 v4, v4
	v_mul_f32_e32 v7, v7, v24
	v_mul_f32_e32 v6, v6, v43
	v_add_f32_e32 v5, 1.0, v5
	v_add_f32_e32 v4, 1.0, v4
	v_fmac_f32_e32 v7, v3, v21
	v_rcp_f32_e32 v5, v5
	v_and_b32_e32 v25, 0xffff0000, v31
	v_fmac_f32_e32 v6, v2, v47
	v_rcp_f32_e32 v4, v4
	v_fmac_f32_e32 v7, v11, v22
	v_lshlrev_b32_e32 v20, 16, v31
	v_fmac_f32_e32 v6, v10, v41
	v_fmac_f32_e32 v7, v17, v25
	v_fmac_f32_e32 v6, v16, v20
	v_mul_f32_e32 v3, 0xbfb8aa3b, v7
	v_mul_f32_e32 v2, 0xbfb8aa3b, v6
	v_exp_f32_e32 v3, v3
	v_mul_f32_e32 v5, v9, v5
	v_exp_f32_e32 v2, v2
	v_mul_f32_e32 v4, v8, v4
	v_mul_f32_e32 v8, v5, v5
	v_fmac_f32_e32 v8, v4, v4
	v_add_f32_e32 v3, 1.0, v3
	v_add_f32_e32 v2, 1.0, v2
	v_add_f32_dpp v8, v8, v8 row_ror:8 row_mask:0xf bank_mask:0xf bound_ctrl:1
	v_rcp_f32_e32 v3, v3
	v_rcp_f32_e32 v2, v2
	v_add_f32_dpp v8, v8, v8 row_ror:4 row_mask:0xf bank_mask:0xf bound_ctrl:1
	v_mov_b32_e32 v9, v163
	v_mul_f32_e32 v3, v7, v3
	v_add_f32_dpp v8, v8, v8 quad_perm:[2,3,0,1] row_mask:0xf bank_mask:0xf bound_ctrl:1
	v_mul_f32_e32 v2, v6, v2
	v_mul_f32_e32 v6, v34, v26
	v_add_f32_dpp v8, v8, v8 quad_perm:[1,0,3,2] row_mask:0xf bank_mask:0xf bound_ctrl:1
	v_fmac_f32_e32 v6, v33, v27
	v_lshlrev_b32_e32 v10, 16, v30
	s_nop 0
	v_add_f32_dpp v8, v8, v8 row_bcast:15 row_mask:0xa bank_mask:0xf
	v_mov_b32_e32 v9, v163
	v_fmac_f32_e32 v6, v35, v23
	v_fmac_f32_e32 v6, v36, v10
	s_nop 0
	v_add_f32_dpp v8, v8, v8 row_bcast:31 row_mask:0xc bank_mask:0xf
	v_mul_f32_e32 v9, v3, v3
	v_fmac_f32_e32 v9, v2, v2
	v_mov_b32_e32 v10, v163
	v_mul_f32_e32 v7, 0xbfb8aa3b, v6
	v_add_f32_dpp v9, v9, v9 row_ror:8 row_mask:0xf bank_mask:0xf bound_ctrl:1
	v_exp_f32_e32 v7, v7
	v_readlane_b32 s0, v8, 63
	v_add_f32_dpp v9, v9, v9 row_ror:4 row_mask:0xf bank_mask:0xf bound_ctrl:1
	s_ashr_i32 s13, s12, 31
	v_add_f32_e32 v8, s0, v171
	v_add_f32_dpp v9, v9, v9 quad_perm:[2,3,0,1] row_mask:0xf bank_mask:0xf bound_ctrl:1
	v_rsq_f32_e32 v8, v8
	v_add_f32_e32 v7, 1.0, v7
	v_add_f32_dpp v9, v9, v9 quad_perm:[1,0,3,2] row_mask:0xf bank_mask:0xf bound_ctrl:1
	v_rcp_f32_e32 v7, v7
	v_mul_f32_e32 v8, 0x3db504f3, v8
	s_nop 0
	v_add_f32_dpp v9, v9, v9 row_bcast:15 row_mask:0xa bank_mask:0xf
	v_mov_b32_e32 v10, v163
	v_mul_f32_e32 v4, v4, v8
	s_nop 0
	s_nop 0
	v_add_f32_dpp v9, v9, v9 row_bcast:31 row_mask:0xc bank_mask:0xf
	s_nop 0
	v_readlane_b32 s0, v9, 63
	s_nop 1
	v_add_f32_e32 v9, s0, v171
	v_rsq_f32_e32 v9, v9
	s_nop 0
	v_mul_f32_e32 v2, v2, v9
	v_mul_f32_e32 v3, v3, v9
	v_add_u32_e32 v9, 0x1c00, v28
	ds_write2_b32 v9, v2, v3 offset1:32
	v_mul_f32_e32 v2, v5, v8
	ds_write2_b32 v9, v4, v2 offset0:128 offset1:160
	v_mul_f32_e32 v2, v6, v7
	ds_write_b32 v37, v2 offset:9984
	s_and_saveexec_b64 s[0:1], s[4:5]
	s_cbranch_execz .LBB0_1194

.LBB0_1249:
	s_add_i32 s0, s14, 0xfffffb80
	s_ashr_i32 s1, s0, 31
	s_lshr_b32 s1, s1, 25
	s_add_i32 s1, s0, s1
	s_and_b32 s1, s1, 0xffffff80
	s_sub_i32 s4, s0, s1
	s_lshl_b32 s22, s4, 3
	s_ashr_i32 s23, s22, 31
	v_readfirstlane_b32 s5, v0
	s_add_u32 s0, s22, 0x4000
	s_addc_u32 s1, s23, 0
	s_lshr_b32 s5, s5, 4
	s_and_b32 s5, s5, 0xffffffc
	s_add_i32 s5, s5, 0
	s_lshl_b64 s[6:7], s[0:1], 11
	v_mov_b32_e32 v2, v0
	s_add_u32 s6, s33, s6
	s_addc_u32 s7, s34, s7
	v_ashrrev_i32_e32 v3, 31, v2
	v_lshl_add_u64 v[4:5], v[2:3], 1, s[6:7]
	s_barrier
	global_load_ushort v9, v[4:5], off offset:1024
	global_load_ushort v8, v[4:5], off
	v_and_b32_e32 v5, 63, v2
	v_cmp_eq_u32_e32 vcc, 0, v5
	v_mov_b32_e32 v4, 0
	s_waitcnt vmcnt(1)
	v_lshlrev_b32_e32 v16, 16, v9
	v_mul_f32_e32 v5, v16, v16
	s_nop 1
	v_mov_b32_dpp v5, v5 row_ror:8 row_mask:0xf bank_mask:0xf bound_ctrl:1
	v_fmac_f32_e32 v5, v16, v16
	s_nop 1
	v_add_f32_dpp v5, v5, v5 row_ror:4 row_mask:0xf bank_mask:0xf bound_ctrl:1
	s_nop 1
	v_add_f32_dpp v5, v5, v5 quad_perm:[2,3,0,1] row_mask:0xf bank_mask:0xf bound_ctrl:1
	s_nop 1
	v_add_f32_dpp v5, v5, v5 quad_perm:[1,0,3,2] row_mask:0xf bank_mask:0xf bound_ctrl:1
	s_nop 1
	v_mov_b32_dpp v4, v5 row_bcast:15 row_mask:0xa bank_mask:0xf
	v_add_f32_e32 v4, v5, v4
	s_nop 0
	s_nop 1
	s_nop 0
	v_add_f32_dpp v4, v4, v4 row_bcast:31 row_mask:0xc bank_mask:0xf
	s_nop 0
	v_readlane_b32 s10, v4, 63
	s_and_saveexec_b64 s[6:7], vcc
	v_mov_b32_e32 v4, s5
	v_mov_b32_e32 v5, s10
	ds_write_b32 v4, v5
	s_or_b64 exec, exec, s[6:7]
	s_add_u32 s6, s22, 0x4001
	s_addc_u32 s7, s23, 0
	s_lshl_b64 s[10:11], s[6:7], 11
	s_add_u32 s10, s33, s10
	s_addc_u32 s11, s34, s11
	v_lshl_add_u64 v[4:5], v[2:3], 1, s[10:11]
	global_load_ushort v10, v[4:5], off offset:1024
	global_load_ushort v9, v[4:5], off
	v_mov_b32_e32 v4, 0
	s_waitcnt vmcnt(1)
	v_lshlrev_b32_e32 v19, 16, v10
	v_mul_f32_e32 v5, v19, v19
	s_nop 1
	v_mov_b32_dpp v5, v5 row_ror:8 row_mask:0xf bank_mask:0xf bound_ctrl:1
	v_fmac_f32_e32 v5, v19, v19
	s_nop 1
	v_add_f32_dpp v5, v5, v5 row_ror:4 row_mask:0xf bank_mask:0xf bound_ctrl:1
	s_nop 1
	v_add_f32_dpp v5, v5, v5 quad_perm:[2,3,0,1] row_mask:0xf bank_mask:0xf bound_ctrl:1
	s_nop 1
	v_add_f32_dpp v5, v5, v5 quad_perm:[1,0,3,2] row_mask:0xf bank_mask:0xf bound_ctrl:1
	s_nop 1
	v_mov_b32_dpp v4, v5 row_bcast:15 row_mask:0xa bank_mask:0xf
	v_add_f32_e32 v4, v5, v4
	s_nop 0
	s_nop 1
	s_nop 0
	v_add_f32_dpp v4, v4, v4 row_bcast:31 row_mask:0xc bank_mask:0xf
	s_nop 0
	v_readlane_b32 s12, v4, 63
	s_and_saveexec_b64 s[10:11], vcc
	v_mov_b32_e32 v4, s5
	v_mov_b32_e32 v5, s12
	ds_write_b32 v4, v5 offset:32
	s_or_b64 exec, exec, s[10:11]
	s_add_u32 s10, s22, 0x4002
	s_addc_u32 s11, s23, 0
	s_lshl_b64 s[12:13], s[10:11], 11
	s_add_u32 s12, s33, s12
	s_addc_u32 s13, s34, s13
	v_lshl_add_u64 v[4:5], v[2:3], 1, s[12:13]
	global_load_ushort v11, v[4:5], off offset:1024
	global_load_ushort v10, v[4:5], off
	v_mov_b32_e32 v4, 0
	s_waitcnt vmcnt(1)
	v_lshlrev_b32_e32 v23, 16, v11
	v_mul_f32_e32 v5, v23, v23
	s_nop 1
	v_mov_b32_dpp v5, v5 row_ror:8 row_mask:0xf bank_mask:0xf bound_ctrl:1
	v_fmac_f32_e32 v5, v23, v23
	s_nop 1
	v_add_f32_dpp v5, v5, v5 row_ror:4 row_mask:0xf bank_mask:0xf bound_ctrl:1
	s_nop 1
	v_add_f32_dpp v5, v5, v5 quad_perm:[2,3,0,1] row_mask:0xf bank_mask:0xf bound_ctrl:1
	s_nop 1
	v_add_f32_dpp v5, v5, v5 quad_perm:[1,0,3,2] row_mask:0xf bank_mask:0xf bound_ctrl:1
	s_nop 1
	v_mov_b32_dpp v4, v5 row_bcast:15 row_mask:0xa bank_mask:0xf
	v_add_f32_e32 v4, v5, v4
	s_nop 0
	s_nop 1
	s_nop 0
	v_add_f32_dpp v4, v4, v4 row_bcast:31 row_mask:0xc bank_mask:0xf
	s_nop 0
	v_readlane_b32 s14, v4, 63
	s_and_saveexec_b64 s[12:13], vcc
	v_mov_b32_e32 v4, s5
	v_mov_b32_e32 v5, s14
	ds_write_b32 v4, v5 offset:64
	s_or_b64 exec, exec, s[12:13]
	s_add_u32 s12, s22, 0x4003
	s_addc_u32 s13, s23, 0
	s_lshl_b64 s[14:15], s[12:13], 11
	s_add_u32 s14, s33, s14
	s_addc_u32 s15, s34, s15
	v_lshl_add_u64 v[4:5], v[2:3], 1, s[14:15]
	global_load_ushort v11, v[4:5], off offset:1024
	global_load_ushort v12, v[4:5], off
	v_mov_b32_e32 v4, 0
	s_waitcnt vmcnt(1)
	v_lshlrev_b32_e32 v22, 16, v11
	v_mul_f32_e32 v5, v22, v22
	s_nop 1
	v_mov_b32_dpp v5, v5 row_ror:8 row_mask:0xf bank_mask:0xf bound_ctrl:1
	v_fmac_f32_e32 v5, v22, v22
	s_nop 1
	v_add_f32_dpp v5, v5, v5 row_ror:4 row_mask:0xf bank_mask:0xf bound_ctrl:1
	s_nop 1
	v_add_f32_dpp v5, v5, v5 quad_perm:[2,3,0,1] row_mask:0xf bank_mask:0xf bound_ctrl:1
	s_nop 1
	v_add_f32_dpp v5, v5, v5 quad_perm:[1,0,3,2] row_mask:0xf bank_mask:0xf bound_ctrl:1
	s_nop 1
	v_mov_b32_dpp v4, v5 row_bcast:15 row_mask:0xa bank_mask:0xf
	v_add_f32_e32 v4, v5, v4
	s_nop 0
	s_nop 1
	s_nop 0
	v_add_f32_dpp v4, v4, v4 row_bcast:31 row_mask:0xc bank_mask:0xf
	s_nop 0
	v_readlane_b32 s16, v4, 63
	s_and_saveexec_b64 s[14:15], vcc
	v_mov_b32_e32 v4, s5
	v_mov_b32_e32 v5, s16
	ds_write_b32 v4, v5 offset:96
	s_or_b64 exec, exec, s[14:15]
	s_add_u32 s14, s22, 0x4004
	s_addc_u32 s15, s23, 0
	s_lshl_b64 s[16:17], s[14:15], 11
	s_add_u32 s16, s33, s16
	s_addc_u32 s17, s34, s17
	v_lshl_add_u64 v[4:5], v[2:3], 1, s[16:17]
	global_load_ushort v13, v[4:5], off offset:1024
	global_load_ushort v11, v[4:5], off
	v_mov_b32_e32 v4, 0
	s_waitcnt vmcnt(1)
	v_lshlrev_b32_e32 v20, 16, v13
	v_mul_f32_e32 v5, v20, v20
	s_nop 1
	v_mov_b32_dpp v5, v5 row_ror:8 row_mask:0xf bank_mask:0xf bound_ctrl:1
	v_fmac_f32_e32 v5, v20, v20
	s_nop 1
	v_add_f32_dpp v5, v5, v5 row_ror:4 row_mask:0xf bank_mask:0xf bound_ctrl:1
	s_nop 1
	v_add_f32_dpp v5, v5, v5 quad_perm:[2,3,0,1] row_mask:0xf bank_mask:0xf bound_ctrl:1
	s_nop 1
	v_add_f32_dpp v5, v5, v5 quad_perm:[1,0,3,2] row_mask:0xf bank_mask:0xf bound_ctrl:1
	s_nop 1
	v_mov_b32_dpp v4, v5 row_bcast:15 row_mask:0xa bank_mask:0xf
	v_add_f32_e32 v4, v5, v4
	s_nop 0
	s_nop 1
	s_nop 0
	v_add_f32_dpp v4, v4, v4 row_bcast:31 row_mask:0xc bank_mask:0xf
	s_nop 0
	v_readlane_b32 s18, v4, 63
	s_and_saveexec_b64 s[16:17], vcc
	v_mov_b32_e32 v4, s5
	v_mov_b32_e32 v5, s18
	ds_write_b32 v4, v5 offset:128
	s_or_b64 exec, exec, s[16:17]
	s_add_u32 s16, s22, 0x4005
	s_addc_u32 s17, s23, 0
	s_lshl_b64 s[18:19], s[16:17], 11
	s_add_u32 s18, s33, s18
	s_addc_u32 s19, s34, s19
	v_lshl_add_u64 v[4:5], v[2:3], 1, s[18:19]
	global_load_ushort v14, v[4:5], off offset:1024
	global_load_ushort v13, v[4:5], off
	v_mov_b32_e32 v4, 0
	s_waitcnt vmcnt(1)
	v_lshlrev_b32_e32 v17, 16, v14
	v_mul_f32_e32 v5, v17, v17
	s_nop 1
	v_mov_b32_dpp v5, v5 row_ror:8 row_mask:0xf bank_mask:0xf bound_ctrl:1
	v_fmac_f32_e32 v5, v17, v17
	s_nop 1
	v_add_f32_dpp v5, v5, v5 row_ror:4 row_mask:0xf bank_mask:0xf bound_ctrl:1
	s_nop 1
	v_add_f32_dpp v5, v5, v5 quad_perm:[2,3,0,1] row_mask:0xf bank_mask:0xf bound_ctrl:1
	s_nop 1
	v_add_f32_dpp v5, v5, v5 quad_perm:[1,0,3,2] row_mask:0xf bank_mask:0xf bound_ctrl:1
	s_nop 1
	v_mov_b32_dpp v4, v5 row_bcast:15 row_mask:0xa bank_mask:0xf
	v_add_f32_e32 v4, v5, v4
	s_nop 0
	s_nop 1
	s_nop 0
	v_add_f32_dpp v4, v4, v4 row_bcast:31 row_mask:0xc bank_mask:0xf
	s_nop 0
	v_readlane_b32 s20, v4, 63
	s_and_saveexec_b64 s[18:19], vcc
	v_mov_b32_e32 v4, s5
	v_mov_b32_e32 v5, s20
	ds_write_b32 v4, v5 offset:160
	s_or_b64 exec, exec, s[18:19]
	s_add_u32 s18, s22, 0x4006
	s_addc_u32 s19, s23, 0
	s_lshl_b64 s[20:21], s[18:19], 11
	s_add_u32 s20, s33, s20
	s_addc_u32 s21, s34, s21
	v_lshl_add_u64 v[4:5], v[2:3], 1, s[20:21]
	global_load_ushort v15, v[4:5], off offset:1024
	global_load_ushort v14, v[4:5], off
	v_mov_b32_e32 v4, 0
	s_waitcnt vmcnt(1)
	v_lshlrev_b32_e32 v18, 16, v15
	v_mul_f32_e32 v5, v18, v18
	s_nop 1
	v_mov_b32_dpp v5, v5 row_ror:8 row_mask:0xf bank_mask:0xf bound_ctrl:1
	v_fmac_f32_e32 v5, v18, v18
	s_nop 1
	v_add_f32_dpp v5, v5, v5 row_ror:4 row_mask:0xf bank_mask:0xf bound_ctrl:1
	s_nop 1
	v_add_f32_dpp v5, v5, v5 quad_perm:[2,3,0,1] row_mask:0xf bank_mask:0xf bound_ctrl:1
	s_nop 1
	v_add_f32_dpp v5, v5, v5 quad_perm:[1,0,3,2] row_mask:0xf bank_mask:0xf bound_ctrl:1
	s_nop 1
	v_mov_b32_dpp v4, v5 row_bcast:15 row_mask:0xa bank_mask:0xf
	v_add_f32_e32 v4, v5, v4
	s_nop 0
	s_nop 1
	s_nop 0
	v_add_f32_dpp v4, v4, v4 row_bcast:31 row_mask:0xc bank_mask:0xf
	s_nop 0
	v_readlane_b32 s28, v4, 63
	s_and_saveexec_b64 s[20:21], vcc
	v_mov_b32_e32 v4, s5
	v_mov_b32_e32 v5, s28
	ds_write_b32 v4, v5 offset:192
	s_or_b64 exec, exec, s[20:21]
	s_add_u32 s20, s22, 0x4007
	s_addc_u32 s21, s23, 0
	s_lshl_b64 s[22:23], s[20:21], 11
	s_add_u32 s22, s33, s22
	s_addc_u32 s23, s34, s23
	v_lshl_add_u64 v[4:5], v[2:3], 1, s[22:23]
	global_load_ushort v21, v[4:5], off offset:1024
	global_load_ushort v15, v[4:5], off
	v_mov_b32_e32 v4, 0
	s_waitcnt vmcnt(1)
	v_lshlrev_b32_e32 v21, 16, v21
	v_mul_f32_e32 v5, v21, v21
	s_nop 1
	v_mov_b32_dpp v5, v5 row_ror:8 row_mask:0xf bank_mask:0xf bound_ctrl:1
	v_fmac_f32_e32 v5, v21, v21
	s_nop 1
	v_add_f32_dpp v5, v5, v5 row_ror:4 row_mask:0xf bank_mask:0xf bound_ctrl:1
	s_nop 1
	v_add_f32_dpp v5, v5, v5 quad_perm:[2,3,0,1] row_mask:0xf bank_mask:0xf bound_ctrl:1
	s_nop 1
	v_add_f32_dpp v5, v5, v5 quad_perm:[1,0,3,2] row_mask:0xf bank_mask:0xf bound_ctrl:1
	s_nop 1
	v_mov_b32_dpp v4, v5 row_bcast:15 row_mask:0xa bank_mask:0xf
	v_add_f32_e32 v4, v5, v4
	s_nop 0
	s_nop 1
	s_nop 0
	v_add_f32_dpp v4, v4, v4 row_bcast:31 row_mask:0xc bank_mask:0xf
	s_nop 0
	v_readlane_b32 s28, v4, 63
	s_and_saveexec_b64 s[22:23], vcc
	v_mov_b32_e32 v4, s5
	v_mov_b32_e32 v5, s28
	ds_write_b32 v4, v5 offset:224
	s_or_b64 exec, exec, s[22:23]
	v_readlane_b32 s36, v245, 26
	v_lshlrev_b64 v[4:5], 2, v[2:3]
	v_readlane_b32 s46, v245, 36
	v_readlane_b32 s47, v245, 37
	s_waitcnt lgkmcnt(0)
	s_barrier
	v_lshl_add_u64 v[24:25], s[46:47], 0, v[4:5]
	global_load_dword v36, v[24:25], off
	ds_read_b128 v[24:27], v1
	ds_read_b128 v[28:31], v1 offset:16
	s_ashr_i32 s5, s4, 31
	s_lshl_b64 s[4:5], s[4:5], 14
	s_add_u32 s22, s2, s4
	s_waitcnt lgkmcnt(1)
	v_add_f32_e32 v24, 0, v24
	v_add_f32_e32 v24, v24, v25
	v_add_f32_e32 v24, v24, v26
	v_add_f32_e32 v24, v24, v27
	s_waitcnt lgkmcnt(0)
	v_add_f32_e32 v24, v24, v28
	v_add_f32_e32 v24, v24, v29
	v_add_f32_e32 v24, v24, v30
	v_add_f32_e32 v24, v24, v31
	v_fmamk_f32 v24, v24, 0x3b000000, v6
	v_mul_f32_e32 v25, 0x4f800000, v24
	v_cmp_gt_f32_e32 vcc, s8, v24
	s_addc_u32 s23, s3, s5
	v_lshl_add_u64 v[4:5], s[22:23], 0, v[4:5]
	v_cndmask_b32_e32 v24, v24, v25, vcc
	v_sqrt_f32_e32 v25, v24
	v_readlane_b32 s48, v245, 38
	v_readlane_b32 s49, v245, 39
	v_readlane_b32 s50, v245, 40
	v_add_u32_e32 v26, -1, v25
	v_fma_f32 v27, -v26, v25, v24
	v_cmp_ge_f32_e64 s[4:5], 0, v27
	v_add_u32_e32 v27, 1, v25
	v_readlane_b32 s51, v245, 41
	v_cndmask_b32_e64 v26, v25, v26, s[4:5]
	v_fma_f32 v25, -v27, v25, v24
	v_cmp_lt_f32_e64 s[4:5], 0, v25
	v_lshlrev_b32_e32 v8, 16, v8
	v_lshlrev_b32_e32 v9, 16, v9
	v_cndmask_b32_e64 v25, v26, v27, s[4:5]
	v_mul_f32_e32 v26, 0x37800000, v25
	v_cndmask_b32_e32 v25, v25, v26, vcc
	v_cmp_class_f32_e32 vcc, v24, v7
	v_readlane_b32 s37, v245, 27
	v_readlane_b32 s38, v245, 28
	v_cndmask_b32_e32 v32, v25, v24, vcc
	ds_read_b128 v[24:27], v1 offset:32
	ds_read_b128 v[28:31], v1 offset:48
	v_div_scale_f32 v33, s[4:5], v32, v32, 1.0
	v_rcp_f32_e32 v34, v33
	s_waitcnt lgkmcnt(1)
	v_add_f32_e32 v24, 0, v24
	v_add_f32_e32 v24, v24, v25
	v_add_f32_e32 v24, v24, v26
	v_add_f32_e32 v24, v24, v27
	s_waitcnt lgkmcnt(0)
	v_add_f32_e32 v24, v24, v28
	v_add_f32_e32 v24, v24, v29
	v_add_f32_e32 v24, v24, v30
	v_add_f32_e32 v24, v24, v31
	v_fmamk_f32 v24, v24, 0x3b000000, v6
	v_mul_f32_e32 v25, 0x4f800000, v24
	v_cmp_gt_f32_e64 s[4:5], s8, v24
	v_fma_f32 v35, -v33, v34, 1.0
	v_fmac_f32_e32 v34, v35, v34
	v_cndmask_b32_e64 v24, v24, v25, s[4:5]
	v_sqrt_f32_e32 v25, v24
	v_div_scale_f32 v35, vcc, 1.0, v32, 1.0
	v_mul_f32_e32 v37, v35, v34
	v_fma_f32 v38, -v33, v37, v35
	v_fmac_f32_e32 v37, v38, v34
	v_add_u32_e32 v27, -1, v25
	v_fma_f32 v33, -v33, v37, v35
	v_fma_f32 v28, -v27, v25, v24
	v_div_fmas_f32 v26, v33, v34, v37
	v_cmp_ge_f32_e32 vcc, 0, v28
	v_add_u32_e32 v28, 1, v25
	v_div_fixup_f32 v26, v26, v32, 1.0
	v_cndmask_b32_e32 v27, v25, v27, vcc
	v_fma_f32 v25, -v28, v25, v24
	v_cmp_lt_f32_e32 vcc, 0, v25
	v_mul_f32_e32 v16, v26, v16
	v_readlane_b32 s39, v245, 29
	v_cndmask_b32_e32 v25, v27, v28, vcc
	v_mul_f32_e32 v27, 0x37800000, v25
	v_cndmask_b32_e64 v25, v25, v27, s[4:5]
	v_cmp_class_f32_e32 vcc, v24, v7
	s_waitcnt vmcnt(0)
	v_mul_f32_e32 v16, v36, v16
	global_store_dword v[4:5], v16, off
	v_cndmask_b32_e32 v32, v25, v24, vcc
	v_div_scale_f32 v28, s[4:5], v32, v32, 1.0
	v_rcp_f32_e32 v33, v28
	v_div_scale_f32 v29, vcc, 1.0, v32, 1.0
	v_readlane_b32 s40, v245, 30
	v_fma_f32 v24, -v28, v33, 1.0
	v_fmac_f32_e32 v33, v24, v33
	ds_read_b128 v[24:27], v1 offset:64
	v_mul_f32_e32 v34, v29, v33
	v_fma_f32 v30, -v28, v34, v29
	v_fmac_f32_e32 v34, v30, v33
	v_fma_f32 v35, -v28, v34, v29
	ds_read_b128 v[28:31], v1 offset:80
	s_waitcnt lgkmcnt(1)
	v_add_f32_e32 v24, 0, v24
	v_add_f32_e32 v24, v24, v25
	v_add_f32_e32 v24, v24, v26
	v_add_f32_e32 v24, v24, v27
	s_waitcnt lgkmcnt(0)
	v_add_f32_e32 v24, v24, v28
	v_add_f32_e32 v24, v24, v29
	v_add_f32_e32 v24, v24, v30
	v_add_f32_e32 v24, v24, v31
	v_fmamk_f32 v24, v24, 0x3b000000, v6
	v_mul_f32_e32 v25, 0x4f800000, v24
	v_cmp_gt_f32_e64 s[4:5], s8, v24
	v_div_fmas_f32 v26, v35, v33, v34
	v_div_fixup_f32 v26, v26, v32, 1.0
	v_cndmask_b32_e64 v24, v24, v25, s[4:5]
	v_sqrt_f32_e32 v25, v24
	v_mul_f32_e32 v19, v26, v19
	v_mul_f32_e32 v19, v36, v19
	global_store_dword v[4:5], v19, off offset:2048
	v_add_u32_e32 v27, -1, v25
	v_fma_f32 v28, -v27, v25, v24
	v_cmp_ge_f32_e32 vcc, 0, v28
	v_add_u32_e32 v28, 1, v25
	v_readlane_b32 s41, v245, 31
	v_cndmask_b32_e32 v27, v25, v27, vcc
	v_fma_f32 v25, -v28, v25, v24
	v_cmp_lt_f32_e32 vcc, 0, v25
	v_readlane_b32 s42, v245, 32
	v_readlane_b32 s43, v245, 33
	v_cndmask_b32_e32 v25, v27, v28, vcc
	v_mul_f32_e32 v27, 0x37800000, v25
	v_cndmask_b32_e64 v25, v25, v27, s[4:5]
	v_cmp_class_f32_e32 vcc, v24, v7
	v_readlane_b32 s44, v245, 34
	v_readlane_b32 s45, v245, 35
	v_cndmask_b32_e32 v28, v25, v24, vcc
	v_div_scale_f32 v24, s[4:5], v28, v28, 1.0
	v_rcp_f32_e32 v25, v24
	v_add_co_u32_e64 v32, s[4:5], s9, v4
	v_fma_f32 v26, -v24, v25, 1.0
	v_fmac_f32_e32 v25, v26, v25
	v_div_scale_f32 v26, vcc, 1.0, v28, 1.0
	v_mul_f32_e32 v27, v26, v25
	v_fma_f32 v29, -v24, v27, v26
	v_fmac_f32_e32 v27, v29, v25
	v_fma_f32 v24, -v24, v27, v26
	v_div_fmas_f32 v29, v24, v25, v27
	ds_read_b128 v[24:27], v1 offset:96
	v_div_fixup_f32 v28, v29, v28, 1.0
	v_mul_f32_e32 v23, v28, v23
	ds_read_b128 v[28:31], v1 offset:112
	v_mul_f32_e32 v42, v36, v23
	s_waitcnt lgkmcnt(1)
	v_add_f32_e32 v23, 0, v24
	v_add_f32_e32 v23, v23, v25
	v_add_f32_e32 v23, v23, v26
	v_add_f32_e32 v23, v23, v27
	s_waitcnt lgkmcnt(0)
	v_add_f32_e32 v23, v23, v28
	v_add_f32_e32 v23, v23, v29
	v_add_f32_e32 v23, v23, v30
	v_add_f32_e32 v23, v23, v31
	v_fmamk_f32 v23, v23, 0x3b000000, v6
	v_mul_f32_e32 v24, 0x4f800000, v23
	v_cmp_gt_f32_e32 vcc, s8, v23
	v_addc_co_u32_e64 v33, s[4:5], 0, v5, s[4:5]
	s_nop 0
	v_cndmask_b32_e32 v23, v23, v24, vcc
	v_sqrt_f32_e32 v24, v23
	s_nop 0
	v_add_u32_e32 v25, -1, v24
	v_fma_f32 v26, -v25, v24, v23
	v_cmp_ge_f32_e64 s[4:5], 0, v26
	v_add_u32_e32 v26, 1, v24
	s_nop 0
	v_cndmask_b32_e64 v25, v24, v25, s[4:5]
	v_fma_f32 v24, -v26, v24, v23
	v_cmp_lt_f32_e64 s[4:5], 0, v24
	s_nop 1
	v_cndmask_b32_e64 v24, v25, v26, s[4:5]
	v_mul_f32_e32 v25, 0x37800000, v24
	v_cndmask_b32_e32 v24, v24, v25, vcc
	v_cmp_class_f32_e32 vcc, v23, v7
	s_nop 1
	v_cndmask_b32_e32 v23, v24, v23, vcc
	v_div_scale_f32 v28, s[4:5], v23, v23, 1.0
	v_rcp_f32_e32 v37, v28
	v_add_co_u32_e32 v34, vcc, s24, v4
	v_fma_f32 v24, -v28, v37, 1.0
	s_nop 0
	v_addc_co_u32_e32 v35, vcc, 0, v5, vcc
	v_fmac_f32_e32 v37, v24, v37
	v_div_scale_f32 v29, vcc, 1.0, v23, 1.0
	ds_read_b128 v[24:27], v1 offset:128
	v_mul_f32_e32 v38, v29, v37
	v_fma_f32 v30, -v28, v38, v29
	v_fmac_f32_e32 v38, v30, v37
	v_fma_f32 v39, -v28, v38, v29
	ds_read_b128 v[28:31], v1 offset:144
	s_waitcnt lgkmcnt(1)
	v_add_f32_e32 v24, 0, v24
	v_add_f32_e32 v24, v24, v25
	v_add_f32_e32 v24, v24, v26
	v_add_f32_e32 v24, v24, v27
	s_waitcnt lgkmcnt(0)
	v_add_f32_e32 v24, v24, v28
	v_add_f32_e32 v24, v24, v29
	v_add_f32_e32 v24, v24, v30
	v_add_f32_e32 v24, v24, v31
	v_fmamk_f32 v24, v24, 0x3b000000, v6
	v_mul_f32_e32 v25, 0x4f800000, v24
	v_cmp_gt_f32_e64 s[4:5], s8, v24
	v_div_fmas_f32 v26, v39, v37, v38
	v_div_fixup_f32 v23, v26, v23, 1.0
	v_cndmask_b32_e64 v24, v24, v25, s[4:5]
	v_sqrt_f32_e32 v25, v24
	v_mul_f32_e32 v22, v23, v22
	v_mul_f32_e32 v43, v36, v22
	global_store_dword v[32:33], v43, off offset:2048
	v_add_u32_e32 v26, -1, v25
	v_fma_f32 v27, -v26, v25, v24
	v_cmp_ge_f32_e32 vcc, 0, v27
	v_add_u32_e32 v27, 1, v25
	global_store_dword v[34:35], v42, off offset:-4096
	v_cndmask_b32_e32 v26, v25, v26, vcc
	v_fma_f32 v25, -v27, v25, v24
	v_cmp_lt_f32_e32 vcc, 0, v25
	s_nop 1
	v_cndmask_b32_e32 v25, v26, v27, vcc
	v_mul_f32_e32 v26, 0x37800000, v25
	v_cndmask_b32_e64 v25, v25, v26, s[4:5]
	v_cmp_class_f32_e32 vcc, v24, v7
	s_nop 1
	v_cndmask_b32_e32 v30, v25, v24, vcc
	v_div_scale_f32 v26, s[4:5], v30, v30, 1.0
	v_rcp_f32_e32 v31, v26
	v_div_scale_f32 v27, vcc, 1.0, v30, 1.0
	v_fma_f32 v22, -v26, v31, 1.0
	v_fmac_f32_e32 v31, v22, v31
	ds_read_b128 v[22:25], v1 offset:160
	v_mul_f32_e32 v32, v27, v31
	v_fma_f32 v28, -v26, v32, v27
	v_fmac_f32_e32 v32, v28, v31
	v_fma_f32 v33, -v26, v32, v27
	ds_read_b128 v[26:29], v1 offset:176
	s_waitcnt lgkmcnt(1)
	v_add_f32_e32 v22, 0, v22
	v_add_f32_e32 v22, v22, v23
	v_add_f32_e32 v22, v22, v24
	v_add_f32_e32 v22, v22, v25
	s_waitcnt lgkmcnt(0)
	v_add_f32_e32 v22, v22, v26
	v_add_f32_e32 v22, v22, v27
	v_add_f32_e32 v22, v22, v28
	v_add_f32_e32 v22, v22, v29
	v_fmamk_f32 v22, v22, 0x3b000000, v6
	v_mul_f32_e32 v23, 0x4f800000, v22
	v_cmp_gt_f32_e64 s[4:5], s8, v22
	v_div_fmas_f32 v24, v33, v31, v32
	v_div_fixup_f32 v24, v24, v30, 1.0
	v_cndmask_b32_e64 v22, v22, v23, s[4:5]
	v_sqrt_f32_e32 v23, v22
	v_mul_f32_e32 v20, v24, v20
	v_mul_f32_e32 v44, v36, v20
	global_store_dword v[34:35], v44, off
	v_add_u32_e32 v25, -1, v23
	v_fma_f32 v26, -v25, v23, v22
	v_cmp_ge_f32_e32 vcc, 0, v26
	v_add_u32_e32 v26, 1, v23
	s_nop 0
	v_cndmask_b32_e32 v25, v23, v25, vcc
	v_fma_f32 v23, -v26, v23, v22
	v_cmp_lt_f32_e32 vcc, 0, v23
	s_nop 1
	v_cndmask_b32_e32 v23, v25, v26, vcc
	v_mul_f32_e32 v25, 0x37800000, v23
	v_cndmask_b32_e64 v23, v23, v25, s[4:5]
	v_cmp_class_f32_e32 vcc, v22, v7
	s_nop 1
	v_cndmask_b32_e32 v30, v23, v22, vcc
	v_div_scale_f32 v26, s[4:5], v30, v30, 1.0
	v_rcp_f32_e32 v31, v26
	ds_read_b128 v[22:25], v1 offset:192
	v_fma_f32 v20, -v26, v31, 1.0
	v_fmac_f32_e32 v31, v20, v31
	v_div_scale_f32 v20, vcc, 1.0, v30, 1.0
	v_mul_f32_e32 v32, v20, v31
	v_fma_f32 v27, -v26, v32, v20
	v_fmac_f32_e32 v32, v27, v31
	v_fma_f32 v20, -v26, v32, v20
	ds_read_b128 v[26:29], v1 offset:208
	s_waitcnt lgkmcnt(1)
	v_add_f32_e32 v22, 0, v22
	v_add_f32_e32 v22, v22, v23
	v_add_f32_e32 v22, v22, v24
	v_add_f32_e32 v22, v22, v25
	s_waitcnt lgkmcnt(0)
	v_add_f32_e32 v22, v22, v26
	v_add_f32_e32 v22, v22, v27
	v_add_f32_e32 v22, v22, v28
	v_add_f32_e32 v22, v22, v29
	v_fmamk_f32 v22, v22, 0x3b000000, v6
	v_mul_f32_e32 v23, 0x4f800000, v22
	v_cmp_gt_f32_e64 s[4:5], s8, v22
	v_div_fmas_f32 v20, v20, v31, v32
	v_div_fixup_f32 v20, v20, v30, 1.0
	v_cndmask_b32_e64 v22, v22, v23, s[4:5]
	v_sqrt_f32_e32 v23, v22
	v_mul_f32_e32 v17, v20, v17
	v_mul_f32_e32 v17, v36, v17
	global_store_dword v[34:35], v17, off offset:2048
	v_add_u32_e32 v24, -1, v23
	v_fma_f32 v25, -v24, v23, v22
	v_cmp_ge_f32_e32 vcc, 0, v25
	v_add_u32_e32 v25, 1, v23
	s_nop 0
	v_cndmask_b32_e32 v24, v23, v24, vcc
	v_fma_f32 v23, -v25, v23, v22
	v_cmp_lt_f32_e32 vcc, 0, v23
	s_nop 1
	v_cndmask_b32_e32 v23, v24, v25, vcc
	v_mul_f32_e32 v24, 0x37800000, v23
	v_cndmask_b32_e64 v23, v23, v24, s[4:5]
	v_cmp_class_f32_e32 vcc, v22, v7
	s_nop 1
	v_cndmask_b32_e32 v30, v23, v22, vcc
	v_div_scale_f32 v26, s[4:5], v30, v30, 1.0
	v_rcp_f32_e32 v27, v26
	s_nop 0
	v_fma_f32 v20, -v26, v27, 1.0
	v_fmac_f32_e32 v27, v20, v27
	v_div_scale_f32 v20, vcc, 1.0, v30, 1.0
	v_mul_f32_e32 v28, v20, v27
	v_fma_f32 v22, -v26, v28, v20
	v_fmac_f32_e32 v28, v22, v27
	ds_read_b128 v[22:25], v1 offset:224
	v_fma_f32 v20, -v26, v28, v20
	v_div_fmas_f32 v20, v20, v27, v28
	ds_read_b128 v[26:29], v1 offset:240
	v_div_fixup_f32 v20, v20, v30, 1.0
	s_waitcnt lgkmcnt(1)
	v_add_f32_e32 v22, 0, v22
	v_add_f32_e32 v22, v22, v23
	v_add_f32_e32 v22, v22, v24
	v_add_f32_e32 v22, v22, v25
	s_waitcnt lgkmcnt(0)
	v_add_f32_e32 v22, v22, v26
	v_add_f32_e32 v22, v22, v27
	v_add_f32_e32 v22, v22, v28
	v_add_f32_e32 v22, v22, v29
	v_fmamk_f32 v22, v22, 0x3b000000, v6
	v_mul_f32_e32 v23, 0x4f800000, v22
	v_cmp_gt_f32_e32 vcc, s8, v22
	v_mul_f32_e32 v18, v20, v18
	v_mul_f32_e32 v18, v36, v18
	v_cndmask_b32_e32 v22, v22, v23, vcc
	v_sqrt_f32_e32 v23, v22
	s_nop 0
	v_add_u32_e32 v20, -1, v23
	v_fma_f32 v24, -v20, v23, v22
	v_cmp_ge_f32_e64 s[4:5], 0, v24
	v_add_u32_e32 v24, 1, v23
	s_nop 0
	v_cndmask_b32_e64 v20, v23, v20, s[4:5]
	v_fma_f32 v23, -v24, v23, v22
	v_cmp_lt_f32_e64 s[4:5], 0, v23
	s_nop 1
	v_cndmask_b32_e64 v20, v20, v24, s[4:5]
	v_mul_f32_e32 v23, 0x37800000, v20
	v_cndmask_b32_e32 v20, v20, v23, vcc
	v_cmp_class_f32_e32 vcc, v22, v7
	s_nop 1
	v_cndmask_b32_e32 v20, v20, v22, vcc
	v_div_scale_f32 v22, s[4:5], v20, v20, 1.0
	v_rcp_f32_e32 v23, v22
	v_add_co_u32_e32 v4, vcc, s25, v4
	v_fma_f32 v24, -v22, v23, 1.0
	s_nop 0
	v_addc_co_u32_e32 v5, vcc, 0, v5, vcc
	v_fmac_f32_e32 v23, v24, v23
	v_div_scale_f32 v24, vcc, 1.0, v20, 1.0
	v_mul_f32_e32 v25, v24, v23
	v_fma_f32 v26, -v22, v25, v24
	v_fmac_f32_e32 v25, v26, v23
	v_fma_f32 v22, -v22, v25, v24
	v_div_fmas_f32 v22, v22, v23, v25
	v_div_fixup_f32 v20, v22, v20, 1.0
	v_mul_f32_e32 v20, v20, v21
	v_mul_f32_e32 v35, v36, v20
	global_store_dword v[4:5], v18, off
	global_store_dword v[4:5], v35, off offset:2048
	v_ashrrev_i32_e32 v4, 7, v2
	v_and_b32_e32 v20, 0xffffff80, v2
	v_ashrrev_i32_e32 v5, 31, v4
	v_lshlrev_b64 v[4:5], 16, v[4:5]
	v_ashrrev_i32_e32 v21, 31, v20
	v_lshl_add_u64 v[36:37], s[48:49], 0, v[4:5]
	v_lshl_add_u64 v[4:5], v[20:21], 2, s[50:51]
	global_load_dwordx4 v[20:23], v[4:5], off
	global_load_dword v40, v[36:37], off
	global_load_dwordx2 v[38:39], v[36:37], off offset:512
	global_load_dwordx3 v[32:34], v[36:37], off offset:1024
	global_load_dwordx4 v[24:27], v[36:37], off offset:1536
	global_load_dwordx4 v[28:31], v[4:5], off offset:16
	v_lshlrev_b32_e32 v5, 16, v10
	v_lshlrev_b32_e32 v4, 16, v12
	s_waitcnt vmcnt(4)
	v_fma_f32 v10, v16, v40, v20
	v_mul_f32_e32 v8, v10, v8
	v_cvt_pk_bf16_f32 v8, v8, s0
	s_lshl_b64 s[0:1], s[0:1], 12
	s_add_u32 s0, s82, s0
	s_addc_u32 s1, s83, s1
	v_lshlrev_b64 v[40:41], 1, v[2:3]
	v_lshl_add_u64 v[2:3], s[0:1], 0, v[40:41]
	global_store_short v[2:3], v8, off offset:2048
	s_waitcnt vmcnt(4)
	v_fma_f32 v2, v16, v38, v21
	v_fmac_f32_e32 v2, v19, v39
	v_mul_f32_e32 v2, v2, v9
	v_cvt_pk_bf16_f32 v8, v2, s0
	s_lshl_b64 s[0:1], s[6:7], 12
	s_add_u32 s0, s82, s0
	s_addc_u32 s1, s83, s1
	v_lshl_add_u64 v[2:3], s[0:1], 0, v[40:41]
	global_store_short v[2:3], v8, off offset:2048
	s_waitcnt vmcnt(4)
	v_fma_f32 v2, v16, v32, v22
	v_fmac_f32_e32 v2, v19, v33
	v_fmac_f32_e32 v2, v42, v34
	v_mul_f32_e32 v2, v2, v5
	v_cvt_pk_bf16_f32 v5, v2, s0
	s_lshl_b64 s[0:1], s[10:11], 12
	s_waitcnt vmcnt(3)
	v_fmac_f32_e32 v23, v16, v24
	s_add_u32 s0, s82, s0
	v_fmac_f32_e32 v23, v19, v25
	s_addc_u32 s1, s83, s1
	v_fmac_f32_e32 v23, v42, v26
	v_lshl_add_u64 v[2:3], s[0:1], 0, v[40:41]
	v_fmac_f32_e32 v23, v43, v27
	global_store_short v[2:3], v5, off offset:2048
	v_mul_f32_e32 v2, v23, v4
	v_cvt_pk_bf16_f32 v4, v2, s0
	s_lshl_b64 s[0:1], s[12:13], 12
	s_add_u32 s0, s82, s0
	s_addc_u32 s1, s83, s1
	v_lshl_add_u64 v[2:3], s[0:1], 0, v[40:41]
	global_store_short v[2:3], v4, off offset:2048
	global_load_dwordx4 v[2:5], v[36:37], off offset:2048
	s_nop 0
	global_load_dword v8, v[36:37], off offset:2064
	v_lshlrev_b32_e32 v9, 16, v11
	v_lshlrev_b32_e32 v10, 16, v13
	v_lshlrev_b32_e32 v11, 16, v14
	v_lshlrev_b32_e32 v14, 16, v15
	v_mov_b32_e32 v15, v0
	s_waitcnt vmcnt(1)
	v_fma_f32 v2, v16, v2, v28
	v_fmac_f32_e32 v2, v19, v3
	v_fmac_f32_e32 v2, v42, v4
	v_fmac_f32_e32 v2, v43, v5
	s_waitcnt vmcnt(0)
	v_fmac_f32_e32 v2, v44, v8
	v_mul_f32_e32 v2, v2, v9
	v_cvt_pk_bf16_f32 v4, v2, s0
	s_lshl_b64 s[0:1], s[14:15], 12
	s_add_u32 s0, s82, s0
	s_addc_u32 s1, s83, s1
	v_lshl_add_u64 v[2:3], s[0:1], 0, v[40:41]
	global_store_short v[2:3], v4, off offset:2048
	global_load_dwordx4 v[2:5], v[36:37], off offset:2560
	s_nop 0
	global_load_dwordx2 v[8:9], v[36:37], off offset:2576
	s_waitcnt vmcnt(1)
	v_fma_f32 v2, v16, v2, v29
	v_fmac_f32_e32 v2, v19, v3
	v_fmac_f32_e32 v2, v42, v4
	v_fmac_f32_e32 v2, v43, v5
	s_waitcnt vmcnt(0)
	v_fmac_f32_e32 v2, v44, v8
	v_fmac_f32_e32 v2, v17, v9
	v_mul_f32_e32 v2, v2, v10
	v_cvt_pk_bf16_f32 v4, v2, s0
	s_lshl_b64 s[0:1], s[16:17], 12
	s_add_u32 s0, s82, s0
	s_addc_u32 s1, s83, s1
	v_lshl_add_u64 v[2:3], s[0:1], 0, v[40:41]
	global_store_short v[2:3], v4, off offset:2048
	global_load_dwordx4 v[2:5], v[36:37], off offset:3072
	s_nop 0
	global_load_dwordx3 v[8:10], v[36:37], off offset:3088
	s_waitcnt vmcnt(1)
	v_fma_f32 v2, v16, v2, v30
	v_fmac_f32_e32 v2, v19, v3
	v_fmac_f32_e32 v2, v42, v4
	v_fmac_f32_e32 v2, v43, v5
	s_waitcnt vmcnt(0)
	v_fmac_f32_e32 v2, v44, v8
	v_fmac_f32_e32 v2, v17, v9
	v_fmac_f32_e32 v2, v18, v10
	v_mul_f32_e32 v2, v2, v11
	v_cvt_pk_bf16_f32 v4, v2, s0
	s_lshl_b64 s[0:1], s[18:19], 12
	s_add_u32 s0, s82, s0
	s_addc_u32 s1, s83, s1
	v_lshl_add_u64 v[2:3], s[0:1], 0, v[40:41]
	global_store_short v[2:3], v4, off offset:2048
	global_load_dwordx4 v[2:5], v[36:37], off offset:3584
	s_nop 0
	global_load_dwordx4 v[8:11], v[36:37], off offset:3600
	s_lshl_b64 s[0:1], s[20:21], 12
	s_add_u32 s0, s82, s0
	s_addc_u32 s1, s83, s1
	v_lshl_add_u64 v[12:13], s[0:1], 0, v[40:41]
	s_waitcnt vmcnt(1)
	v_fmac_f32_e32 v31, v16, v2
	v_fmac_f32_e32 v31, v19, v3
	v_fmac_f32_e32 v31, v42, v4
	v_fmac_f32_e32 v31, v43, v5
	s_waitcnt vmcnt(0)
	v_fmac_f32_e32 v31, v44, v8
	v_fmac_f32_e32 v31, v17, v9
	v_fmac_f32_e32 v31, v18, v10
	v_fmac_f32_e32 v31, v35, v11
	v_mul_f32_e32 v2, v31, v14
	v_cvt_pk_bf16_f32 v2, v2, s0
	global_store_short v[12:13], v2, off offset:2048
	s_barrier
	s_nop 0
	v_cmp_eq_u32_e32 vcc, 0, v15
	s_and_saveexec_b64 s[0:1], vcc
	s_cbranch_execz .LBB0_1248
	s_mov_b64 s[6:7], exec
	v_mbcnt_lo_u32_b32 v2, s6, 0
	v_mbcnt_hi_u32_b32 v2, s7, v2
	v_cmp_eq_u32_e32 vcc, 0, v2
	s_and_saveexec_b64 s[4:5], vcc
	s_cbranch_execz .LBB0_1247
	s_bcnt1_i32_b64 s6, s[6:7]
	v_mov_b32_e32 v3, s6
	global_atomic_add v3, v1, v3, s[54:55] sc0
	s_branch .LBB0_1247
